# speedup vs baseline: 1.0172x; 1.0039x over previous
; __device__ __forceinline__ int bid_() { int b = blockIdx.x; asm volatile("" : "+s"(b)); return b; }
; template <int MODE>
; __device__ __forceinline__ void convT(const float* __restrict__ src, int K, int N, u16* __restrict__ dst, const float* __restrict__ scale) {
;     ...
;   const int nkt = K / 256, nnt = (N + 63) / 64, ntile = nkt * nnt;
;   const int n = tid & 63, kk = tid >> 6;
;   float v[32];
;   int tile = bid_();
;   if (tile < ntile) {
;     const int k0 = (tile % nkt) * 256, nn = (tile / nkt) * 64 + n;
; #pragma unroll
;     for (int it = 0; it < 32; ++it) v[it] = (nn < N) ? __builtin_nontemporal_load(src + (long)(k0 + kk + it * 8) * N + nn) : 0.f;
.LBB0_33:
	s_mul_hi_u32 s3, s8, 0x580000
	s_mul_i32 s2, s8, 0x580000
	s_lshl_b64 s[24:25], s[2:3], 2
	s_add_u32 s26, s74, s24
	s_addc_u32 s27, s75, s25
	v_mov_b32_e32 v36, v182
	s_load_dword s2, s[0:1], 0x188
	s_lshl_b32 s40, s8, 2
	s_add_i32 s40, s40, 0
	s_sub_i32 s40, s92, s40
	s_and_b32 s40, s40, 0xff
	s_waitcnt lgkmcnt(0)
	s_cmpk_eq_u32 s2, 0x100
	s_cselect_b32 s40, s40, s92
	s_waitcnt vmcnt(0)
	v_mov_b32_e32 v4, v3
	v_mov_b32_e32 v5, v3
	v_mov_b32_e32 v6, v3
	v_mov_b32_e32 v7, v3
	v_mov_b32_e32 v8, v3
	v_mov_b32_e32 v9, v3
	v_mov_b32_e32 v10, v3
	v_mov_b32_e32 v11, v3
	v_mov_b32_e32 v12, v3
	v_mov_b32_e32 v13, v3
	v_mov_b32_e32 v14, v3
	v_mov_b32_e32 v15, v3
	v_mov_b32_e32 v16, v3
	v_mov_b32_e32 v17, v3
	v_mov_b32_e32 v18, v3
	v_mov_b32_e32 v19, v3
	v_mov_b32_e32 v20, v3
	v_mov_b32_e32 v21, v3
	v_mov_b32_e32 v22, v3
	v_mov_b32_e32 v23, v3
	v_mov_b32_e32 v24, v3
	v_mov_b32_e32 v25, v3
	v_mov_b32_e32 v26, v3
	v_mov_b32_e32 v27, v3
	v_mov_b32_e32 v28, v3
	v_mov_b32_e32 v29, v3
	v_mov_b32_e32 v30, v3
	v_mov_b32_e32 v31, v3
	v_mov_b32_e32 v32, v3
	v_mov_b32_e32 v33, v3
	v_mov_b32_e32 v2, v3
	s_cmpk_lt_i32 s40, 0x160
	v_mov_b64_e32 v[34:35], v[32:33]
	v_and_b32_e32 v46, 63, v36
	v_ashrrev_i32_e32 v47, 6, v36
	s_cselect_b64 s[2:3], -1, 0
	s_cmpk_gt_i32 s40, 0x15f
	v_mov_b64_e32 v[32:33], v[30:31]
	v_mov_b64_e32 v[30:31], v[28:29]
	v_mov_b64_e32 v[28:29], v[26:27]
	v_mov_b64_e32 v[26:27], v[24:25]
	v_mov_b64_e32 v[24:25], v[22:23]
	v_mov_b64_e32 v[22:23], v[20:21]
	v_mov_b64_e32 v[20:21], v[18:19]
	v_mov_b64_e32 v[18:19], v[16:17]
	v_mov_b64_e32 v[16:17], v[14:15]
	v_mov_b64_e32 v[14:15], v[12:13]
	v_mov_b64_e32 v[12:13], v[10:11]
	v_mov_b64_e32 v[10:11], v[8:9]
	v_mov_b64_e32 v[8:9], v[6:7]
	v_mov_b64_e32 v[6:7], v[4:5]
	v_mov_b64_e32 v[4:5], v[2:3]
	s_cbranch_scc1 .LBB0_35
	s_ashr_i32 s20, s40, 31
	s_lshr_b32 s20, s20, 30
	s_add_i32 s20, s40, s20
	s_and_b32 s21, s20, 0xfffffc
	s_lshl_b32 s20, s20, 4
	s_andn2_b32 s20, s20, 63
	s_sub_i32 s21, s40, s21
	v_or_b32_e32 v4, s20, v46
	v_lshl_add_u32 v2, s21, 8, v47
	v_ashrrev_i32_e32 v5, 31, v4
	v_lshl_add_u64 v[28:29], v[4:5], 2, s[26:27]
	v_add_u32_e32 v6, 8, v2
	v_add_u32_e32 v8, 16, v2
	v_add_u32_e32 v10, 24, v2
	v_add_u32_e32 v12, 32, v2
	v_add_u32_e32 v14, 40, v2
	v_add_u32_e32 v16, 48, v2
	v_add_u32_e32 v18, 56, v2
	v_mad_i64_i32 v[4:5], s[20:21], v2, s54, v[28:29]
	v_mad_i64_i32 v[6:7], s[20:21], v6, s54, v[28:29]
	v_mad_i64_i32 v[8:9], s[20:21], v8, s54, v[28:29]
	v_mad_i64_i32 v[10:11], s[20:21], v10, s54, v[28:29]
	v_mad_i64_i32 v[12:13], s[20:21], v12, s54, v[28:29]
	v_mad_i64_i32 v[14:15], s[20:21], v14, s54, v[28:29]
	v_mad_i64_i32 v[16:17], s[20:21], v16, s54, v[28:29]
	v_mad_i64_i32 v[18:19], s[20:21], v18, s54, v[28:29]
	global_load_dword v4, v[4:5], off nt
	s_nop 0
	global_load_dword v5, v[6:7], off nt
	s_nop 0
	global_load_dword v6, v[8:9], off nt
	global_load_dword v7, v[10:11], off nt
	s_nop 0
	global_load_dword v8, v[12:13], off nt
	global_load_dword v9, v[14:15], off nt
	global_load_dword v10, v[16:17], off nt
	global_load_dword v11, v[18:19], off nt
	v_add_u32_e32 v12, 64, v2
	v_add_u32_e32 v14, 0x48, v2
	v_add_u32_e32 v16, 0x50, v2
	v_add_u32_e32 v18, 0x58, v2
	v_add_u32_e32 v20, 0x60, v2
	v_add_u32_e32 v22, 0x68, v2
	v_add_u32_e32 v24, 0x70, v2
	v_add_u32_e32 v26, 0x78, v2
	v_mad_i64_i32 v[12:13], s[20:21], v12, s54, v[28:29]
	v_mad_i64_i32 v[14:15], s[20:21], v14, s54, v[28:29]
	v_mad_i64_i32 v[16:17], s[20:21], v16, s54, v[28:29]
	v_mad_i64_i32 v[18:19], s[20:21], v18, s54, v[28:29]
	v_mad_i64_i32 v[20:21], s[20:21], v20, s54, v[28:29]
	v_mad_i64_i32 v[22:23], s[20:21], v22, s54, v[28:29]
	v_mad_i64_i32 v[24:25], s[20:21], v24, s54, v[28:29]
	v_mad_i64_i32 v[26:27], s[20:21], v26, s54, v[28:29]
	global_load_dword v12, v[12:13], off nt
	s_nop 0
	global_load_dword v13, v[14:15], off nt
	s_nop 0
	global_load_dword v14, v[16:17], off nt
	global_load_dword v15, v[18:19], off nt
	s_nop 0
	global_load_dword v16, v[20:21], off nt
	global_load_dword v17, v[22:23], off nt
	global_load_dword v18, v[24:25], off nt
	global_load_dword v19, v[26:27], off nt
	v_add_u32_e32 v20, 0x80, v2
	v_add_u32_e32 v22, 0x88, v2
	v_add_u32_e32 v24, 0x90, v2
	v_add_u32_e32 v26, 0x98, v2
	v_add_u32_e32 v37, 0xb8, v2
	v_mad_i64_i32 v[20:21], s[20:21], v20, s54, v[28:29]
	v_mad_i64_i32 v[22:23], s[20:21], v22, s54, v[28:29]
	v_mad_i64_i32 v[24:25], s[20:21], v24, s54, v[28:29]
	v_mad_i64_i32 v[26:27], s[20:21], v26, s54, v[28:29]
	v_add_u32_e32 v30, 0xa0, v2
	v_add_u32_e32 v32, 0xa8, v2
	v_add_u32_e32 v34, 0xb0, v2
	v_mad_i64_i32 v[38:39], s[20:21], v37, s54, v[28:29]
	v_add_u32_e32 v37, 0xd8, v2
	v_mad_i64_i32 v[30:31], s[20:21], v30, s54, v[28:29]
	v_mad_i64_i32 v[32:33], s[20:21], v32, s54, v[28:29]
	v_mad_i64_i32 v[34:35], s[20:21], v34, s54, v[28:29]
	global_load_dword v20, v[20:21], off nt
	s_nop 0
	global_load_dword v21, v[22:23], off nt
	s_nop 0
	global_load_dword v22, v[24:25], off nt
	global_load_dword v23, v[26:27], off nt
	s_nop 0
	global_load_dword v24, v[30:31], off nt
	global_load_dword v25, v[32:33], off nt
	global_load_dword v26, v[34:35], off nt
	global_load_dword v27, v[38:39], off nt
	v_mad_i64_i32 v[38:39], s[20:21], v37, s54, v[28:29]
	v_add_u32_e32 v37, 0xe0, v2
	v_add_u32_e32 v30, 0xc0, v2
	v_add_u32_e32 v32, 0xc8, v2
	v_add_u32_e32 v34, 0xd0, v2
	v_mad_i64_i32 v[42:43], s[20:21], v37, s54, v[28:29]
	v_add_u32_e32 v37, 0xe8, v2
	v_mad_i64_i32 v[30:31], s[20:21], v30, s54, v[28:29]
	v_mad_i64_i32 v[32:33], s[20:21], v32, s54, v[28:29]
	v_mad_i64_i32 v[34:35], s[20:21], v34, s54, v[28:29]
	v_mad_i64_i32 v[44:45], s[20:21], v37, s54, v[28:29]
	v_add_u32_e32 v37, 0xf0, v2
	v_add_u32_e32 v2, 0xf8, v2
	v_mad_i64_i32 v[48:49], s[20:21], v37, s54, v[28:29]
	v_mad_i64_i32 v[50:51], s[20:21], v2, s54, v[28:29]
	global_load_dword v28, v[30:31], off nt
	global_load_dword v29, v[32:33], off nt
	s_nop 0
	global_load_dword v30, v[34:35], off nt
	global_load_dword v31, v[38:39], off nt
	global_load_dword v32, v[42:43], off nt
	global_load_dword v33, v[44:45], off nt
	s_nop 0
	global_load_dword v34, v[48:49], off nt
	global_load_dword v35, v[50:51], off nt

; __device__ __forceinline__ int bid_() { int b = blockIdx.x; asm volatile("" : "+s"(b)); return b; }
; template <int MODE>
; __device__ __forceinline__ void convT(const float* __restrict__ src, int K, int N, u16* __restrict__ dst, const float* __restrict__ scale) {
;     ...
;   const int nkt = K / 256, nnt = (N + 63) / 64, ntile = nkt * nnt;
;   const int n = tid & 63, kk = tid >> 6;
;   float v[32];
;   int tile = bid_();
;   if (tile < ntile) {
;     const int k0 = (tile % nkt) * 256, nn = (tile / nkt) * 64 + n;
; #pragma unroll
;     for (int it = 0; it < 32; ++it) v[it] = (nn < N) ? __builtin_nontemporal_load(src + (long)(k0 + kk + it * 8) * N + nn) : 0.f;
.LBB0_71:
	s_mul_hi_u32 s3, s8, 0x2c0000
	s_mul_i32 s2, s8, 0x2c0000
	s_lshl_b64 s[26:27], s[2:3], 2
	s_add_u32 s34, s76, s26
	s_addc_u32 s35, s77, s27
	v_mov_b32_e32 v43, v182
	s_load_dword s38, s[0:1], 0x188
	s_lshl_b32 s44, s8, 2
	s_add_i32 s44, s44, 96
	s_sub_i32 s44, s92, s44
	s_and_b32 s44, s44, 0xff
	s_waitcnt lgkmcnt(0)
	s_cmpk_eq_u32 s38, 0x100
	s_cselect_b32 s44, s44, s92
	s_cmpk_lt_i32 s44, 0xb0
	v_and_b32_e32 v46, 63, v43
	s_cselect_b64 s[38:39], -1, 0
	s_cmpk_gt_i32 s44, 0xaf
	v_ashrrev_i32_e32 v42, 6, v43
	s_cbranch_scc1 .LBB0_137
	s_mul_hi_i32 s2, s44, 0x2e8ba2e9
	s_lshr_b32 s3, s2, 31
	s_ashr_i32 s2, s2, 1
	s_add_i32 s2, s2, s3
	s_mul_i32 s3, s2, 11
	s_sub_i32 s40, s44, s3
	s_waitcnt vmcnt(31)
	v_lshl_or_b32 v4, s2, 6, v46
	v_lshl_add_u32 v36, s40, 8, v42
	s_waitcnt vmcnt(30)
	v_ashrrev_i32_e32 v5, 31, v4
	v_cmp_gt_i32_e64 s[2:3], s59, v4
	v_lshl_add_u64 v[38:39], v[4:5], 2, s[34:35]
	v_mov_b32_e32 v5, 0
	v_ashrrev_i32_e32 v37, 31, v36
	v_mov_b32_e32 v4, 0
	s_and_saveexec_b64 s[40:41], s[2:3]
	s_cbranch_execz .LBB0_74
	s_waitcnt vmcnt(28)
	v_lshlrev_b64 v[6:7], 12, v[36:37]
	v_lshl_add_u64 v[6:7], v[38:39], 0, v[6:7]
	global_load_dword v4, v[6:7], off nt

; __device__ __forceinline__ int bid_() { int b = blockIdx.x; asm volatile("" : "+s"(b)); return b; }
; template <int MODE>
; __device__ __forceinline__ void convT(const float* __restrict__ src, int K, int N, u16* __restrict__ dst, const float* __restrict__ scale) {
;     ...
;   const int nkt = K / 256, nnt = (N + 63) / 64, ntile = nkt * nnt;
;   const int n = tid & 63, kk = tid >> 6;
;   float v[32];
;   int tile = bid_();
;   if (tile < ntile) {
;     const int k0 = (tile % nkt) * 256, nn = (tile / nkt) * 64 + n;
; #pragma unroll
;     for (int it = 0; it < 32; ++it) v[it] = (nn < N) ? __builtin_nontemporal_load(src + (long)(k0 + kk + it * 8) * N + nn) : 0.f;
.LBB0_215:
	s_mul_i32 s3, s8, 0xa06000
	s_mul_hi_u32 s2, s8, 0xa06000
	s_add_u32 s34, s82, s3
	s_addc_u32 s35, s83, s2
	v_mov_b32_e32 v38, v182
	s_load_dword s2, s[0:1], 0x188
	s_lshl_b32 s44, s8, 2
	s_add_i32 s44, s44, 16
	s_sub_i32 s44, s92, s44
	s_and_b32 s44, s44, 0xff
	s_waitcnt lgkmcnt(0)
	s_cmpk_eq_u32 s2, 0x100
	s_cselect_b32 s44, s44, s92
	s_cmpk_lt_i32 s44, 0xa4
	v_and_b32_e32 v42, 63, v38
	s_cselect_b64 s[2:3], -1, 0
	s_cmpk_gt_i32 s44, 0xa3
	v_ashrrev_i32_e32 v43, 6, v38
	s_cbranch_scc1 .LBB0_281
	s_ashr_i32 s38, s44, 31
	s_lshr_b32 s38, s38, 30
	s_add_i32 s38, s44, s38
	s_and_b32 s39, s38, 0xfffffc
	s_lshl_b32 s38, s38, 4
	s_andn2_b32 s38, s38, 63
	s_waitcnt vmcnt(0)
	v_or_b32_e32 v4, s38, v42
	s_sub_i32 s39, s44, s39
	v_ashrrev_i32_e32 v5, 31, v4
	v_cmp_gt_i32_e32 vcc, s86, v4
	v_lshl_add_u32 v2, s39, 8, v43
	v_lshl_add_u64 v[36:37], v[4:5], 2, s[34:35]
	v_mov_b32_e32 v5, 0
	v_mov_b32_e32 v4, 0
	s_and_saveexec_b64 s[38:39], vcc
	s_cbranch_execz .LBB0_218
	v_mad_i64_i32 v[6:7], s[40:41], v2, s87, v[36:37]
	global_load_dword v4, v[6:7], off nt

; __device__ __forceinline__ int bid_() { int b = blockIdx.x; asm volatile("" : "+s"(b)); return b; }
; template <int MODE>
; __device__ __forceinline__ void convT(const float* __restrict__ src, int K, int N, u16* __restrict__ dst, const float* __restrict__ scale) {
;     ...
;   const int nkt = K / 256, nnt = (N + 63) / 64, ntile = nkt * nnt;
;   const int n = tid & 63, kk = tid >> 6;
;   float v[32];
;   int tile = bid_();
;   if (tile < ntile) {
;     const int k0 = (tile % nkt) * 256, nn = (tile / nkt) * 64 + n;
; #pragma unroll
;     for (int it = 0; it < 32; ++it) v[it] = (nn < N) ? __builtin_nontemporal_load(src + (long)(k0 + kk + it * 8) * N + nn) : 0.f;
.LBB0_361:
	s_lshl_b64 s[2:3], s[8:9], 22
	s_add_u32 s34, s36, s2
	s_addc_u32 s35, s37, s3
	v_mov_b32_e32 v43, v182
	s_load_dword s38, s[0:1], 0x188
	s_lshl_b32 s44, s8, 2
	s_add_i32 s44, s44, 180
	s_sub_i32 s44, s92, s44
	s_and_b32 s44, s44, 0xff
	s_waitcnt lgkmcnt(0)
	s_cmpk_eq_u32 s38, 0x100
	s_cselect_b32 s44, s44, s92
	s_cmp_lt_i32 s44, 64
	v_and_b32_e32 v44, 63, v43
	s_cselect_b64 s[38:39], -1, 0
	s_cmp_gt_i32 s44, 63
	v_ashrrev_i32_e32 v42, 6, v43
	s_cbranch_scc1 .LBB0_427
	s_ashr_i32 s2, s44, 31
	s_lshr_b32 s2, s2, 30
	s_add_i32 s2, s44, s2
	s_and_b32 s3, s2, 0xfffffc
	s_lshl_b32 s2, s2, 4
	s_andn2_b32 s2, s2, 63
	s_sub_i32 s40, s44, s3
	s_waitcnt vmcnt(0)
	v_or_b32_e32 v4, s2, v44
	v_lshl_add_u32 v36, s40, 8, v42
	v_ashrrev_i32_e32 v5, 31, v4
	v_cmp_gt_i32_e64 s[2:3], s59, v4
	v_lshl_add_u64 v[38:39], v[4:5], 2, s[34:35]
	v_mov_b32_e32 v5, 0
	v_ashrrev_i32_e32 v37, 31, v36
	v_mov_b32_e32 v4, 0
	s_and_saveexec_b64 s[40:41], s[2:3]
	s_cbranch_execz .LBB0_364
	v_lshlrev_b64 v[6:7], 12, v[36:37]
	v_lshl_add_u64 v[6:7], v[38:39], 0, v[6:7]
	global_load_dword v4, v[6:7], off nt

; __device__ __forceinline__ int bid_() { int b = blockIdx.x; asm volatile("" : "+s"(b)); return b; }
; template <int MODE>
; __device__ __forceinline__ void convT(const float* __restrict__ src, int K, int N, u16* __restrict__ dst, const float* __restrict__ scale) {
;     ...
;   const int nkt = K / 256, nnt = (N + 63) / 64, ntile = nkt * nnt;
;   const int n = tid & 63, kk = tid >> 6;
;   float v[32];
;   int tile = bid_();
;   if (tile < ntile) {
;     const int k0 = (tile % nkt) * 256, nn = (tile / nkt) * 64 + n;
; #pragma unroll
;     for (int it = 0; it < 32; ++it) v[it] = (nn < N) ? __builtin_nontemporal_load(src + (long)(k0 + kk + it * 8) * N + nn) : 0.f;
.LBB0_505:
	s_add_u32 s24, s60, s24
	s_addc_u32 s25, s61, s25
	v_mov_b32_e32 v36, v182
	s_load_dword s2, s[0:1], 0x188
	s_lshl_b32 s38, s8, 2
	s_add_i32 s38, s38, 244
	s_sub_i32 s38, s92, s38
	s_and_b32 s38, s38, 0xff
	s_waitcnt lgkmcnt(0)
	s_cmpk_eq_u32 s2, 0x100
	s_cselect_b32 s38, s38, s92
	s_cmpk_lt_i32 s38, 0x160
	v_and_b32_e32 v46, 63, v36
	s_cselect_b64 s[2:3], -1, 0
	s_cmpk_gt_i32 s38, 0x15f
	v_ashrrev_i32_e32 v47, 6, v36
	s_cbranch_scc1 .LBB0_507
	s_ashr_i32 s34, s38, 31
	s_lshr_b32 s34, s34, 30
	s_add_i32 s34, s38, s34
	s_and_b32 s35, s34, 0xfffffc
	s_lshl_b32 s34, s34, 4
	s_andn2_b32 s34, s34, 63
	s_sub_i32 s35, s38, s35
	s_waitcnt vmcnt(0)
	v_or_b32_e32 v4, s34, v46
	v_lshl_add_u32 v2, s35, 8, v47
	v_ashrrev_i32_e32 v5, 31, v4
	v_lshl_add_u64 v[28:29], v[4:5], 2, s[24:25]
	v_add_u32_e32 v6, 8, v2
	v_add_u32_e32 v8, 16, v2
	v_add_u32_e32 v10, 24, v2
	v_add_u32_e32 v12, 32, v2
	v_add_u32_e32 v14, 40, v2
	v_add_u32_e32 v16, 48, v2
	v_add_u32_e32 v18, 56, v2
	v_mad_i64_i32 v[4:5], s[34:35], v2, s54, v[28:29]
	v_mad_i64_i32 v[6:7], s[34:35], v6, s54, v[28:29]
	v_mad_i64_i32 v[8:9], s[34:35], v8, s54, v[28:29]
	v_mad_i64_i32 v[10:11], s[34:35], v10, s54, v[28:29]
	v_mad_i64_i32 v[12:13], s[34:35], v12, s54, v[28:29]
	v_mad_i64_i32 v[14:15], s[34:35], v14, s54, v[28:29]
	v_mad_i64_i32 v[16:17], s[34:35], v16, s54, v[28:29]
	v_mad_i64_i32 v[18:19], s[34:35], v18, s54, v[28:29]
	global_load_dword v4, v[4:5], off nt
	s_nop 0
	global_load_dword v5, v[6:7], off nt
	s_nop 0
	global_load_dword v6, v[8:9], off nt
	global_load_dword v7, v[10:11], off nt
	s_nop 0
	global_load_dword v8, v[12:13], off nt
	global_load_dword v9, v[14:15], off nt
	global_load_dword v10, v[16:17], off nt
	global_load_dword v11, v[18:19], off nt
	v_add_u32_e32 v12, 64, v2
	v_add_u32_e32 v14, 0x48, v2
	v_add_u32_e32 v16, 0x50, v2
	v_add_u32_e32 v18, 0x58, v2
	v_add_u32_e32 v20, 0x60, v2
	v_add_u32_e32 v22, 0x68, v2
	v_add_u32_e32 v24, 0x70, v2
	v_add_u32_e32 v26, 0x78, v2
	v_mad_i64_i32 v[12:13], s[34:35], v12, s54, v[28:29]
	v_mad_i64_i32 v[14:15], s[34:35], v14, s54, v[28:29]
	v_mad_i64_i32 v[16:17], s[34:35], v16, s54, v[28:29]
	v_mad_i64_i32 v[18:19], s[34:35], v18, s54, v[28:29]
	v_mad_i64_i32 v[20:21], s[34:35], v20, s54, v[28:29]
	v_mad_i64_i32 v[22:23], s[34:35], v22, s54, v[28:29]
	v_mad_i64_i32 v[24:25], s[34:35], v24, s54, v[28:29]
	v_mad_i64_i32 v[26:27], s[34:35], v26, s54, v[28:29]
	global_load_dword v12, v[12:13], off nt
	s_nop 0
	global_load_dword v13, v[14:15], off nt
	s_nop 0
	global_load_dword v14, v[16:17], off nt
	global_load_dword v15, v[18:19], off nt
	s_nop 0
	global_load_dword v16, v[20:21], off nt
	global_load_dword v17, v[22:23], off nt
	global_load_dword v18, v[24:25], off nt
	global_load_dword v19, v[26:27], off nt
	v_add_u32_e32 v20, 0x80, v2
	v_add_u32_e32 v22, 0x88, v2
	v_add_u32_e32 v24, 0x90, v2
	v_add_u32_e32 v26, 0x98, v2
	v_add_u32_e32 v37, 0xb8, v2
	v_mad_i64_i32 v[20:21], s[34:35], v20, s54, v[28:29]
	v_mad_i64_i32 v[22:23], s[34:35], v22, s54, v[28:29]
	v_mad_i64_i32 v[24:25], s[34:35], v24, s54, v[28:29]
	v_mad_i64_i32 v[26:27], s[34:35], v26, s54, v[28:29]
	v_add_u32_e32 v30, 0xa0, v2
	v_add_u32_e32 v32, 0xa8, v2
	v_add_u32_e32 v34, 0xb0, v2
	v_mad_i64_i32 v[38:39], s[34:35], v37, s54, v[28:29]
	v_add_u32_e32 v37, 0xd8, v2
	v_mad_i64_i32 v[30:31], s[34:35], v30, s54, v[28:29]
	v_mad_i64_i32 v[32:33], s[34:35], v32, s54, v[28:29]
	v_mad_i64_i32 v[34:35], s[34:35], v34, s54, v[28:29]
	global_load_dword v20, v[20:21], off nt
	s_nop 0
	global_load_dword v21, v[22:23], off nt
	s_nop 0
	global_load_dword v22, v[24:25], off nt
	global_load_dword v23, v[26:27], off nt
	s_nop 0
	global_load_dword v24, v[30:31], off nt
	global_load_dword v25, v[32:33], off nt
	global_load_dword v26, v[34:35], off nt
	global_load_dword v27, v[38:39], off nt
	v_mad_i64_i32 v[38:39], s[34:35], v37, s54, v[28:29]
	v_add_u32_e32 v37, 0xe0, v2
	v_add_u32_e32 v30, 0xc0, v2
	v_add_u32_e32 v32, 0xc8, v2
	v_add_u32_e32 v34, 0xd0, v2
	v_mad_i64_i32 v[42:43], s[34:35], v37, s54, v[28:29]
	v_add_u32_e32 v37, 0xe8, v2
	v_mad_i64_i32 v[30:31], s[34:35], v30, s54, v[28:29]
	v_mad_i64_i32 v[32:33], s[34:35], v32, s54, v[28:29]
	v_mad_i64_i32 v[34:35], s[34:35], v34, s54, v[28:29]
	v_mad_i64_i32 v[44:45], s[34:35], v37, s54, v[28:29]
	v_add_u32_e32 v37, 0xf0, v2
	v_add_u32_e32 v2, 0xf8, v2
	v_mad_i64_i32 v[48:49], s[34:35], v37, s54, v[28:29]
	v_mad_i64_i32 v[50:51], s[34:35], v2, s54, v[28:29]
	global_load_dword v28, v[30:31], off nt
	global_load_dword v29, v[32:33], off nt
	s_nop 0
	global_load_dword v30, v[34:35], off nt
	global_load_dword v31, v[38:39], off nt
	global_load_dword v32, v[42:43], off nt
	global_load_dword v33, v[44:45], off nt
	s_nop 0
	global_load_dword v34, v[48:49], off nt
	global_load_dword v35, v[50:51], off nt
	s_andn2_b64 vcc, exec, s[2:3]
	s_cbranch_vccz .LBB0_508
	s_branch .LBB0_543

; __device__ __forceinline__ int bid_() { int b = blockIdx.x; asm volatile("" : "+s"(b)); return b; }
; template <int MODE>
; __device__ __forceinline__ void convT(const float* __restrict__ src, int K, int N, u16* __restrict__ dst, const float* __restrict__ scale) {
;     ...
;   const int nkt = K / 256, nnt = (N + 63) / 64, ntile = nkt * nnt;
;   const int n = tid & 63, kk = tid >> 6;
;   float v[32];
;   int tile = bid_();
;   if (tile < ntile) {
;     const int k0 = (tile % nkt) * 256, nn = (tile / nkt) * 64 + n;
; #pragma unroll
;     for (int it = 0; it < 32; ++it) v[it] = (nn < N) ? __builtin_nontemporal_load(src + (long)(k0 + kk + it * 8) * N + nn) : 0.f;
.LBB0_543:
	s_add_u32 s22, s62, s26
	s_addc_u32 s23, s63, s27
	v_mov_b32_e32 v43, v182
	s_load_dword s24, s[0:1], 0x188
	s_lshl_b32 s34, s8, 2
	s_add_i32 s34, s34, 84
	s_sub_i32 s34, s92, s34
	s_and_b32 s34, s34, 0xff
	s_waitcnt lgkmcnt(0)
	s_cmpk_eq_u32 s24, 0x100
	s_cselect_b32 s34, s34, s92
	s_cmpk_lt_i32 s34, 0xb0
	v_and_b32_e32 v46, 63, v43
	s_cselect_b64 s[24:25], -1, 0
	s_cmpk_gt_i32 s34, 0xaf
	v_ashrrev_i32_e32 v42, 6, v43
	s_cbranch_scc1 .LBB0_609
	s_mul_hi_i32 s2, s34, 0x2e8ba2e9
	s_lshr_b32 s3, s2, 31
	s_ashr_i32 s2, s2, 1
	s_add_i32 s2, s2, s3
	s_mul_i32 s3, s2, 11
	s_sub_i32 s26, s34, s3
	s_waitcnt vmcnt(31)
	v_lshl_or_b32 v4, s2, 6, v46
	v_lshl_add_u32 v36, s26, 8, v42
	s_waitcnt vmcnt(30)
	v_ashrrev_i32_e32 v5, 31, v4
	v_cmp_gt_i32_e64 s[2:3], s59, v4
	v_lshl_add_u64 v[38:39], v[4:5], 2, s[22:23]
	v_mov_b32_e32 v5, 0
	v_ashrrev_i32_e32 v37, 31, v36
	v_mov_b32_e32 v4, 0
	s_and_saveexec_b64 s[26:27], s[2:3]
	s_cbranch_execz .LBB0_546
	s_waitcnt vmcnt(28)
	v_lshlrev_b64 v[6:7], 12, v[36:37]
	v_lshl_add_u64 v[6:7], v[38:39], 0, v[6:7]
	global_load_dword v4, v[6:7], off nt

.LBB0_707:
	s_or_b64 exec, exec, s[0:1]
	s_lshl_b32 s0, s48, 9
	s_lshl_b32 s2, s33, 6
	v_writelane_b32 v249, s0, 4
	s_lshl_b32 s0, s48, 3
	s_add_i32 s8, s2, 0x500
	s_mov_b32 s9, 0
	s_mov_b32 s33, s0
	s_lshl_b64 s[0:1], s[8:9], 2
	s_add_u32 s0, s30, s0
	s_addc_u32 s1, s31, s1
	v_writelane_b32 v249, s0, 5
	s_add_i32 s8, s2, 0x900
	s_mov_b32 s12, 1
	v_writelane_b32 v249, s1, 6
	s_lshl_b64 s[0:1], s[8:9], 2
	s_add_u32 s0, s30, s0
	s_addc_u32 s1, s31, s1
	v_writelane_b32 v249, s0, 7
	v_mov_b32_e32 v172, 0
	s_mov_b32 s49, 0x2aaaaaab
	v_writelane_b32 v249, s1, 8
	s_add_u32 s0, s30, 0x200
	s_addc_u32 s1, s31, 0
	v_writelane_b32 v249, s0, 9
	s_mov_b32 s19, 0x18000
	s_movk_i32 s50, 0x1000
	v_writelane_b32 v249, s1, 10
	s_add_u32 s0, s30, 0x3400
	s_addc_u32 s1, s31, 0
	v_writelane_b32 v249, s0, 11
	s_mov_b32 s51, 0x30000
	s_mov_b32 s52, 0x60000
	v_writelane_b32 v249, s1, 12
	s_add_u32 s0, s30, 0x3500
	s_addc_u32 s1, s31, 0
	v_writelane_b32 v249, s0, 13
	s_mov_b32 s53, 0x90000
	s_mov_b32 s54, 0x3a83126f
	v_writelane_b32 v249, s1, 14
	s_lshl_b32 s0, s48, 11
	v_writelane_b32 v249, s0, 15
	v_writelane_b32 v249, s33, 16
	v_writelane_b32 v249, s92, 17
	v_writelane_b32 v249, s94, 18
	s_mov_b32 s55, 0x800000
	s_mov_b32 s56, 0x3f317217
	s_mov_b32 s57, 0x7f800000
	v_mov_b32_e32 v183, 0x358637bd
	s_movk_i32 s58, 0xb00
	v_mov_b32_e32 v184, 1
	v_mov_b32_e32 v185, 0x41b17218
	v_bfrev_b32_e32 v186, 0.5
	v_mov_b32_e32 v187, 0x20000
	v_mov_b32_e32 v188, 0x10000
	v_mov_b32_e32 v189, 0x1800
	v_mov_b32_e32 v190, 0x180
	s_movk_i32 s59, 0x161
	s_mov_b64 s[60:61], 0x2000
	s_mov_b64 s[62:63], 0x80
	v_writelane_b32 v249, s95, 19
	s_barrier
	v_writelane_b32 v249, s48, 20
	v_mbcnt_lo_u32_b32 v250, -1, 0
	v_mbcnt_hi_u32_b32 v250, -1, v250
	v_min_u32_e32 v250, 44, v250
	v_lshlrev_b32_e32 v250, 3, v250
	global_load_dwordx2 v[250:251], v250, s[94:95]
	s_waitcnt vmcnt(0)
	s_branch .LBB0_711

;   if (ph == 0) { phase_init(p); return; }
;   const int l = (ph - 1) / 12, k = (ph - 1) % 12;
;   const u16* wl = TAB_wb + (long)l * W_LAYER;
.LBB0_711:
	s_add_i32 s42, s12, -1
	s_bfe_i32 s0, s42, 0x80000
	s_mul_i32 s0, s0, 43
	s_sext_i32_i16 s1, s0
	s_ashr_i32 s1, s1, 9
	s_bfe_u32 s0, s0, 0x1000f
	s_add_i32 s0, s1, s0
	s_sext_i32_i16 s14, s0
	s_mul_i32 s0, s0, 12
	s_sub_i32 s0, s42, s0
	s_mul_i32 s20, s14, 0x2880000
	s_mul_hi_u32 s37, s14, 0x2880000
	v_readlane_b32 s35, v250, 31
	v_readlane_b32 s36, v251, 31
	s_add_u32 s66, s35, s20
	s_addc_u32 s67, s36, s37
	s_and_b32 s70, s0, 0xff
	s_cmp_lt_i32 s70, 9
	s_cbranch_scc1 .LBB0_713
	s_and_b32 s2, 0xffff, s70
	s_cmp_lg_u32 s2, 9
	s_mov_b64 s[4:5], 0
	s_mov_b64 s[0:1], -1
	s_cselect_b64 s[2:3], -1, 0
	s_branch .LBB0_714

;     ...
;   } else if (k == 1 || k == 10 || k == 7) {
;     const u16* A = (k == 7) ? TAB_ymix : TAB_big;
;     const u16* W = wl + (k == 1 ? W_DN1 : (k == 10 ? W_DN2 : W_WOUT));
;     gemm_phase<EPI_SS>(p, A, W, (k == 7) ? DM : DFF, 4, TAB_xb, DM);
.LBB0_721:
	s_andn2_b64 vcc, exec, s[4:5]
	s_cbranch_vccnz .LBB0_733
	s_cmp_eq_u32 s6, 7
	s_cbranch_scc0 .LBB0_732
	s_mov_b64 s[2:3], 0
	s_waitcnt vmcnt(0)
	v_readlane_b32 s5, v251, 34
	v_readlane_b32 s4, v250, 34
	s_nop 1
	v_writelane_b32 v249, s4, 24
	s_nop 1
	v_writelane_b32 v249, s5, 25
	s_mov_b64 s[4:5], -1
	v_writelane_b32 v249, s4, 22
	s_nop 1
	v_writelane_b32 v249, s5, 23
	s_branch .LBB0_726

; __device__ __forceinline__ int tid_() { int t = threadIdx.x; asm volatile("" : "+v"(t)); return t; }
; __device__ __forceinline__ int bid_() { int b = blockIdx.x; asm volatile("" : "+s"(b)); return b; }
; __device__ __forceinline__ void phase_statepass(const Params& p) {
;   u16* const L_prevb = TAB_prevb;
;   float* const L_states = TAB_states;
;   float* const L_lcarry = TAB_lcarry;
;   float* const L_lagg = TAB_lagg;
;   float* const L_cdec = TAB_cdec;
;   if (bid_() + 6 >= (int)gridDim.x) {
;     const int idx = (bid_() + 6 - (int)gridDim.x) * 512 + tid_();
;     if (idx < 8 * 384) {
;       const int b = idx / 384, ch = idx % 384;
;       float hc = 0.f;
; #pragma unroll 8
;       for (int c = 0; c < NCHUNK; ++c) {
;         const float2 ah = *(const float2*)(L_lagg + (((long)b * NCHUNK + c) * 384 + ch) * 2);
;         L_lcarry[((long)b * NCHUNK + c) * 384 + ch] = hc;
;         hc = ah.x * hc + ah.y;
;       }
;     }
.LBB0_738:
	s_cmp_eq_u32 s2, 5
	s_mov_b64 s[6:7], -1
	s_cbranch_scc0 .LBB0_750
	s_mov_b32 s0, s92
	s_add_i32 s0, s0, 6
	s_cmp_lt_i32 s0, s48
	s_waitcnt vmcnt(0)
	v_readlane_b32 s1, v251, 35
	v_readlane_b32 s0, v250, 35
	s_waitcnt vmcnt(2)
	v_readlane_b32 s3, v251, 38
	v_readlane_b32 s2, v250, 38
	s_waitcnt vmcnt(1)
	v_readlane_b32 s15, v251, 40
	v_readlane_b32 s14, v250, 40
	s_waitcnt vmcnt(0)
	v_readlane_b32 s13, v251, 42
	v_readlane_b32 s12, v250, 42
	v_readlane_b32 s7, v251, 43
	v_readlane_b32 s6, v250, 43
	s_cbranch_scc1 .LBB0_744
	s_mov_b32 s8, s92
	v_mov_b32_e32 v0, v182
	s_sub_i32 s8, s8, s48
	s_mov_b32 s18, s20
	v_lshl_add_u32 v0, s8, 9, v0
	v_add_u32_e32 v0, 0xc00, v0
	s_movk_i32 s8, 0xc00
	v_cmp_gt_i32_e32 vcc, s8, v0
	s_and_saveexec_b64 s[10:11], vcc
	s_mov_b64 s[20:21], 0x3000
	s_cbranch_execz .LBB0_743
	v_mul_hi_i32 v1, v0, s49
	v_lshrrev_b32_e32 v2, 31, v1
	v_ashrrev_i32_e32 v1, 6, v1
	v_add_u32_e32 v4, v1, v2
	v_mul_i32_i24_e32 v1, 0x180, v4
	v_sub_u32_e32 v2, v0, v1
	v_ashrrev_i32_e32 v3, 31, v2
	v_lshlrev_b64 v[0:1], 2, v[2:3]
	s_mov_b32 s8, 0xc000
	v_mad_i64_i32 v[0:1], s[16:17], v4, s8, v[0:1]
	v_lshl_add_u64 v[0:1], s[14:15], 0, v[0:1]
	s_mov_b64 s[14:15], 0x2a00
	v_lshlrev_b64 v[2:3], 3, v[2:3]
	v_lshl_add_u64 v[0:1], v[0:1], 0, s[14:15]
	v_mad_i64_i32 v[2:3], s[14:15], v4, s19, v[2:3]
	v_lshl_add_u64 v[2:3], s[12:13], 0, v[2:3]
	v_mov_b32_e32 v5, 0
	s_mov_b64 s[12:13], 0

; #define TAB_IN(i) uni((const float*)p.tab[(i)])
; __device__ __forceinline__ float softplus_(float x) { return fmaxf(x, 0.f) + log1p_(__expf(-fabsf(x))); }
; __device__ __forceinline__ int tid_() { int t = threadIdx.x; asm volatile("" : "+v"(t)); return t; }
; __device__ __forceinline__ void ssd_dt(const Params& p, int l, long rowbase) {
;   float* const L_dtbuf = TAB_dtbuf;
;   const float* const L_in18 = TAB_IN(18);
;   const float* const L_in19 = TAB_IN(19);
;   const int tid = tid_(); const int wid = tid >> 6, lane = tid & 63;
;   float* dts = (float*)shm;
;   float* acs = dts + 768;
;   if (wid < 6) {
;     const int h = wid;
;     const float a = -__expf(L_in19[l * 6 + h]), bias = L_in18[l * 6 + h];
;     const long row = rowbase + 2 * lane;
;     const float d0 = softplus_(L_dtbuf[row * 8 + h] + bias), d1 = softplus_(L_dtbuf[(row + 1) * 8 + h] + bias);
;     const float a0 = d0 * a, a1 = d1 * a, s = a0 + a1;
.LBB0_756:
	v_mov_b32_e32 v16, v182
	s_ashr_i32 s2, s36, 5
	s_and_b32 s8, s36, 31
	s_ashr_i32 s3, s2, 31
	s_lshl_b64 s[20:21], s[2:3], 12
	s_lshl_b32 s0, s8, 7
	s_or_b32 s20, s20, s0
	v_mov_b32_e32 v4, v182
	s_waitcnt vmcnt(0)
	v_readlane_b32 s23, v251, 33
	v_readlane_b32 s22, v250, 33
	s_waitcnt vmcnt(0)
	v_readlane_b32 s30, v251, 38
	v_readlane_b32 s31, v250, 38
	s_waitcnt vmcnt(0)
	v_readlane_b32 s28, v251, 43
	v_readlane_b32 s29, v250, 43
	s_waitcnt vmcnt(0)
	v_readlane_b32 s34, v251, 16
	v_readlane_b32 s33, v250, 16
	v_readlane_b32 s41, v251, 17
	v_readlane_b32 s35, v250, 17
	s_waitcnt vmcnt(0)
	v_readlane_b32 s1, v251, 41
	v_readlane_b32 s0, v250, 41
	s_waitcnt vmcnt(0)
	v_readlane_b32 s24, v250, 18
	v_ashrrev_i32_e32 v0, 6, v4
	v_readlane_b32 s25, v251, 18
	v_readlane_b32 s27, v251, 19
	v_readlane_b32 s26, v250, 19
	v_cmp_gt_i32_e32 vcc, 6, v0
	s_and_saveexec_b64 s[10:11], vcc
	s_cbranch_execz .LBB0_766
	v_add_u32_e32 v2, s37, v0
	v_ashrrev_i32_e32 v3, 31, v2
	v_lshlrev_b64 v[2:3], 2, v[2:3]
	v_and_b32_e32 v5, 63, v4
	v_lshl_add_u64 v[6:7], s[26:27], 0, v[2:3]
	flat_load_dword v7, v[6:7]
	v_lshl_add_u64 v[2:3], s[24:25], 0, v[2:3]
	v_lshlrev_b32_e32 v6, 1, v5
	flat_load_dword v9, v[2:3]
	v_or_b32_e32 v2, s20, v6
	v_mov_b32_e32 v3, s21
	v_lshlrev_b64 v[2:3], 5, v[2:3]
	v_ashrrev_i32_e32 v1, 31, v0
	v_lshl_add_u64 v[2:3], s[0:1], 0, v[2:3]
	v_lshl_add_u64 v[2:3], v[0:1], 2, v[2:3]
	flat_load_dword v1, v[2:3]
	s_mov_b32 s0, 0xbfb8aa3b
	s_waitcnt vmcnt(0) lgkmcnt(0)
	v_add_f32_e32 v1, v9, v1
	v_mul_f32_e64 v8, |v1|, s0
	v_exp_f32_e32 v10, v8
	s_nop 0
	v_cmp_ngt_f32_e32 vcc, s54, v10
	s_and_saveexec_b64 s[0:1], vcc
	s_xor_b64 s[24:25], exec, s[0:1]
	s_cbranch_execz .LBB0_759
	v_add_f32_e32 v8, 1.0, v10
	v_cmp_gt_f32_e32 vcc, s55, v8
	s_nop 1
	v_cndmask_b32_e64 v10, 0, 32, vcc
	v_ldexp_f32 v8, v8, v10
	v_log_f32_e32 v8, v8
	s_nop 0
	v_mul_f32_e32 v10, 0x3f317217, v8
	v_fma_f32 v10, v8, s56, -v10
	v_fmac_f32_e32 v10, 0x3377d1cf, v8
	v_fmac_f32_e32 v10, 0x3f317217, v8
	v_cmp_lt_f32_e64 s[0:1], |v8|, s57
	s_nop 1
	v_cndmask_b32_e64 v8, v8, v10, s[0:1]
	v_cndmask_b32_e32 v10, 0, v185, vcc
	v_sub_f32_e32 v8, v8, v10

; #define TAB_IN(i) uni((const float*)p.tab[(i)])
; __device__ __forceinline__ int tid_() { int t = threadIdx.x; asm volatile("" : "+v"(t)); return t; }
; template <int NCG, class F>
; __device__ __forceinline__ void conv_chunk(const u16* __restrict__ proj, int c, long rowbase, int col,
;                                            const float* __restrict__ cw, int cstride, const float* __restrict__ cb, F store) {
;   const int tid = tid_(); const int wid = tid >> 6, lane = tid & 63;
;   const int t0 = wid * 16;
;   const bool has_prev = !(c == 0 && wid == 0);
;   const u16* src = proj + (rowbase + t0) * PS + col + lane;
;   u16 raw[NCG][19];
; #pragma unroll
;   for (int i = 0; i < NCG; ++i) {
; #pragma unroll
;     for (int r = 0; r < 3; ++r) raw[i][r] = has_prev ? src[(long)(r - 3) * PS + i * 64] : (u16)0;
; #pragma unroll
;     for (int r = 0; r < 16; ++r) raw[i][3 + r] = src[(long)r * PS + i * 64];
; __device__ __forceinline__ void lru_chunk(const Params& p, int l, int b, int c, bool final) {
;   u16* const L_big = TAB_big;
;   u16* const L_ymix = TAB_ymix;
;   u16* const L_wgt = TAB_wgt;
;   float* const L_lcarry = TAB_lcarry;
;   float* const L_lagg = TAB_lagg;
;   const float* const L_in9 = TAB_IN(9);
;   const float* const L_in10 = TAB_IN(10);
;   const float* const L_in12 = TAB_IN(12);
;   const float* const L_in14 = TAB_IN(14);
;   const float* const L_in15 = TAB_IN(15);
;   const int tid = tid_(), wid = tid >> 6, lane = tid & 63, fr = lane & 15, fq = lane >> 4;
;   const long rowbase = (long)b * SEQ + c * 128;
;   const u16* proj = L_big;
;   constexpr int RROW = 392;
;   u16* rec = (u16*)shm;
;   conv_chunk<6>(proj, c, rowbase, PC_REC, L_in9 + l * 4 * 384, 384, L_in10 + l * 384,
;              [&](int t, int chl, float y) { rec[t * RROW + chl] = f2bf(y); });
.LBB0_800:
	global_load_dwordx2 v[16:17], v172, s[94:95] offset:296
	global_load_dwordx2 v[18:19], v172, s[94:95] offset:336
	global_load_dwordx4 v[6:9], v172, s[94:95] offset:72
	global_load_dwordx2 v[20:21], v172, s[94:95] offset:96
	v_mov_b32_e32 v5, v182
	v_mov_b32_e32 v0, v182
	s_movk_i32 s41, 0x1600
	v_ashrrev_i32_e32 v109, 2, v0
	v_and_b32_e32 v4, 63, v0
	v_cmp_lt_u32_e32 vcc, 63, v0
	v_and_b32_e32 v0, -16, v109
	v_ashrrev_i32_e32 v1, 31, v0
	v_lshl_add_u64 v[22:23], s[20:21], 0, v[0:1]
	v_mov_b32_e32 v3, v172
	v_lshlrev_b32_e32 v2, 1, v4
	v_mov_b32_e32 v110, 0
	s_or_b64 s[0:1], s[24:25], vcc
	v_mov_b32_e32 v1, 0
	s_waitcnt vmcnt(0)
	v_readlane_b32 s10, v251, 33
	v_readlane_b32 s11, v250, 33
	v_readfirstlane_b32 s23, v17
	v_readfirstlane_b32 s34, v7
	v_readfirstlane_b32 s35, v6
	v_mov_b32_e32 v6, s11
	v_mov_b32_e32 v7, s10
	v_mad_u64_u32 v[6:7], s[10:11], v22, s41, v[6:7]
	v_readfirstlane_b32 s33, v8
	v_mov_b32_e32 v8, v7
	v_readfirstlane_b32 s8, v9
	v_mad_u64_u32 v[8:9], s[10:11], v23, s41, v[8:9]
	v_mov_b32_e32 v7, v8
	v_readlane_b32 s31, v251, 15
	v_readlane_b32 s30, v250, 15
	v_lshl_add_u64 v[12:13], v[6:7], 0, v[2:3]
	s_mov_b64 s[10:11], 0x300
	v_readfirstlane_b32 s22, v16
	v_readfirstlane_b32 s25, v19
	v_readfirstlane_b32 s24, v18
	v_readfirstlane_b32 s27, v21
	v_readfirstlane_b32 s26, v20
	v_readlane_b32 s29, v251, 14
	v_readlane_b32 s28, v250, 14
	v_lshl_add_u64 v[10:11], v[12:13], 0, s[10:11]
	s_and_saveexec_b64 s[10:11], s[0:1]
	s_cbranch_execz .LBB0_802
	v_add_co_u32_e32 v6, vcc, 0xffffbe00, v10
	s_nop 1
	v_addc_co_u32_e32 v7, vcc, -1, v11, vcc
	flat_load_ushort v1, v[6:7]
	s_waitcnt vmcnt(0) lgkmcnt(0)
	v_lshlrev_b32_e32 v1, 16, v1

; #define TAB_IN(i) uni((const float*)p.tab[(i)])
; __device__ __forceinline__ int tid_() { int t = threadIdx.x; asm volatile("" : "+v"(t)); return t; }
; __device__ __forceinline__ void sgu_chunk(const Params& p, int l, int b, int c) {
;   u16* const L_big = TAB_big;
;   u16* const L_ymix = TAB_ymix;
;   u16* const L_wmask = TAB_wmask;
;   const float* const L_in22 = TAB_IN(22);
;   const float* const L_in23 = TAB_IN(23);
;   const float* const L_in25 = TAB_IN(25);
;   const int tid = tid_(), wid = tid >> 6, lane = tid & 63, fr = lane & 15, fq = lane >> 4;
;   const long rowbase = (long)b * SEQ + c * 128;
;   const u16* proj = L_big;
;   u16* vT = (u16*)shm;
;   float lg[4], lb[4];
; #pragma unroll
;   for (int e = 0; e < 4; ++e) { lg[e] = L_in22[l * 256 + lane + 64 * e]; lb[e] = L_in23[l * 256 + lane + 64 * e]; }
;   {
;     u16 rv[16][4];
; #pragma unroll
;     for (int i = 0; i < 16; ++i)
; #pragma unroll
;       for (int e = 0; e < 4; ++e) rv[i][e] = proj[(rowbase + wid * 16 + i) * PS + PC_V + lane + 64 * e];
.LBB0_846:
	s_waitcnt lgkmcnt(0)
	s_barrier
	global_load_dwordx4 v[30:33], v172, s[94:95] offset:264
	global_load_dwordx2 v[4:5], v172, s[94:95] offset:200
	v_mov_b32_e32 v11, v182
	s_movk_i32 s25, 0x1600
	v_ashrrev_i32_e32 v9, 6, v11
	v_lshlrev_b32_e32 v6, 4, v9
	v_ashrrev_i32_e32 v7, 31, v6
	v_lshl_add_u64 v[12:13], s[20:21], 0, v[6:7]
	v_and_b32_e32 v15, 63, v11
	v_mov_b32_e32 v1, v172
	v_lshlrev_b32_e32 v0, 1, v15
	s_movk_i32 s23, 0x2000
	s_movk_i32 s24, 0x3000
	v_mov_b32_e32 v29, v172
	v_or_b32_e32 v28, s39, v15
	v_lshlrev_b64 v[28:29], 2, v[28:29]
	s_mov_b32 s26, 0x3b800000
	v_mul_u32_u24_e32 v15, 0x110, v15
	v_lshl_add_u32 v15, v9, 5, v15
	v_and_b32_e32 v104, 48, v11
	v_mov_b32_e32 v105, v172
	s_waitcnt vmcnt(0)
	v_readfirstlane_b32 s1, v31
	v_readfirstlane_b32 s0, v30
	v_readlane_b32 s3, v251, 22
	v_readlane_b32 s2, v250, 22
	v_mov_b64_e32 v[6:7], s[0:1]
	v_mad_u64_u32 v[16:17], s[0:1], v12, s25, v[6:7]
	v_mov_b32_e32 v8, v17
	v_mad_u64_u32 v[12:13], s[0:1], v13, s25, v[8:9]
	v_mov_b32_e32 v17, v12
	v_lshl_add_u64 v[0:1], v[16:17], 0, v[0:1]
	v_add_co_u32_e32 v12, vcc, s50, v0
	s_mov_b64 s[0:1], 0x1200
	s_nop 0
	v_addc_co_u32_e32 v13, vcc, 0, v1, vcc
	v_add_co_u32_e32 v18, vcc, s23, v0
	v_lshl_add_u64 v[48:49], v[0:1], 0, s[0:1]
	s_nop 0
	v_addc_co_u32_e32 v19, vcc, 0, v1, vcc
	v_add_co_u32_e32 v20, vcc, s24, v0
	s_movk_i32 s0, 0x5000
	s_nop 0
	v_addc_co_u32_e32 v21, vcc, 0, v1, vcc
	v_add_co_u32_e32 v22, vcc, s0, v0
	s_mov_b64 s[0:1], 0x2800
	s_nop 0
	v_addc_co_u32_e32 v23, vcc, 0, v1, vcc
	flat_load_ushort v17, v[12:13] offset:512
	s_nop 0
	flat_load_ushort v19, v[18:19] offset:2048
	s_nop 0
	flat_load_ushort v21, v[20:21] offset:3584
	s_nop 0
	flat_load_ushort v23, v[22:23] offset:1024
	v_lshl_add_u64 v[52:53], v[0:1], 0, s[0:1]
	s_mov_b64 s[0:1], 0x3e00
	v_lshl_add_u64 v[46:47], v[0:1], 0, s[0:1]
	s_mov_b64 s[0:1], 0x5400
	v_lshl_add_u64 v[54:55], v[0:1], 0, s[0:1]
	flat_load_ushort v65, v[54:55] offset:128
	flat_load_ushort v64, v[46:47] offset:128
	flat_load_ushort v63, v[52:53] offset:128
	flat_load_ushort v62, v[48:49] offset:128
	v_readlane_b32 s1, v251, 36
	v_readlane_b32 s0, v250, 36
	v_lshl_add_u64 v[2:3], s[2:3], 0, v[28:29]
	s_mov_b64 s[2:3], 0x6a00
	v_lshl_add_u64 v[50:51], v[0:1], 0, s[2:3]
	s_mov_b64 s[2:3], 0x8000
	v_lshl_add_u64 v[40:41], v[0:1], 0, s[2:3]
	s_mov_b64 s[2:3], 0x9600
	v_lshl_add_u64 v[42:43], v[0:1], 0, s[2:3]
	s_mov_b64 s[2:3], 0xac00
	v_lshl_add_u64 v[44:45], v[0:1], 0, s[2:3]
	s_mov_b64 s[2:3], 0xc200
	v_lshl_add_u64 v[30:31], v[0:1], 0, s[2:3]
	s_mov_b64 s[2:3], 0xd800
	v_readlane_b32 s11, v251, 23
	v_readlane_b32 s10, v250, 23
	v_lshl_add_u64 v[34:35], v[0:1], 0, s[2:3]
	s_mov_b64 s[2:3], 0xee00
	v_lshl_add_u64 v[24:25], s[10:11], 0, v[28:29]
	flat_load_dword v20, v[2:3]
	flat_load_dword v16, v[2:3] offset:256
	flat_load_dword v12, v[2:3] offset:512
	flat_load_dword v8, v[2:3] offset:768
	flat_load_dword v22, v[24:25]
	flat_load_dword v18, v[24:25] offset:256
	flat_load_dword v14, v[24:25] offset:512
	flat_load_dword v10, v[24:25] offset:768
	v_lshl_add_u64 v[2:3], v[0:1], 0, s[2:3]
	s_mov_b64 s[2:3], 0x10400
	v_lshl_add_u64 v[36:37], v[0:1], 0, s[2:3]
	s_mov_b64 s[2:3], 0x11a00
	v_lshl_add_u64 v[38:39], v[0:1], 0, s[2:3]
	s_mov_b64 s[2:3], 0x13000
	v_lshl_add_u64 v[24:25], v[0:1], 0, s[2:3]
	s_mov_b64 s[2:3], 0x14600
	v_lshl_add_u64 v[26:27], v[0:1], 0, s[2:3]
	s_mov_b64 s[2:3], 0x15c00
	v_lshl_add_u64 v[28:29], v[0:1], 0, s[2:3]
	s_movk_i32 s2, 0x6000
	v_add_co_u32_e32 v56, vcc, s2, v0
	s_mov_b32 s2, 0x8000
	s_nop 0
	v_addc_co_u32_e32 v57, vcc, 0, v1, vcc
	v_add_co_u32_e32 v58, vcc, s2, v0
	s_mov_b32 s2, 0x9000
	s_nop 0
	v_addc_co_u32_e32 v59, vcc, 0, v1, vcc
	v_add_co_u32_e32 v60, vcc, s2, v0
	s_mov_b32 s2, 0xa000
	s_nop 0
	v_addc_co_u32_e32 v61, vcc, 0, v1, vcc
	v_add_co_u32_e32 v70, vcc, s2, v0
	v_and_b32_e32 v13, 15, v11
	s_nop 0
	v_addc_co_u32_e32 v71, vcc, 0, v1, vcc
	flat_load_ushort v72, v[48:49] offset:256
	flat_load_ushort v73, v[52:53] offset:256
	flat_load_ushort v74, v[46:47] offset:256
	flat_load_ushort v75, v[52:53] offset:384
	flat_load_ushort v76, v[48:49] offset:384
	flat_load_ushort v77, v[54:55] offset:256
	flat_load_ushort v78, v[54:55] offset:384
	flat_load_ushort v67, v[50:51] offset:128
	flat_load_ushort v66, v[40:41] offset:128
	flat_load_ushort v68, v[50:51] offset:256
	flat_load_ushort v69, v[50:51] offset:384
	flat_load_ushort v79, v[46:47] offset:384
	flat_load_ushort v80, v[56:57] offset:2560
	flat_load_ushort v81, v[58:59]
	flat_load_ushort v82, v[60:61] offset:1536
	flat_load_ushort v83, v[70:71] offset:3072
	s_waitcnt vmcnt(0) lgkmcnt(0)
; __device__ __forceinline__ float bf2f(u16 h) { return __uint_as_float(((unsigned)h) << 16); }
; __device__ __forceinline__ float gelu_(float x) { float u = 0.7978845608028654f * (x + 0.044715f * x * x * x); return x * rcp_(1.f + __expf(-2.f * u)); }
; __device__ __forceinline__ float rsq_(float x) { return __builtin_amdgcn_rsqf(x); }
; __device__ __forceinline__ void sgu_chunk(const Params& p, int l, int b, int c) {
;     ...
;       for (int e = 0; e < 4; ++e) rv[i][e] = proj[(rowbase + wid * 16 + i) * PS + PC_V + lane + 64 * e];
; #pragma unroll
;     for (int i = 0; i < 16; ++i) {
;       const int t = wid * 16 + i;
;       float v[4], s = 0.f;
; #pragma unroll
;       for (int e = 0; e < 4; ++e) { v[e] = gelu_(bf2f(rv[i][e])); s += v[e]; }
;       const float mean = wave_sum(s) * (1.f / 256.f);
;       float q = 0.f;
; #pragma unroll
;       for (int e = 0; e < 4; ++e) { v[e] -= mean; q += v[e] * v[e]; }
;       const float rs = rsq_(wave_sum(q) * (1.f / 256.f) + EPS);
	v_lshlrev_b32_e32 v48, 16, v17
	v_lshlrev_b32_e32 v49, 16, v19
	v_lshlrev_b32_e32 v46, 16, v21
	v_lshlrev_b32_e32 v47, 16, v23
	v_mul_f32_e32 v23, 0x3d372713, v47
	v_mul_f32_e32 v23, v23, v47
	v_fma_f32 v23, v23, v47, v47
	v_mul_f32_e32 v21, 0x3d372713, v46
	v_mul_f32_e32 v23, 0x3f4c422a, v23
	v_mul_f32_e32 v21, v21, v46
	v_mul_f32_e32 v23, -2.0, v23
	v_fma_f32 v21, v21, v46, v46
	v_mul_f32_e32 v23, 0x3fb8aa3b, v23
	v_mul_f32_e32 v17, 0x3d372713, v48
	v_mul_f32_e32 v19, 0x3d372713, v49
	v_mul_f32_e32 v21, 0x3f4c422a, v21
	v_exp_f32_e32 v23, v23
	v_mul_f32_e32 v17, v17, v48
	v_mul_f32_e32 v19, v19, v49
	v_mul_f32_e32 v21, -2.0, v21
	v_fma_f32 v17, v17, v48, v48
	v_fma_f32 v19, v19, v49, v49
	v_mul_f32_e32 v21, 0x3fb8aa3b, v21
	v_lshlrev_b32_e32 v50, 16, v64
	v_mul_f32_e32 v17, 0x3f4c422a, v17
	v_mul_f32_e32 v19, 0x3f4c422a, v19
	v_exp_f32_e32 v21, v21
	v_lshlrev_b32_e32 v51, 16, v65
	v_lshlrev_b32_e32 v53, 16, v63
	v_lshlrev_b32_e32 v52, 16, v62
	v_mul_f32_e32 v56, 0x3d372713, v50
	v_mul_f32_e32 v17, -2.0, v17
	v_mul_f32_e32 v19, -2.0, v19
	v_add_f32_e32 v23, 1.0, v23
	v_mul_f32_e32 v54, 0x3d372713, v52
	v_mul_f32_e32 v55, 0x3d372713, v53
	v_mul_f32_e32 v56, v56, v50
	v_mul_f32_e32 v17, 0x3fb8aa3b, v17
	v_mul_f32_e32 v19, 0x3fb8aa3b, v19
	v_rcp_f32_e32 v57, v23
	v_mul_f32_e32 v23, 0x3d372713, v51
	v_mul_f32_e32 v54, v54, v52
	v_mul_f32_e32 v55, v55, v53
	v_fma_f32 v56, v56, v50, v50
	v_exp_f32_e32 v17, v17
	v_exp_f32_e32 v19, v19
	v_mul_f32_e32 v23, v23, v51
	v_fma_f32 v54, v54, v52, v52
	v_fma_f32 v55, v55, v53, v53
	v_mul_f32_e32 v59, 0x3f4c422a, v56
	v_add_f32_e32 v21, 1.0, v21
	v_fma_f32 v23, v23, v51, v51
	v_mul_f32_e32 v54, 0x3f4c422a, v54
	v_mul_f32_e32 v55, 0x3f4c422a, v55
	v_rcp_f32_e32 v56, v21
	v_mul_f32_e32 v21, -2.0, v59
	v_mul_f32_e32 v23, 0x3f4c422a, v23
	v_mul_f32_e32 v54, -2.0, v54
	v_mul_f32_e32 v55, -2.0, v55
	v_mul_f32_e32 v21, 0x3fb8aa3b, v21
	v_mul_f32_e32 v23, -2.0, v23
	v_mul_f32_e32 v54, 0x3fb8aa3b, v54
	v_mul_f32_e32 v55, 0x3fb8aa3b, v55
	v_add_f32_e32 v17, 1.0, v17
	v_add_f32_e32 v19, 1.0, v19
	v_exp_f32_e32 v21, v21
	v_mul_f32_e32 v23, 0x3fb8aa3b, v23
	v_exp_f32_e32 v58, v54
	v_exp_f32_e32 v60, v55
	v_rcp_f32_e32 v54, v17
	v_rcp_f32_e32 v55, v19
	v_exp_f32_e32 v23, v23
	v_add_f32_e32 v21, 1.0, v21
	v_add_f32_e32 v17, 1.0, v58
	v_pk_mul_f32 v[48:49], v[54:55], v[48:49]
	v_rcp_f32_e32 v54, v21
	v_add_f32_e32 v21, 1.0, v23
	v_rcp_f32_e32 v55, v21
	v_pk_mul_f32 v[46:47], v[56:57], v[46:47]
	v_add_f32_e32 v56, 1.0, v60
	v_rcp_f32_e32 v58, v17
	v_pk_mul_f32 v[50:51], v[54:55], v[50:51]
	v_lshlrev_b32_e32 v54, 16, v72
	v_mul_f32_e32 v55, 0x3d372713, v54
	v_mul_f32_e32 v55, v55, v54
	v_rcp_f32_e32 v59, v56
	v_fma_f32 v55, v55, v54, v54
	v_mul_f32_e32 v55, 0x3f4c422a, v55
	v_mul_f32_e32 v55, -2.0, v55
	v_mul_f32_e32 v55, 0x3fb8aa3b, v55
	v_pk_mul_f32 v[52:53], v[58:59], v[52:53]
	v_exp_f32_e32 v58, v55
	v_lshlrev_b32_e32 v55, 16, v73
	v_lshlrev_b32_e32 v57, 16, v77
	v_lshlrev_b32_e32 v56, 16, v74
	v_mul_f32_e32 v59, 0x3d372713, v55
	v_mul_f32_e32 v59, v59, v55
	v_mul_f32_e32 v60, 0x3d372713, v56
	v_mul_f32_e32 v61, 0x3d372713, v57
	v_fma_f32 v59, v59, v55, v55
	v_mul_f32_e32 v60, v60, v56
	v_mul_f32_e32 v61, v61, v57
	v_mul_f32_e32 v59, 0x3f4c422a, v59
	v_fma_f32 v60, v60, v56, v56
	v_fma_f32 v61, v61, v57, v57
	v_mul_f32_e32 v59, -2.0, v59
	v_mul_f32_e32 v60, 0x3f4c422a, v60
	v_mul_f32_e32 v61, 0x3f4c422a, v61
	v_mul_f32_e32 v59, 0x3fb8aa3b, v59
	v_mul_f32_e32 v60, -2.0, v60
	v_mul_f32_e32 v61, -2.0, v61
	v_exp_f32_e32 v59, v59
	v_mul_f32_e32 v60, 0x3fb8aa3b, v60
	v_mul_f32_e32 v61, 0x3fb8aa3b, v61
	v_exp_f32_e32 v60, v60
	v_exp_f32_e32 v61, v61
	v_add_f32_e32 v58, 1.0, v58
	v_add_f32_e32 v59, 1.0, v59
	v_rcp_f32_e32 v58, v58
	v_add_f32_e32 v60, 1.0, v60
	v_add_f32_e32 v61, 1.0, v61
	v_rcp_f32_e32 v59, v59
	v_rcp_f32_e32 v60, v60
	v_rcp_f32_e32 v61, v61
	v_add_f32_e32 v17, 0, v48
	v_pk_mul_f32 v[54:55], v[58:59], v[54:55]
	v_lshlrev_b32_e32 v58, 16, v76
	v_pk_mul_f32 v[56:57], v[60:61], v[56:57]
	v_mul_f32_e32 v60, 0x3d372713, v58
	v_mul_f32_e32 v60, v60, v58
	v_fma_f32 v60, v60, v58, v58
	v_mul_f32_e32 v60, 0x3f4c422a, v60
	v_mul_f32_e32 v60, -2.0, v60
	v_lshlrev_b32_e32 v59, 16, v75
	v_mul_f32_e32 v60, 0x3fb8aa3b, v60
	v_exp_f32_e32 v61, v60
	v_mul_f32_e32 v60, 0x3d372713, v59
	v_mul_f32_e32 v60, v60, v59
	v_fma_f32 v60, v60, v59, v59
	v_mul_f32_e32 v60, 0x3f4c422a, v60
	v_mul_f32_e32 v60, -2.0, v60
	v_mul_f32_e32 v60, 0x3fb8aa3b, v60
	v_exp_f32_e32 v63, v60
	v_lshlrev_b32_e32 v60, 16, v79
	v_add_f32_e32 v61, 1.0, v61
	v_rcp_f32_e32 v62, v61
	v_add_f32_e32 v61, 1.0, v63
	v_mul_f32_e32 v63, 0x3d372713, v60
	v_mul_f32_e32 v63, v63, v60
	v_fma_f32 v63, v63, v60, v60
	v_mul_f32_e32 v63, 0x3f4c422a, v63
	v_mul_f32_e32 v63, -2.0, v63
	v_mul_f32_e32 v63, 0x3fb8aa3b, v63
	v_exp_f32_e32 v64, v63
	v_rcp_f32_e32 v63, v61
	v_add_f32_e32 v17, v17, v52
	v_add_f32_e32 v17, v17, v54
	v_lshlrev_b32_e32 v61, 16, v78
	v_pk_mul_f32 v[58:59], v[62:63], v[58:59]
	v_add_f32_e32 v64, 1.0, v64
	v_add_f32_e32 v17, v17, v58
	ds_swizzle_b32 v63, v17 offset:swizzle(SWAP,1)
	v_rcp_f32_e32 v62, v64
	v_mul_f32_e32 v64, 0x3d372713, v61
	v_mul_f32_e32 v64, v64, v61
	v_fma_f32 v64, v64, v61, v61
	s_waitcnt lgkmcnt(0)
	v_add_f32_e32 v17, v17, v63
	ds_swizzle_b32 v63, v17 offset:swizzle(SWAP,2)
	v_mul_f32_e32 v64, 0x3f4c422a, v64
	v_mul_f32_e32 v64, -2.0, v64
	v_mul_f32_e32 v64, 0x3fb8aa3b, v64
	v_exp_f32_e32 v64, v64
	s_waitcnt lgkmcnt(0)
	v_add_f32_e32 v17, v17, v63
	ds_swizzle_b32 v65, v17 offset:swizzle(SWAP,4)
	v_add_f32_e32 v19, 0, v49
	v_add_f32_e32 v19, v19, v53
	v_add_f32_e32 v19, v19, v55
	v_add_f32_e32 v19, v19, v59
	v_add_f32_e32 v63, 1.0, v64
	ds_swizzle_b32 v70, v19 offset:swizzle(SWAP,1)
	v_rcp_f32_e32 v63, v63
	s_waitcnt lgkmcnt(1)
; __device__ __forceinline__ float bf2f(u16 h) { return __uint_as_float(((unsigned)h) << 16); }
; __device__ __forceinline__ float gelu_(float x) { float u = 0.7978845608028654f * (x + 0.044715f * x * x * x); return x * rcp_(1.f + __expf(-2.f * u)); }
; __device__ __forceinline__ float rsq_(float x) { return __builtin_amdgcn_rsqf(x); }
; __device__ __forceinline__ void sgu_chunk(const Params& p, int l, int b, int c) {
;     ...
;     for (int i = 0; i < 16; ++i) {
;       const int t = wid * 16 + i;
;       float v[4], s = 0.f;
; #pragma unroll
;       for (int e = 0; e < 4; ++e) { v[e] = gelu_(bf2f(rv[i][e])); s += v[e]; }
;       const float mean = wave_sum(s) * (1.f / 256.f);
;       float q = 0.f;
; #pragma unroll
;       for (int e = 0; e < 4; ++e) { v[e] -= mean; q += v[e] * v[e]; }
;       const float rs = rsq_(wave_sum(q) * (1.f / 256.f) + EPS);
	v_add_f32_e32 v17, v17, v65
	ds_swizzle_b32 v64, v17 offset:swizzle(SWAP,8)
	v_add_f32_e32 v21, 0, v46
	v_add_f32_e32 v21, v21, v50
	v_add_f32_e32 v21, v21, v56
	v_pk_mul_f32 v[60:61], v[62:63], v[60:61]
	s_waitcnt lgkmcnt(1)
	v_add_f32_e32 v19, v19, v70
	v_add_f32_e32 v21, v21, v60
	ds_swizzle_b32 v65, v19 offset:swizzle(SWAP,2)
	s_waitcnt lgkmcnt(1)
	v_add_f32_e32 v17, v17, v64
	ds_swizzle_b32 v64, v21 offset:swizzle(SWAP,1)
	ds_swizzle_b32 v62, v17 offset:swizzle(SWAP,16)
	v_add_f32_e32 v23, 0, v47
	s_waitcnt lgkmcnt(2)
	v_add_f32_e32 v19, v19, v65
	ds_swizzle_b32 v63, v19 offset:swizzle(SWAP,4)
	s_waitcnt lgkmcnt(2)
	v_add_f32_e32 v21, v21, v64
	s_waitcnt lgkmcnt(1)
	v_add_f32_e32 v17, v17, v62
	ds_swizzle_b32 v62, v21 offset:swizzle(SWAP,2)
	v_add_f32_e32 v23, v23, v51
	v_add_f32_e32 v23, v23, v57
	v_add_f32_e32 v23, v23, v61
	s_waitcnt lgkmcnt(1)
	v_add_f32_e32 v19, v19, v63
	ds_swizzle_b32 v64, v23 offset:swizzle(SWAP,1)
	s_waitcnt lgkmcnt(1)
	v_add_f32_e32 v21, v21, v62
	ds_swizzle_b32 v63, v19 offset:swizzle(SWAP,8)
	ds_swizzle_b32 v62, v21 offset:swizzle(SWAP,4)
	v_readlane_b32 s2, v17, 0
	s_waitcnt lgkmcnt(2)
	v_add_f32_e32 v23, v23, v64
	v_readlane_b32 s8, v17, 32
	s_waitcnt lgkmcnt(1)
	v_add_f32_e32 v19, v19, v63
	ds_swizzle_b32 v63, v23 offset:swizzle(SWAP,2)
	s_waitcnt lgkmcnt(1)
	v_add_f32_e32 v21, v21, v62
	ds_swizzle_b32 v62, v21 offset:swizzle(SWAP,8)
	ds_swizzle_b32 v64, v19 offset:swizzle(SWAP,16)
	s_waitcnt lgkmcnt(2)
	v_add_f32_e32 v17, v23, v63
	ds_swizzle_b32 v23, v17 offset:swizzle(SWAP,4)
	s_waitcnt lgkmcnt(2)
	v_add_f32_e32 v21, v21, v62
	ds_swizzle_b32 v62, v21 offset:swizzle(SWAP,16)
	s_waitcnt lgkmcnt(2)
	v_add_f32_e32 v19, v19, v64
	s_waitcnt lgkmcnt(1)
	v_add_f32_e32 v17, v17, v23
	v_readlane_b32 s11, v19, 32
	v_readlane_b32 s3, v19, 0
	ds_swizzle_b32 v23, v17 offset:swizzle(SWAP,8)
	s_waitcnt lgkmcnt(1)
	v_add_f32_e32 v19, v21, v62
	v_mov_b32_e32 v62, s8
	v_mov_b32_e32 v63, s11
	v_pk_add_f32 v[62:63], s[2:3], v[62:63]
	s_waitcnt lgkmcnt(0)
	v_add_f32_e32 v17, v17, v23
	v_pk_fma_f32 v[52:53], v[62:63], s[26:27], v[52:53] op_sel_hi:[1,0,1] neg_lo:[1,0,0] neg_hi:[1,0,0]
	v_pk_fma_f32 v[48:49], v[62:63], s[26:27], v[48:49] op_sel_hi:[1,0,1] neg_lo:[1,0,0] neg_hi:[1,0,0]
	v_mul_f32_e32 v21, v52, v52
	v_fmac_f32_e32 v21, v48, v48
	v_pk_fma_f32 v[64:65], v[62:63], s[26:27], v[54:55] op_sel_hi:[1,0,1] neg_lo:[1,0,0] neg_hi:[1,0,0]
	v_pk_fma_f32 v[58:59], v[62:63], s[26:27], v[58:59] op_sel_hi:[1,0,1] neg_lo:[1,0,0] neg_hi:[1,0,0]
	v_fmac_f32_e32 v21, v64, v64
	v_readlane_b32 s10, v19, 0
	v_readlane_b32 s22, v19, 32
	ds_swizzle_b32 v19, v17 offset:swizzle(SWAP,16)
	v_fmac_f32_e32 v21, v58, v58
	ds_swizzle_b32 v23, v21 offset:swizzle(SWAP,1)
	v_mov_b32_e32 v54, s22
	s_waitcnt lgkmcnt(1)
	v_add_f32_e32 v17, v17, v19
	s_nop 0
	v_readlane_b32 s11, v17, 0
	v_readlane_b32 s2, v17, 32
	s_waitcnt lgkmcnt(0)
	v_add_f32_e32 v17, v21, v23
	v_mul_f32_e32 v21, v53, v53
	v_fmac_f32_e32 v21, v49, v49
	v_fmac_f32_e32 v21, v65, v65
	v_fmac_f32_e32 v21, v59, v59
	ds_swizzle_b32 v19, v17 offset:swizzle(SWAP,2)
	ds_swizzle_b32 v23, v21 offset:swizzle(SWAP,1)
	v_mov_b32_e32 v55, s2
	v_pk_add_f32 v[54:55], s[10:11], v[54:55]
	s_waitcnt lgkmcnt(1)
	v_add_f32_e32 v17, v17, v19
	s_waitcnt lgkmcnt(0)
	v_add_f32_e32 v21, v21, v23
	ds_swizzle_b32 v19, v17 offset:swizzle(SWAP,4)
	ds_swizzle_b32 v23, v21 offset:swizzle(SWAP,2)
	v_pk_fma_f32 v[50:51], v[54:55], s[26:27], v[50:51] op_sel_hi:[1,0,1] neg_lo:[1,0,0] neg_hi:[1,0,0]
	v_pk_fma_f32 v[46:47], v[54:55], s[26:27], v[46:47] op_sel_hi:[1,0,1] neg_lo:[1,0,0] neg_hi:[1,0,0]
	v_pk_fma_f32 v[62:63], v[54:55], s[26:27], v[56:57] op_sel_hi:[1,0,1] neg_lo:[1,0,0] neg_hi:[1,0,0]
	s_waitcnt lgkmcnt(1)
	v_add_f32_e32 v17, v17, v19
	s_waitcnt lgkmcnt(0)
	v_add_f32_e32 v21, v21, v23
	ds_swizzle_b32 v19, v17 offset:swizzle(SWAP,8)
	ds_swizzle_b32 v23, v21 offset:swizzle(SWAP,4)
	v_pk_fma_f32 v[60:61], v[54:55], s[26:27], v[60:61] op_sel_hi:[1,0,1] neg_lo:[1,0,0] neg_hi:[1,0,0]
	s_waitcnt lgkmcnt(1)
	v_add_f32_e32 v17, v17, v19
	s_waitcnt lgkmcnt(0)
	v_add_f32_e32 v21, v21, v23
	ds_swizzle_b32 v19, v17 offset:swizzle(SWAP,16)
	ds_swizzle_b32 v23, v21 offset:swizzle(SWAP,8)
	s_waitcnt lgkmcnt(1)
	v_add_f32_e32 v17, v17, v19
	s_waitcnt lgkmcnt(0)
	v_add_f32_e32 v19, v21, v23
	v_mul_f32_e32 v23, v50, v50
	v_fmac_f32_e32 v23, v46, v46
	v_fmac_f32_e32 v23, v62, v62
	v_fmac_f32_e32 v23, v60, v60
	ds_swizzle_b32 v21, v19 offset:swizzle(SWAP,16)
	ds_swizzle_b32 v54, v23 offset:swizzle(SWAP,1)
	v_readlane_b32 s3, v17, 32
	v_readlane_b32 s2, v17, 0
	s_nop 0
	v_mov_b32_e32 v17, s3
	v_add_f32_e32 v17, s2, v17
	v_fmamk_f32 v17, v17, 0x3b800000, v183
	v_rsq_f32_e32 v70, v17
	s_waitcnt lgkmcnt(1)
	v_add_f32_e32 v17, v19, v21
	s_waitcnt lgkmcnt(0)
	v_add_f32_e32 v19, v23, v54
	v_mul_f32_e32 v23, v51, v51
	v_fmac_f32_e32 v23, v47, v47
	v_fmac_f32_e32 v23, v63, v63
	v_fmac_f32_e32 v23, v61, v61
	ds_swizzle_b32 v54, v23 offset:swizzle(SWAP,1)
	ds_swizzle_b32 v21, v19 offset:swizzle(SWAP,2)
	v_readlane_b32 s2, v17, 0
	v_readlane_b32 s3, v17, 32
	s_waitcnt lgkmcnt(1)
	v_add_f32_e32 v17, v23, v54
	s_waitcnt lgkmcnt(0)
	v_add_f32_e32 v19, v19, v21
	ds_swizzle_b32 v23, v17 offset:swizzle(SWAP,2)
	ds_swizzle_b32 v21, v19 offset:swizzle(SWAP,4)
	v_mov_b32_e32 v54, s3
	v_add_f32_e32 v54, s2, v54
	v_fmamk_f32 v54, v54, 0x3b800000, v183
	s_waitcnt lgkmcnt(1)
	v_add_f32_e32 v17, v17, v23
	s_waitcnt lgkmcnt(0)
	v_add_f32_e32 v19, v19, v21
	ds_swizzle_b32 v23, v17 offset:swizzle(SWAP,4)
	ds_swizzle_b32 v21, v19 offset:swizzle(SWAP,8)
	v_rsq_f32_e32 v71, v54
	s_waitcnt lgkmcnt(1)
	v_add_f32_e32 v17, v17, v23
	s_waitcnt lgkmcnt(0)
; __device__ __forceinline__ float bf2f(u16 h) { return __uint_as_float(((unsigned)h) << 16); }
; __device__ __forceinline__ float gelu_(float x) { float u = 0.7978845608028654f * (x + 0.044715f * x * x * x); return x * rcp_(1.f + __expf(-2.f * u)); }
; __device__ __forceinline__ float rsq_(float x) { return __builtin_amdgcn_rsqf(x); }
; __device__ __forceinline__ void sgu_chunk(const Params& p, int l, int b, int c) {
;     ...
;       for (int e = 0; e < 4; ++e) { v[e] = gelu_(bf2f(rv[i][e])); s += v[e]; }
;       const float mean = wave_sum(s) * (1.f / 256.f);
;       float q = 0.f;
; #pragma unroll
;       for (int e = 0; e < 4; ++e) { v[e] -= mean; q += v[e] * v[e]; }
;       const float rs = rsq_(wave_sum(q) * (1.f / 256.f) + EPS);
; #pragma unroll
;       for (int e = 0; e < 4; ++e) vT[(lane + 64 * e) * LROW + t] = f2bf(v[e] * rs * lg[e] + lb[e]);
	v_add_f32_e32 v19, v19, v21
	ds_swizzle_b32 v23, v17 offset:swizzle(SWAP,8)
	ds_swizzle_b32 v21, v19 offset:swizzle(SWAP,16)
	v_pk_mul_f32 v[48:49], v[48:49], v[70:71]
	v_pk_mul_f32 v[58:59], v[58:59], v[70:71]
	s_waitcnt lgkmcnt(1)
	v_add_f32_e32 v17, v17, v23
	s_waitcnt lgkmcnt(0)
	v_add_f32_e32 v19, v19, v21
	ds_swizzle_b32 v21, v17 offset:swizzle(SWAP,16)
	v_readlane_b32 s3, v19, 32
	v_readlane_b32 s2, v19, 0
	flat_load_ushort v19, v[44:45] offset:128
	v_mov_b32_e32 v23, s3
	s_waitcnt lgkmcnt(0)
	v_add_f32_e32 v17, v17, v21
	v_add_f32_e32 v23, s2, v23
	v_readlane_b32 s2, v17, 0
	v_readlane_b32 s3, v17, 32
	flat_load_ushort v17, v[42:43] offset:128
	v_fmamk_f32 v23, v23, 0x3b800000, v183
	v_mov_b32_e32 v21, s3
	v_add_f32_e32 v21, s2, v21
	v_fmamk_f32 v21, v21, 0x3b800000, v183
	v_rsq_f32_e32 v72, v23
	v_rsq_f32_e32 v73, v21
	v_pk_fma_f32 v[56:57], v[20:21], v[48:49], v[22:23] op_sel_hi:[0,1,0]
	v_pk_mul_f32 v[48:49], v[50:51], v[72:73]
	v_pk_mul_f32 v[46:47], v[46:47], v[72:73]
	v_pk_mul_f32 v[60:61], v[60:61], v[72:73]
	v_pk_fma_f32 v[54:55], v[20:21], v[46:47], v[22:23] op_sel_hi:[0,1,0]
	v_pk_mul_f32 v[46:47], v[52:53], v[70:71]
	s_waitcnt vmcnt(0) lgkmcnt(0)
	v_pk_fma_f32 v[50:51], v[16:17], v[48:49], v[18:19] op_sel_hi:[0,1,0]
	v_pk_mul_f32 v[48:49], v[64:65], v[70:71]
	v_lshlrev_b32_e32 v64, 16, v80
	v_mul_f32_e32 v21, 0x3d372713, v64
	v_mul_f32_e32 v21, v21, v64
	v_fma_f32 v21, v21, v64, v64
	v_mul_f32_e32 v21, 0x3f4c422a, v21
	v_mul_f32_e32 v21, -2.0, v21
	flat_load_ushort v78, v[44:45] offset:256
	flat_load_ushort v79, v[42:43] offset:256
	flat_load_ushort v80, v[40:41] offset:256
	v_mul_f32_e32 v21, 0x3fb8aa3b, v21
	v_exp_f32_e32 v21, v21
	v_pk_fma_f32 v[52:53], v[16:17], v[46:47], v[18:19] op_sel_hi:[0,1,0]
	v_pk_mul_f32 v[46:47], v[62:63], v[72:73]
	v_lshlrev_b32_e32 v62, 16, v82
	v_lshlrev_b32_e32 v63, 16, v83
	v_lshlrev_b32_e32 v65, 16, v81
	v_add_f32_e32 v21, 1.0, v21
	v_mul_f32_e32 v23, 0x3d372713, v62
	v_rcp_f32_e32 v74, v21
	v_mul_f32_e32 v21, 0x3d372713, v65
	v_mul_f32_e32 v23, v23, v62
	v_mul_f32_e32 v75, 0x3d372713, v63
	v_mul_f32_e32 v21, v21, v65
	v_fma_f32 v23, v23, v62, v62
	v_mul_f32_e32 v75, v75, v63
	v_fma_f32 v21, v21, v65, v65
	v_mul_f32_e32 v23, 0x3f4c422a, v23
	v_fma_f32 v75, v75, v63, v63
	v_mul_f32_e32 v21, 0x3f4c422a, v21
	v_mul_f32_e32 v23, -2.0, v23
	v_mul_f32_e32 v75, 0x3f4c422a, v75
	v_mul_f32_e32 v21, -2.0, v21
	v_mul_f32_e32 v23, 0x3fb8aa3b, v23
	v_mul_f32_e32 v75, -2.0, v75
	v_mul_f32_e32 v21, 0x3fb8aa3b, v21
	v_exp_f32_e32 v23, v23
	v_mul_f32_e32 v75, 0x3fb8aa3b, v75
	v_exp_f32_e32 v21, v21
	v_exp_f32_e32 v75, v75
	v_add_f32_e32 v23, 1.0, v23
	v_rcp_f32_e32 v76, v23
	v_add_f32_e32 v21, 1.0, v21
	v_add_f32_e32 v23, 1.0, v75
	v_rcp_f32_e32 v77, v23
	v_rcp_f32_e32 v75, v21
	v_pk_fma_f32 v[82:83], v[8:9], v[60:61], v[10:11] op_sel_hi:[0,1,0]
	v_pk_fma_f32 v[46:47], v[12:13], v[46:47], v[14:15] op_sel_hi:[0,1,0]
	v_pk_mul_f32 v[62:63], v[76:77], v[62:63]
	v_pk_mul_f32 v[64:65], v[74:75], v[64:65]
	flat_load_ushort v74, v[44:45] offset:384
	flat_load_ushort v75, v[42:43] offset:384
	flat_load_ushort v76, v[40:41] offset:384
	v_lshlrev_b32_e32 v44, 16, v67
	v_lshlrev_b32_e32 v43, 16, v19
	v_mul_f32_e32 v19, 0x3d372713, v44
	v_mul_f32_e32 v19, v19, v44
	v_fma_f32 v19, v19, v44, v44
	v_mul_f32_e32 v19, 0x3f4c422a, v19
	v_mul_f32_e32 v19, -2.0, v19
	v_mul_f32_e32 v19, 0x3fb8aa3b, v19
	v_exp_f32_e32 v19, v19
	v_lshlrev_b32_e32 v42, 16, v17
	v_lshlrev_b32_e32 v45, 16, v66
	v_mul_f32_e32 v40, 0x3d372713, v43
	v_add_f32_e32 v17, 1.0, v19
	v_mul_f32_e32 v19, 0x3d372713, v42
	v_rcp_f32_e32 v66, v17
	v_mul_f32_e32 v17, 0x3d372713, v45
	v_mul_f32_e32 v19, v19, v42
	v_mul_f32_e32 v17, v17, v45
	v_fma_f32 v19, v19, v42, v42
	v_mul_f32_e32 v40, v40, v43
	v_fma_f32 v17, v17, v45, v45
	v_mul_f32_e32 v19, 0x3f4c422a, v19
	v_fma_f32 v40, v40, v43, v43
	v_mul_f32_e32 v17, 0x3f4c422a, v17
	v_mul_f32_e32 v19, -2.0, v19
	v_mul_f32_e32 v40, 0x3f4c422a, v40
	v_mul_f32_e32 v17, -2.0, v17
	v_mul_f32_e32 v19, 0x3fb8aa3b, v19
	v_mul_f32_e32 v40, -2.0, v40
	v_mul_f32_e32 v17, 0x3fb8aa3b, v17
	v_exp_f32_e32 v19, v19
	v_mul_f32_e32 v40, 0x3fb8aa3b, v40
	v_exp_f32_e32 v17, v17
	v_exp_f32_e32 v41, v40
	v_add_f32_e32 v19, 1.0, v19
	v_rcp_f32_e32 v40, v19
	v_add_f32_e32 v17, 1.0, v17
	v_add_f32_e32 v19, 1.0, v41
	v_rcp_f32_e32 v41, v19
	v_rcp_f32_e32 v67, v17
	v_add_f32_e32 v21, 0, v64
	v_add_f32_e32 v23, 0, v65
	v_pk_mul_f32 v[40:41], v[40:41], v[42:43]
	v_pk_mul_f32 v[42:43], v[66:67], v[44:45]
	v_lshlrev_b32_e32 v44, 16, v68
	v_mul_f32_e32 v45, 0x3d372713, v44
	v_mul_f32_e32 v45, v45, v44
	v_fma_f32 v45, v45, v44, v44
	v_mul_f32_e32 v45, 0x3f4c422a, v45
	v_mul_f32_e32 v45, -2.0, v45
	v_mul_f32_e32 v45, 0x3fb8aa3b, v45
	v_exp_f32_e32 v68, v45
	s_waitcnt vmcnt(0) lgkmcnt(0)
; __device__ __forceinline__ float bf2f(u16 h) { return __uint_as_float(((unsigned)h) << 16); }
; __device__ __forceinline__ float gelu_(float x) { float u = 0.7978845608028654f * (x + 0.044715f * x * x * x); return x * rcp_(1.f + __expf(-2.f * u)); }
; __device__ __forceinline__ float rsq_(float x) { return __builtin_amdgcn_rsqf(x); }
; __device__ __forceinline__ void sgu_chunk(const Params& p, int l, int b, int c) {
;     ...
;     for (int i = 0; i < 16; ++i) {
;       const int t = wid * 16 + i;
;       float v[4], s = 0.f;
; #pragma unroll
;       for (int e = 0; e < 4; ++e) { v[e] = gelu_(bf2f(rv[i][e])); s += v[e]; }
;       const float mean = wave_sum(s) * (1.f / 256.f);
;       float q = 0.f;
; #pragma unroll
;       for (int e = 0; e < 4; ++e) { v[e] -= mean; q += v[e] * v[e]; }
;       const float rs = rsq_(wave_sum(q) * (1.f / 256.f) + EPS);
	v_lshlrev_b32_e32 v66, 16, v79
	v_lshlrev_b32_e32 v67, 16, v78
	v_lshlrev_b32_e32 v45, 16, v80
	v_add_f32_e32 v68, 1.0, v68
	v_mul_f32_e32 v71, 0x3d372713, v66
	v_rcp_f32_e32 v70, v68
	v_mul_f32_e32 v68, 0x3d372713, v45
	v_mul_f32_e32 v71, v71, v66
	v_mul_f32_e32 v72, 0x3d372713, v67
	v_mul_f32_e32 v68, v68, v45
	v_fma_f32 v71, v71, v66, v66
	v_mul_f32_e32 v72, v72, v67
	v_fma_f32 v68, v68, v45, v45
	v_mul_f32_e32 v71, 0x3f4c422a, v71
	v_fma_f32 v72, v72, v67, v67
	v_mul_f32_e32 v68, 0x3f4c422a, v68
	v_mul_f32_e32 v71, -2.0, v71
	v_mul_f32_e32 v72, 0x3f4c422a, v72
	v_mul_f32_e32 v68, -2.0, v68
	v_mul_f32_e32 v71, 0x3fb8aa3b, v71
	v_mul_f32_e32 v72, -2.0, v72
	v_mul_f32_e32 v68, 0x3fb8aa3b, v68
	v_exp_f32_e32 v71, v71
	v_mul_f32_e32 v72, 0x3fb8aa3b, v72
	v_exp_f32_e32 v68, v68
	v_exp_f32_e32 v73, v72
	v_add_f32_e32 v71, 1.0, v71
	v_rcp_f32_e32 v72, v71
	v_add_f32_e32 v68, 1.0, v68
	v_add_f32_e32 v71, 1.0, v73
	v_rcp_f32_e32 v73, v71
	v_rcp_f32_e32 v71, v68
	v_add_f32_e32 v21, v21, v42
	v_add_f32_e32 v23, v23, v43
	v_pk_mul_f32 v[66:67], v[72:73], v[66:67]
	v_pk_mul_f32 v[44:45], v[70:71], v[44:45]
	v_lshlrev_b32_e32 v70, 16, v69
	v_mul_f32_e32 v68, 0x3d372713, v70
	v_mul_f32_e32 v68, v68, v70
	v_fma_f32 v68, v68, v70, v70
	v_mul_f32_e32 v68, 0x3f4c422a, v68
	v_mul_f32_e32 v68, -2.0, v68
	v_lshlrev_b32_e32 v71, 16, v76
	v_mul_f32_e32 v68, 0x3fb8aa3b, v68
	v_exp_f32_e32 v69, v68
	v_mul_f32_e32 v68, 0x3d372713, v71
	v_mul_f32_e32 v68, v68, v71
	v_fma_f32 v68, v68, v71, v71
	v_mul_f32_e32 v68, 0x3f4c422a, v68
	v_mul_f32_e32 v68, -2.0, v68
	v_mul_f32_e32 v68, 0x3fb8aa3b, v68
	v_exp_f32_e32 v73, v68
	v_add_f32_e32 v69, 1.0, v69
	v_rcp_f32_e32 v72, v69
	v_add_f32_e32 v21, v21, v44
	v_add_f32_e32 v69, 1.0, v73
	v_rcp_f32_e32 v73, v69
	v_lshlrev_b32_e32 v68, 16, v75
	v_mul_f32_e32 v69, 0x3d372713, v68
	v_mul_f32_e32 v69, v69, v68
	v_pk_mul_f32 v[70:71], v[72:73], v[70:71]
	v_fma_f32 v69, v69, v68, v68
	v_add_f32_e32 v21, v21, v70
	ds_swizzle_b32 v73, v21 offset:swizzle(SWAP,1)
	v_mul_f32_e32 v69, 0x3f4c422a, v69
	v_mul_f32_e32 v69, -2.0, v69
	v_mul_f32_e32 v69, 0x3fb8aa3b, v69
	v_exp_f32_e32 v75, v69
	s_waitcnt lgkmcnt(0)
	v_add_f32_e32 v21, v21, v73
	ds_swizzle_b32 v73, v21 offset:swizzle(SWAP,2)
	v_add_f32_e32 v23, v23, v45
	v_lshlrev_b32_e32 v69, 16, v74
	v_add_f32_e32 v23, v23, v71
	v_add_f32_e32 v72, 1.0, v75
	s_waitcnt lgkmcnt(0)
	v_add_f32_e32 v21, v21, v73
	v_mul_f32_e32 v74, 0x3d372713, v69
	ds_swizzle_b32 v73, v21 offset:swizzle(SWAP,4)
	ds_swizzle_b32 v75, v23 offset:swizzle(SWAP,1)
	v_mul_f32_e32 v74, v74, v69
	v_fma_f32 v74, v74, v69, v69
	v_mul_f32_e32 v74, 0x3f4c422a, v74
	v_mul_f32_e32 v74, -2.0, v74
	v_mul_f32_e32 v74, 0x3fb8aa3b, v74
	s_waitcnt lgkmcnt(1)
	v_add_f32_e32 v21, v21, v73
	s_waitcnt lgkmcnt(0)
	v_add_f32_e32 v23, v23, v75
	v_exp_f32_e32 v74, v74
	ds_swizzle_b32 v76, v21 offset:swizzle(SWAP,8)
	ds_swizzle_b32 v75, v23 offset:swizzle(SWAP,2)
	v_rcp_f32_e32 v72, v72
	v_add_f32_e32 v73, 1.0, v74
	v_rcp_f32_e32 v73, v73
	s_waitcnt lgkmcnt(1)
	v_add_f32_e32 v21, v21, v76
	s_waitcnt lgkmcnt(0)
	v_add_f32_e32 v23, v23, v75
	ds_swizzle_b32 v74, v21 offset:swizzle(SWAP,16)
	ds_swizzle_b32 v75, v23 offset:swizzle(SWAP,4)
	v_add_f32_e32 v19, 0, v63
	v_add_f32_e32 v19, v19, v41
	v_add_f32_e32 v19, v19, v67
	v_pk_mul_f32 v[68:69], v[72:73], v[68:69]
	s_waitcnt lgkmcnt(1)
	v_add_f32_e32 v21, v21, v74
	v_add_f32_e32 v19, v19, v69
	s_waitcnt lgkmcnt(0)
	v_add_f32_e32 v23, v23, v75
	ds_swizzle_b32 v74, v19 offset:swizzle(SWAP,1)
	v_add_f32_e32 v17, 0, v62
	ds_swizzle_b32 v72, v23 offset:swizzle(SWAP,8)
	v_add_f32_e32 v17, v17, v40
	v_add_f32_e32 v17, v17, v66
	v_add_f32_e32 v17, v17, v68
	ds_swizzle_b32 v73, v17 offset:swizzle(SWAP,1)
	s_waitcnt lgkmcnt(2)
	v_add_f32_e32 v19, v19, v74
	s_waitcnt lgkmcnt(1)
	v_add_f32_e32 v23, v23, v72
	ds_swizzle_b32 v74, v19 offset:swizzle(SWAP,2)
	ds_swizzle_b32 v72, v23 offset:swizzle(SWAP,16)
	s_waitcnt lgkmcnt(2)
	v_add_f32_e32 v17, v17, v73
	ds_swizzle_b32 v73, v17 offset:swizzle(SWAP,2)
	v_readlane_b32 s2, v21, 0
	s_waitcnt lgkmcnt(2)
	v_add_f32_e32 v19, v19, v74
	v_readlane_b32 s8, v21, 32
	s_waitcnt lgkmcnt(1)
	v_add_f32_e32 v21, v23, v72
	ds_swizzle_b32 v72, v19 offset:swizzle(SWAP,4)
	s_waitcnt lgkmcnt(1)
	v_add_f32_e32 v17, v17, v73
	v_readlane_b32 s10, v21, 32
	ds_swizzle_b32 v23, v17 offset:swizzle(SWAP,4)
	v_readlane_b32 s3, v21, 0
	s_waitcnt lgkmcnt(1)
	v_add_f32_e32 v19, v19, v72
	v_mov_b32_e32 v72, s8
	v_mov_b32_e32 v73, s10
	v_pk_add_f32 v[72:73], s[2:3], v[72:73]
	s_waitcnt lgkmcnt(0)
	v_add_f32_e32 v17, v17, v23
	v_pk_fma_f32 v[74:75], v[72:73], s[26:27], v[64:65] op_sel_hi:[1,0,1] neg_lo:[1,0,0] neg_hi:[1,0,0]
	v_pk_fma_f32 v[64:65], v[72:73], s[26:27], v[42:43] op_sel_hi:[1,0,1] neg_lo:[1,0,0] neg_hi:[1,0,0]
	v_pk_fma_f32 v[44:45], v[72:73], s[26:27], v[44:45] op_sel_hi:[1,0,1] neg_lo:[1,0,0] neg_hi:[1,0,0]
	v_mul_f32_e32 v76, v64, v64
	v_fmac_f32_e32 v76, v74, v74
	v_fmac_f32_e32 v76, v44, v44
	v_pk_fma_f32 v[42:43], v[72:73], s[26:27], v[70:71] op_sel_hi:[1,0,1] neg_lo:[1,0,0] neg_hi:[1,0,0]
	ds_swizzle_b32 v21, v17 offset:swizzle(SWAP,8)
	v_fmac_f32_e32 v76, v42, v42
	ds_swizzle_b32 v23, v19 offset:swizzle(SWAP,8)
	ds_swizzle_b32 v70, v76 offset:swizzle(SWAP,1)
	v_pk_fma_f32 v[48:49], v[12:13], v[48:49], v[14:15] op_sel_hi:[0,1,0]
	s_waitcnt lgkmcnt(2)
	v_add_f32_e32 v17, v17, v21
	ds_swizzle_b32 v21, v17 offset:swizzle(SWAP,16)
	s_waitcnt lgkmcnt(2)
	v_add_f32_e32 v19, v19, v23
	s_waitcnt lgkmcnt(1)
	v_add_f32_e32 v70, v76, v70
	ds_swizzle_b32 v23, v19 offset:swizzle(SWAP,16)
	ds_swizzle_b32 v71, v70 offset:swizzle(SWAP,2)
	s_waitcnt lgkmcnt(2)
; __device__ __forceinline__ float bf2f(u16 h) { return __uint_as_float(((unsigned)h) << 16); }
; __device__ __forceinline__ float gelu_(float x) { float u = 0.7978845608028654f * (x + 0.044715f * x * x * x); return x * rcp_(1.f + __expf(-2.f * u)); }
; __device__ __forceinline__ float rsq_(float x) { return __builtin_amdgcn_rsqf(x); }
; __device__ __forceinline__ void sgu_chunk(const Params& p, int l, int b, int c) {
;     ...
;       for (int e = 0; e < 4; ++e) rv[i][e] = proj[(rowbase + wid * 16 + i) * PS + PC_V + lane + 64 * e];
; #pragma unroll
;     for (int i = 0; i < 16; ++i) {
;       const int t = wid * 16 + i;
;       float v[4], s = 0.f;
; #pragma unroll
;       for (int e = 0; e < 4; ++e) { v[e] = gelu_(bf2f(rv[i][e])); s += v[e]; }
;       const float mean = wave_sum(s) * (1.f / 256.f);
;       float q = 0.f;
; #pragma unroll
;       for (int e = 0; e < 4; ++e) { v[e] -= mean; q += v[e] * v[e]; }
;       const float rs = rsq_(wave_sum(q) * (1.f / 256.f) + EPS);
; #pragma unroll
;       for (int e = 0; e < 4; ++e) vT[(lane + 64 * e) * LROW + t] = f2bf(v[e] * rs * lg[e] + lb[e]);
	v_add_f32_e32 v17, v17, v21
	s_nop 0
	v_readlane_b32 s2, v17, 0
	v_readlane_b32 s8, v17, 32
	s_waitcnt lgkmcnt(1)
	v_add_f32_e32 v17, v19, v23
	s_waitcnt lgkmcnt(0)
	v_add_f32_e32 v19, v70, v71
	ds_swizzle_b32 v21, v19 offset:swizzle(SWAP,4)
	v_readlane_b32 s3, v17, 0
	v_readlane_b32 s10, v17, 32
	v_mov_b32_e32 v70, s8
	s_waitcnt lgkmcnt(0)
	v_add_f32_e32 v17, v19, v21
	v_mul_f32_e32 v21, v65, v65
	v_fmac_f32_e32 v21, v75, v75
	v_fmac_f32_e32 v21, v45, v45
	v_fmac_f32_e32 v21, v43, v43
	ds_swizzle_b32 v19, v17 offset:swizzle(SWAP,8)
	ds_swizzle_b32 v23, v21 offset:swizzle(SWAP,1)
	v_mov_b32_e32 v71, s10
	v_pk_add_f32 v[70:71], s[2:3], v[70:71]
	s_waitcnt lgkmcnt(1)
	v_add_f32_e32 v17, v17, v19
	s_waitcnt lgkmcnt(0)
	v_add_f32_e32 v21, v21, v23
	ds_swizzle_b32 v19, v17 offset:swizzle(SWAP,16)
	ds_swizzle_b32 v23, v21 offset:swizzle(SWAP,2)
	v_pk_fma_f32 v[72:73], v[70:71], s[26:27], v[40:41] op_sel_hi:[1,0,1] neg_lo:[1,0,0] neg_hi:[1,0,0]
	v_pk_fma_f32 v[62:63], v[70:71], s[26:27], v[62:63] op_sel_hi:[1,0,1] neg_lo:[1,0,0] neg_hi:[1,0,0]
	v_pk_fma_f32 v[76:77], v[70:71], s[26:27], v[66:67] op_sel_hi:[1,0,1] neg_lo:[1,0,0] neg_hi:[1,0,0]
	s_waitcnt lgkmcnt(1)
	v_add_f32_e32 v17, v17, v19
	s_waitcnt lgkmcnt(0)
	v_add_f32_e32 v19, v21, v23
	ds_swizzle_b32 v21, v19 offset:swizzle(SWAP,4)
	v_mul_f32_e32 v23, v72, v72
	v_fmac_f32_e32 v23, v62, v62
	v_pk_fma_f32 v[70:71], v[70:71], s[26:27], v[68:69] op_sel_hi:[1,0,1] neg_lo:[1,0,0] neg_hi:[1,0,0]
	v_fmac_f32_e32 v23, v76, v76
	s_waitcnt lgkmcnt(0)
	v_add_f32_e32 v19, v19, v21
	v_fmac_f32_e32 v23, v70, v70
	ds_swizzle_b32 v21, v19 offset:swizzle(SWAP,8)
	ds_swizzle_b32 v40, v23 offset:swizzle(SWAP,1)
	v_readlane_b32 s3, v17, 32
	v_readlane_b32 s2, v17, 0
	s_nop 0
	v_mov_b32_e32 v17, s3
	v_add_f32_e32 v17, s2, v17
	v_fmamk_f32 v17, v17, 0x3b800000, v183
	v_rsq_f32_e32 v78, v17
	s_waitcnt lgkmcnt(1)
	v_add_f32_e32 v17, v19, v21
	s_waitcnt lgkmcnt(0)
	v_add_f32_e32 v21, v23, v40
	v_mul_f32_e32 v40, v73, v73
	v_fmac_f32_e32 v40, v63, v63
	v_fmac_f32_e32 v40, v77, v77
	ds_swizzle_b32 v19, v17 offset:swizzle(SWAP,16)
	ds_swizzle_b32 v23, v21 offset:swizzle(SWAP,2)
	v_fmac_f32_e32 v40, v71, v71
	ds_swizzle_b32 v41, v40 offset:swizzle(SWAP,1)
	s_waitcnt lgkmcnt(2)
	v_add_f32_e32 v17, v17, v19
	s_waitcnt lgkmcnt(1)
	v_add_f32_e32 v19, v21, v23
	ds_swizzle_b32 v21, v19 offset:swizzle(SWAP,4)
	s_waitcnt lgkmcnt(1)
	v_add_f32_e32 v23, v40, v41
	ds_swizzle_b32 v40, v23 offset:swizzle(SWAP,2)
	v_readlane_b32 s2, v17, 0
	v_readlane_b32 s3, v17, 32
	s_waitcnt lgkmcnt(1)
	v_add_f32_e32 v17, v19, v21
	ds_swizzle_b32 v19, v17 offset:swizzle(SWAP,8)
	s_waitcnt lgkmcnt(1)
	v_add_f32_e32 v23, v23, v40
	ds_swizzle_b32 v40, v23 offset:swizzle(SWAP,4)
	v_mov_b32_e32 v21, s3
	v_add_f32_e32 v21, s2, v21
	s_waitcnt lgkmcnt(1)
	v_add_f32_e32 v17, v17, v19
	ds_swizzle_b32 v19, v17 offset:swizzle(SWAP,16)
	s_waitcnt lgkmcnt(1)
	v_add_f32_e32 v23, v23, v40
	ds_swizzle_b32 v40, v23 offset:swizzle(SWAP,8)
	v_fmamk_f32 v21, v21, 0x3b800000, v183
	v_rsq_f32_e32 v79, v21
	s_waitcnt lgkmcnt(1)
	v_add_f32_e32 v17, v17, v19
	s_nop 0
	v_readlane_b32 s2, v17, 0
	v_readlane_b32 s3, v17, 32
	s_waitcnt lgkmcnt(0)
	v_add_f32_e32 v17, v23, v40
	ds_swizzle_b32 v19, v17 offset:swizzle(SWAP,16)
	v_mov_b32_e32 v21, s3
	v_add_f32_e32 v21, s2, v21
	v_fmamk_f32 v21, v21, 0x3b800000, v183
	v_rsq_f32_e32 v80, v21
	s_waitcnt lgkmcnt(0)
	v_add_f32_e32 v17, v17, v19
	v_pk_fma_f32 v[40:41], v[8:9], v[58:59], v[10:11] op_sel_hi:[0,1,0]
	v_readlane_b32 s3, v17, 32
	v_readlane_b32 s2, v17, 0
	v_pk_mul_f32 v[58:59], v[74:75], v[78:79]
	v_mov_b32_e32 v17, s3
	v_add_f32_e32 v17, s2, v17
	v_fmamk_f32 v17, v17, 0x3b800000, v183
	v_rsq_f32_e32 v81, v17
	s_mov_b32 s2, 0xc000
	v_pk_fma_f32 v[58:59], v[20:21], v[58:59], v[22:23] op_sel_hi:[0,1,0]
	v_cvt_pk_bf16_f32 v68, v58, v59
	v_pk_mul_f32 v[60:61], v[62:63], v[80:81]
	s_nop 0
	v_pk_fma_f32 v[60:61], v[20:21], v[60:61], v[22:23] op_sel_hi:[0,1,0]
	v_cvt_pk_bf16_f32 v69, v60, v61
	v_add_co_u32_e32 v60, vcc, s2, v0
	s_mov_b32 s2, 0xd000
	s_nop 0
	v_addc_co_u32_e32 v61, vcc, 0, v1, vcc
	flat_load_ushort v74, v[60:61] offset:512
	v_add_co_u32_e32 v60, vcc, s2, v0
	s_mov_b32 s2, 0xe000
	s_nop 0
	v_addc_co_u32_e32 v61, vcc, 0, v1, vcc
	v_add_co_u32_e32 v62, vcc, s2, v0
	s_mov_b32 s2, 0x10000
	s_nop 0
	v_addc_co_u32_e32 v63, vcc, 0, v1, vcc
	v_add_co_u32_e32 v66, vcc, s2, v0
	s_mov_b32 s2, 0x11000
	s_nop 0
	v_addc_co_u32_e32 v67, vcc, 0, v1, vcc
	flat_load_ushort v75, v[60:61] offset:2048
	s_nop 0
	flat_load_ushort v62, v[62:63] offset:3584
	s_nop 0
	flat_load_ushort v63, v[66:67] offset:1024
	v_cvt_pk_bf16_f32 v67, v54, v55
	flat_load_ushort v84, v[30:31] offset:128
	flat_load_ushort v85, v[34:35] offset:128
	flat_load_ushort v86, v[2:3] offset:128
	flat_load_ushort v87, v[30:31] offset:256
	flat_load_ushort v88, v[34:35] offset:256
	flat_load_ushort v89, v[2:3] offset:256
	flat_load_ushort v90, v[34:35] offset:384
	flat_load_ushort v91, v[30:31] offset:384
	flat_load_ushort v92, v[36:37] offset:128
	flat_load_ushort v93, v[36:37] offset:256
	flat_load_ushort v94, v[36:37] offset:384
	flat_load_ushort v59, v[38:39] offset:128
	flat_load_ushort v58, v[24:25] offset:128
	flat_load_ushort v54, v[38:39] offset:256
	flat_load_ushort v19, v[38:39] offset:384
	flat_load_ushort v95, v[2:3] offset:384
	v_add_co_u32_e32 v2, vcc, s2, v0
	s_mov_b32 s2, 0x13000
	s_nop 0
	v_addc_co_u32_e32 v3, vcc, 0, v1, vcc
	v_add_co_u32_e32 v30, vcc, s2, v0
	s_mov_b32 s2, 0x14000
	s_nop 0
	v_addc_co_u32_e32 v31, vcc, 0, v1, vcc
	v_add_co_u32_e32 v38, vcc, s2, v0
	s_mov_b32 s2, 0x15000
	s_nop 0
	v_addc_co_u32_e32 v39, vcc, 0, v1, vcc
	v_add_co_u32_e32 v0, vcc, s2, v0
	v_cvt_pk_bf16_f32 v66, v56, v57
	s_nop 0
	v_addc_co_u32_e32 v1, vcc, 0, v1, vcc
	flat_load_ushort v37, v[2:3] offset:2560
	flat_load_ushort v34, v[30:31]
	flat_load_ushort v35, v[38:39] offset:1536
	flat_load_ushort v36, v[0:1] offset:3072
	flat_load_ushort v60, v[26:27] offset:128
	flat_load_ushort v61, v[28:29] offset:128
	flat_load_ushort v55, v[24:25] offset:256
	flat_load_ushort v56, v[26:27] offset:256
	flat_load_ushort v57, v[28:29] offset:256
	flat_load_ushort v17, v[28:29] offset:384
	flat_load_ushort v21, v[26:27] offset:384
	flat_load_ushort v23, v[24:25] offset:384
	v_pk_mul_f32 v[0:1], v[64:65], v[78:79]
	v_pk_mul_f32 v[2:3], v[72:73], v[80:81]
	ds_write_b128 v15, v[66:69]
	v_and_b32_e32 v67, 1, v9
	v_lshlrev_b32_e32 v73, 7, v13
	s_waitcnt vmcnt(0) lgkmcnt(0)
; __device__ __forceinline__ float bf2f(u16 h) { return __uint_as_float(((unsigned)h) << 16); }
; __device__ __forceinline__ float gelu_(float x) { float u = 0.7978845608028654f * (x + 0.044715f * x * x * x); return x * rcp_(1.f + __expf(-2.f * u)); }
; __device__ __forceinline__ float rsq_(float x) { return __builtin_amdgcn_rsqf(x); }
; __device__ __forceinline__ void sgu_chunk(const Params& p, int l, int b, int c) {
;     ...
;     for (int i = 0; i < 16; ++i) {
;       const int t = wid * 16 + i;
;       float v[4], s = 0.f;
; #pragma unroll
;       for (int e = 0; e < 4; ++e) { v[e] = gelu_(bf2f(rv[i][e])); s += v[e]; }
;       const float mean = wave_sum(s) * (1.f / 256.f);
;       float q = 0.f;
; #pragma unroll
;       for (int e = 0; e < 4; ++e) { v[e] -= mean; q += v[e] * v[e]; }
;       const float rs = rsq_(wave_sum(q) * (1.f / 256.f) + EPS);
; #pragma unroll
;       for (int e = 0; e < 4; ++e) vT[(lane + 64 * e) * LROW + t] = f2bf(v[e] * rs * lg[e] + lb[e]);
	v_lshlrev_b32_e32 v26, 16, v74
	v_lshlrev_b32_e32 v27, 16, v75
	v_lshlrev_b32_e32 v24, 16, v62
	v_lshlrev_b32_e32 v25, 16, v63
	v_mul_f32_e32 v29, 0x3d372713, v24
	v_mul_f32_e32 v29, v29, v24
	v_mul_f32_e32 v30, 0x3d372713, v25
	v_fma_f32 v29, v29, v24, v24
	v_mul_f32_e32 v30, v30, v25
	v_mul_f32_e32 v29, 0x3f4c422a, v29
	v_fma_f32 v30, v30, v25, v25
	v_mul_f32_e32 v29, -2.0, v29
	v_mul_f32_e32 v30, 0x3f4c422a, v30
	v_mul_f32_e32 v29, 0x3fb8aa3b, v29
	v_mul_f32_e32 v30, -2.0, v30
	v_exp_f32_e32 v29, v29
	v_mul_f32_e32 v30, 0x3fb8aa3b, v30
	v_exp_f32_e32 v31, v30
	v_add_f32_e32 v29, 1.0, v29
	v_rcp_f32_e32 v30, v29
	v_add_f32_e32 v29, 1.0, v31
	v_rcp_f32_e32 v31, v29
	v_pk_fma_f32 v[2:3], v[16:17], v[2:3], v[18:19] op_sel_hi:[0,1,0]
	v_pk_fma_f32 v[0:1], v[16:17], v[0:1], v[18:19] op_sel_hi:[0,1,0]
	v_cvt_pk_bf16_f32 v3, v2, v3
	v_cvt_pk_bf16_f32 v2, v0, v1
	v_cvt_pk_bf16_f32 v1, v50, v51
	v_cvt_pk_bf16_f32 v0, v52, v53
	ds_write_b128 v15, v[0:3] offset:17408
	v_pk_mul_f32 v[0:1], v[44:45], v[78:79]
	v_pk_mul_f32 v[2:3], v[76:77], v[80:81]
	v_pk_fma_f32 v[0:1], v[12:13], v[0:1], v[14:15] op_sel_hi:[0,1,0]
	v_pk_fma_f32 v[2:3], v[12:13], v[2:3], v[14:15] op_sel_hi:[0,1,0]
	v_cvt_pk_bf16_f32 v3, v2, v3
	v_cvt_pk_bf16_f32 v2, v0, v1
	v_cvt_pk_bf16_f32 v1, v46, v47
	v_cvt_pk_bf16_f32 v0, v48, v49
	ds_write_b128 v15, v[0:3] offset:34816
	v_pk_mul_f32 v[2:3], v[70:71], v[80:81]
	v_pk_mul_f32 v[24:25], v[30:31], v[24:25]
	v_pk_fma_f32 v[2:3], v[8:9], v[2:3], v[10:11] op_sel_hi:[0,1,0]
	v_cvt_pk_bf16_f32 v3, v2, v3
	v_mul_f32_e32 v2, 0x3d372713, v26
	v_mul_f32_e32 v2, v2, v26
	v_fma_f32 v2, v2, v26, v26
	v_mul_f32_e32 v2, 0x3f4c422a, v2
	v_mul_f32_e32 v2, -2.0, v2
	v_mul_f32_e32 v2, 0x3fb8aa3b, v2
	v_exp_f32_e32 v2, v2
	v_lshlrev_b32_e32 v30, 16, v84
	v_lshlrev_b32_e32 v31, 16, v85
	v_mul_f32_e32 v39, 0x3d372713, v31
	v_add_f32_e32 v2, 1.0, v2
	v_rcp_f32_e32 v28, v2
	v_mul_f32_e32 v2, 0x3d372713, v27
	v_mul_f32_e32 v2, v2, v27
	v_fma_f32 v2, v2, v27, v27
	v_mul_f32_e32 v2, 0x3f4c422a, v2
	v_mul_f32_e32 v2, -2.0, v2
	v_mul_f32_e32 v2, 0x3fb8aa3b, v2
	v_exp_f32_e32 v2, v2
	v_mul_f32_e32 v39, v39, v31
	v_fma_f32 v39, v39, v31, v31
	v_mul_f32_e32 v39, 0x3f4c422a, v39
	v_add_f32_e32 v2, 1.0, v2
	v_rcp_f32_e32 v29, v2
	v_mul_f32_e32 v39, -2.0, v39
	v_mul_f32_e32 v39, 0x3fb8aa3b, v39
	v_exp_f32_e32 v39, v39
	v_pk_mul_f32 v[26:27], v[28:29], v[26:27]
	v_mul_f32_e32 v28, 0x3d372713, v30
	v_mul_f32_e32 v28, v28, v30
	v_fma_f32 v28, v28, v30, v30
	v_mul_f32_e32 v28, 0x3f4c422a, v28
	v_mul_f32_e32 v28, -2.0, v28
	v_mul_f32_e32 v28, 0x3fb8aa3b, v28
	v_exp_f32_e32 v38, v28
	v_lshlrev_b32_e32 v29, 16, v92
	v_lshlrev_b32_e32 v28, 16, v86
	v_pk_mul_f32 v[0:1], v[42:43], v[78:79]
	v_mul_f32_e32 v42, 0x3d372713, v28
	v_mul_f32_e32 v43, 0x3d372713, v29
	v_mul_f32_e32 v42, v42, v28
	v_mul_f32_e32 v43, v43, v29
	v_add_f32_e32 v38, 1.0, v38
	v_fma_f32 v42, v42, v28, v28
	v_fma_f32 v43, v43, v29, v29
	v_add_f32_e32 v39, 1.0, v39
	v_rcp_f32_e32 v38, v38
	v_mul_f32_e32 v42, 0x3f4c422a, v42
	v_mul_f32_e32 v43, 0x3f4c422a, v43
	v_rcp_f32_e32 v39, v39
	v_mul_f32_e32 v42, -2.0, v42
	v_mul_f32_e32 v43, -2.0, v43
	v_mul_f32_e32 v42, 0x3fb8aa3b, v42
	v_mul_f32_e32 v43, 0x3fb8aa3b, v43
	v_exp_f32_e32 v42, v42
	v_exp_f32_e32 v43, v43
	v_pk_mul_f32 v[30:31], v[38:39], v[30:31]
	v_lshlrev_b32_e32 v38, 16, v87
	v_mul_f32_e32 v39, 0x3d372713, v38
	v_mul_f32_e32 v39, v39, v38
	v_add_f32_e32 v42, 1.0, v42
	v_add_f32_e32 v43, 1.0, v43
	v_fma_f32 v39, v39, v38, v38
	v_rcp_f32_e32 v42, v42
	v_rcp_f32_e32 v43, v43
	v_mul_f32_e32 v39, 0x3f4c422a, v39
	v_mul_f32_e32 v39, -2.0, v39
	v_add_f32_e32 v44, 0, v27
	v_mul_f32_e32 v39, 0x3fb8aa3b, v39
	v_add_f32_e32 v50, v44, v31
	v_exp_f32_e32 v44, v39
	v_lshlrev_b32_e32 v39, 16, v88
	v_pk_mul_f32 v[28:29], v[42:43], v[28:29]
	v_lshlrev_b32_e32 v43, 16, v93
	v_lshlrev_b32_e32 v42, 16, v89
	v_mul_f32_e32 v45, 0x3d372713, v39
	v_mul_f32_e32 v45, v45, v39
	v_mul_f32_e32 v46, 0x3d372713, v42
	v_mul_f32_e32 v47, 0x3d372713, v43
	v_fma_f32 v45, v45, v39, v39
	v_mul_f32_e32 v46, v46, v42
	v_mul_f32_e32 v47, v47, v43
	v_mul_f32_e32 v45, 0x3f4c422a, v45
	v_fma_f32 v46, v46, v42, v42
	v_fma_f32 v47, v47, v43, v43
	v_mul_f32_e32 v45, -2.0, v45
	v_mul_f32_e32 v46, 0x3f4c422a, v46
	v_mul_f32_e32 v47, 0x3f4c422a, v47
	v_mul_f32_e32 v45, 0x3fb8aa3b, v45
	v_mul_f32_e32 v46, -2.0, v46
	v_mul_f32_e32 v47, -2.0, v47
	v_exp_f32_e32 v45, v45
	v_mul_f32_e32 v46, 0x3fb8aa3b, v46
	v_mul_f32_e32 v47, 0x3fb8aa3b, v47
	v_exp_f32_e32 v46, v46
	v_exp_f32_e32 v47, v47
	v_add_f32_e32 v44, 1.0, v44
	v_add_f32_e32 v45, 1.0, v45
	v_rcp_f32_e32 v44, v44
	v_add_f32_e32 v46, 1.0, v46
	v_add_f32_e32 v47, 1.0, v47
	v_rcp_f32_e32 v45, v45
	v_rcp_f32_e32 v46, v46
	v_rcp_f32_e32 v47, v47
	v_add_f32_e32 v49, 0, v25
	v_pk_mul_f32 v[38:39], v[44:45], v[38:39]
	v_lshlrev_b32_e32 v44, 16, v91
	v_pk_mul_f32 v[42:43], v[46:47], v[42:43]
	v_mul_f32_e32 v46, 0x3d372713, v44
	v_mul_f32_e32 v46, v46, v44
	v_fma_f32 v46, v46, v44, v44
	v_mul_f32_e32 v46, 0x3f4c422a, v46
	v_mul_f32_e32 v46, -2.0, v46
	v_lshlrev_b32_e32 v45, 16, v90
	v_mul_f32_e32 v46, 0x3fb8aa3b, v46
	v_exp_f32_e32 v47, v46
	v_mul_f32_e32 v46, 0x3d372713, v45
	v_mul_f32_e32 v46, v46, v45
	v_fma_f32 v46, v46, v45, v45
	v_mul_f32_e32 v46, 0x3f4c422a, v46
	v_mul_f32_e32 v46, -2.0, v46
	v_mul_f32_e32 v46, 0x3fb8aa3b, v46
	v_add_f32_e32 v51, v49, v29
	v_exp_f32_e32 v49, v46
	v_add_f32_e32 v48, 0, v24
	v_add_f32_e32 v48, v48, v28
	v_add_f32_e32 v47, 1.0, v47
	v_add_f32_e32 v52, v48, v42
	v_rcp_f32_e32 v48, v47
	v_add_f32_e32 v47, 1.0, v49
	v_rcp_f32_e32 v49, v47
	v_pk_fma_f32 v[0:1], v[8:9], v[0:1], v[10:11] op_sel_hi:[0,1,0]
	v_cvt_pk_bf16_f32 v2, v0, v1
	v_add_f32_e32 v0, 0, v26
	v_add_f32_e32 v0, v0, v30
	v_add_f32_e32 v0, v0, v38
	v_pk_mul_f32 v[44:45], v[48:49], v[44:45]
	v_lshlrev_b32_e32 v46, 16, v95
	v_add_f32_e32 v0, v0, v44
	v_mul_f32_e32 v47, 0x3d372713, v46
	ds_swizzle_b32 v49, v0 offset:swizzle(SWAP,1)
	v_mul_f32_e32 v47, v47, v46
	v_fma_f32 v47, v47, v46, v46
	v_mul_f32_e32 v47, 0x3f4c422a, v47
	v_mul_f32_e32 v47, -2.0, v47
	v_mul_f32_e32 v47, 0x3fb8aa3b, v47
	s_waitcnt lgkmcnt(0)
; __device__ __forceinline__ float rsq_(float x) { return __builtin_amdgcn_rsqf(x); }
; __device__ __forceinline__ void sgu_chunk(const Params& p, int l, int b, int c) {
;     ...
;       const float mean = wave_sum(s) * (1.f / 256.f);
;       float q = 0.f;
; #pragma unroll
;       for (int e = 0; e < 4; ++e) { v[e] -= mean; q += v[e] * v[e]; }
;       const float rs = rsq_(wave_sum(q) * (1.f / 256.f) + EPS);
	v_add_f32_e32 v0, v0, v49
	v_exp_f32_e32 v53, v47
	ds_swizzle_b32 v49, v0 offset:swizzle(SWAP,2)
	v_add_f32_e32 v50, v50, v39
	v_add_f32_e32 v50, v50, v45
	v_lshlrev_b32_e32 v47, 16, v94
	ds_swizzle_b32 v62, v50 offset:swizzle(SWAP,1)
	v_add_f32_e32 v48, 1.0, v53
	v_mul_f32_e32 v53, 0x3d372713, v47
	v_mul_f32_e32 v53, v53, v47
	s_waitcnt lgkmcnt(1)
	v_add_f32_e32 v0, v0, v49
	v_fma_f32 v53, v53, v47, v47
	ds_swizzle_b32 v49, v0 offset:swizzle(SWAP,4)
	v_mul_f32_e32 v53, 0x3f4c422a, v53
	v_mul_f32_e32 v53, -2.0, v53
	s_waitcnt lgkmcnt(1)
	v_add_f32_e32 v50, v50, v62
	v_mul_f32_e32 v53, 0x3fb8aa3b, v53
	ds_swizzle_b32 v62, v50 offset:swizzle(SWAP,2)
	v_exp_f32_e32 v53, v53
	s_waitcnt lgkmcnt(1)
	v_add_f32_e32 v0, v0, v49
	ds_swizzle_b32 v63, v0 offset:swizzle(SWAP,8)
	v_rcp_f32_e32 v48, v48
	v_add_f32_e32 v49, 1.0, v53
	s_waitcnt lgkmcnt(1)
	v_add_f32_e32 v50, v50, v62
	v_rcp_f32_e32 v49, v49
	ds_swizzle_b32 v62, v50 offset:swizzle(SWAP,4)
	s_waitcnt lgkmcnt(1)
	v_add_f32_e32 v0, v0, v63
	ds_swizzle_b32 v53, v0 offset:swizzle(SWAP,16)
	v_pk_mul_f32 v[46:47], v[48:49], v[46:47]
	v_add_f32_e32 v51, v51, v43
	s_waitcnt lgkmcnt(1)
	v_add_f32_e32 v48, v50, v62
	v_add_f32_e32 v50, v52, v46
	ds_swizzle_b32 v49, v48 offset:swizzle(SWAP,8)
	ds_swizzle_b32 v52, v50 offset:swizzle(SWAP,1)
	v_add_f32_e32 v51, v51, v47
	s_waitcnt lgkmcnt(2)
	v_add_f32_e32 v0, v0, v53
	ds_swizzle_b32 v53, v51 offset:swizzle(SWAP,1)
	s_waitcnt lgkmcnt(2)
	v_add_f32_e32 v48, v48, v49
	s_waitcnt lgkmcnt(1)
	v_add_f32_e32 v50, v50, v52
	ds_swizzle_b32 v49, v48 offset:swizzle(SWAP,16)
	ds_swizzle_b32 v52, v50 offset:swizzle(SWAP,2)
	s_waitcnt lgkmcnt(2)
	v_add_f32_e32 v51, v51, v53
	ds_swizzle_b32 v53, v51 offset:swizzle(SWAP,2)
	v_readlane_b32 s2, v0, 0
	v_readlane_b32 s8, v0, 32
	s_waitcnt lgkmcnt(2)
	v_add_f32_e32 v0, v48, v49
	s_waitcnt lgkmcnt(1)
	v_add_f32_e32 v48, v50, v52
	ds_swizzle_b32 v49, v48 offset:swizzle(SWAP,4)
	s_waitcnt lgkmcnt(1)
	v_add_f32_e32 v50, v51, v53
	ds_swizzle_b32 v51, v50 offset:swizzle(SWAP,4)
	v_readlane_b32 s10, v0, 32
	v_readlane_b32 s3, v0, 0
	s_waitcnt lgkmcnt(1)
	v_add_f32_e32 v0, v48, v49
	v_mov_b32_e32 v48, s8
	v_mov_b32_e32 v49, s10
	v_pk_add_f32 v[48:49], s[2:3], v[48:49]
	s_waitcnt lgkmcnt(0)
	v_add_f32_e32 v53, v50, v51
	v_pk_fma_f32 v[50:51], v[48:49], s[26:27], v[30:31] op_sel_hi:[1,0,1] neg_lo:[1,0,0] neg_hi:[1,0,0]
	v_pk_fma_f32 v[26:27], v[48:49], s[26:27], v[26:27] op_sel_hi:[1,0,1] neg_lo:[1,0,0] neg_hi:[1,0,0]
	v_mul_f32_e32 v30, v50, v50
	v_fmac_f32_e32 v30, v26, v26
	v_pk_fma_f32 v[38:39], v[48:49], s[26:27], v[38:39] op_sel_hi:[1,0,1] neg_lo:[1,0,0] neg_hi:[1,0,0]
	v_pk_fma_f32 v[44:45], v[48:49], s[26:27], v[44:45] op_sel_hi:[1,0,1] neg_lo:[1,0,0] neg_hi:[1,0,0]
	v_fmac_f32_e32 v30, v38, v38
	v_fmac_f32_e32 v30, v44, v44
	ds_swizzle_b32 v52, v0 offset:swizzle(SWAP,8)
	ds_swizzle_b32 v31, v30 offset:swizzle(SWAP,1)
	ds_swizzle_b32 v62, v53 offset:swizzle(SWAP,8)
	v_cvt_pk_bf16_f32 v1, v82, v83
	v_mov_b32_e32 v71, s21
	s_waitcnt lgkmcnt(2)
	v_add_f32_e32 v0, v0, v52
	s_waitcnt lgkmcnt(1)
	v_add_f32_e32 v30, v30, v31
	ds_swizzle_b32 v48, v0 offset:swizzle(SWAP,16)
	s_waitcnt lgkmcnt(1)
	v_add_f32_e32 v49, v53, v62
	ds_swizzle_b32 v31, v30 offset:swizzle(SWAP,2)
	ds_swizzle_b32 v52, v49 offset:swizzle(SWAP,16)
	s_waitcnt lgkmcnt(2)
	v_add_f32_e32 v0, v0, v48
	s_nop 0
	v_readlane_b32 s2, v0, 0
	s_waitcnt lgkmcnt(1)
	v_add_f32_e32 v48, v30, v31
	v_readlane_b32 s8, v0, 32
	s_waitcnt lgkmcnt(0)
	v_add_f32_e32 v0, v49, v52
	ds_swizzle_b32 v49, v48 offset:swizzle(SWAP,4)
	v_readlane_b32 s3, v0, 0
	v_readlane_b32 s10, v0, 32
	v_mov_b32_e32 v30, s8
	s_waitcnt lgkmcnt(0)
	v_add_f32_e32 v0, v48, v49
	v_mul_f32_e32 v49, v51, v51
	v_fmac_f32_e32 v49, v27, v27
	v_fmac_f32_e32 v49, v39, v39
	v_fmac_f32_e32 v49, v45, v45
	ds_swizzle_b32 v52, v49 offset:swizzle(SWAP,1)
	ds_swizzle_b32 v48, v0 offset:swizzle(SWAP,8)
	v_mov_b32_e32 v31, s10
	v_pk_add_f32 v[30:31], s[2:3], v[30:31]
	s_waitcnt lgkmcnt(1)
	v_add_f32_e32 v52, v49, v52
	ds_swizzle_b32 v62, v52 offset:swizzle(SWAP,2)
	s_waitcnt lgkmcnt(1)
	v_add_f32_e32 v0, v0, v48
	v_pk_fma_f32 v[48:49], v[30:31], s[26:27], v[28:29] op_sel_hi:[1,0,1] neg_lo:[1,0,0] neg_hi:[1,0,0]
	ds_swizzle_b32 v53, v0 offset:swizzle(SWAP,16)
	v_pk_fma_f32 v[24:25], v[30:31], s[26:27], v[24:25] op_sel_hi:[1,0,1] neg_lo:[1,0,0] neg_hi:[1,0,0]
	s_waitcnt lgkmcnt(1)
	v_add_f32_e32 v28, v52, v62
	ds_swizzle_b32 v29, v28 offset:swizzle(SWAP,4)
	v_pk_fma_f32 v[42:43], v[30:31], s[26:27], v[42:43] op_sel_hi:[1,0,1] neg_lo:[1,0,0] neg_hi:[1,0,0]
	v_pk_fma_f32 v[46:47], v[30:31], s[26:27], v[46:47] op_sel_hi:[1,0,1] neg_lo:[1,0,0] neg_hi:[1,0,0]
	v_mul_f32_e32 v30, v48, v48
	v_fmac_f32_e32 v30, v24, v24
	v_fmac_f32_e32 v30, v42, v42
	s_waitcnt lgkmcnt(0)
	v_add_f32_e32 v28, v28, v29
	v_fmac_f32_e32 v30, v46, v46
	v_add_f32_e32 v0, v0, v53
	ds_swizzle_b32 v29, v28 offset:swizzle(SWAP,8)
	ds_swizzle_b32 v31, v30 offset:swizzle(SWAP,1)
	v_readlane_b32 s3, v0, 32
	v_readlane_b32 s2, v0, 0
	s_nop 0
	v_mov_b32_e32 v0, s3
	v_add_f32_e32 v0, s2, v0
	v_fmamk_f32 v0, v0, 0x3b800000, v183
	v_rsq_f32_e32 v52, v0
	s_waitcnt lgkmcnt(1)
	v_add_f32_e32 v0, v28, v29
	s_waitcnt lgkmcnt(0)
	v_add_f32_e32 v29, v30, v31
	v_mul_f32_e32 v31, v49, v49
	v_fmac_f32_e32 v31, v25, v25
	v_fmac_f32_e32 v31, v43, v43
	ds_swizzle_b32 v28, v0 offset:swizzle(SWAP,16)
	ds_swizzle_b32 v30, v29 offset:swizzle(SWAP,2)
	v_fmac_f32_e32 v31, v47, v47
	ds_swizzle_b32 v53, v31 offset:swizzle(SWAP,1)
	s_waitcnt lgkmcnt(2)
	v_add_f32_e32 v0, v0, v28
	s_waitcnt lgkmcnt(1)
	v_add_f32_e32 v28, v29, v30
	ds_swizzle_b32 v29, v28 offset:swizzle(SWAP,4)
	s_waitcnt lgkmcnt(1)
; __device__ __forceinline__ float bf2f(u16 h) { return __uint_as_float(((unsigned)h) << 16); }
; __device__ __forceinline__ float gelu_(float x) { float u = 0.7978845608028654f * (x + 0.044715f * x * x * x); return x * rcp_(1.f + __expf(-2.f * u)); }
; __device__ __forceinline__ float rsq_(float x) { return __builtin_amdgcn_rsqf(x); }
; __device__ __forceinline__ void sgu_chunk(const Params& p, int l, int b, int c) {
;     ...
;       for (int e = 0; e < 4; ++e) { v[e] = gelu_(bf2f(rv[i][e])); s += v[e]; }
;       const float mean = wave_sum(s) * (1.f / 256.f);
;       float q = 0.f;
; #pragma unroll
;       for (int e = 0; e < 4; ++e) { v[e] -= mean; q += v[e] * v[e]; }
;       const float rs = rsq_(wave_sum(q) * (1.f / 256.f) + EPS);
; #pragma unroll
;       for (int e = 0; e < 4; ++e) vT[(lane + 64 * e) * LROW + t] = f2bf(v[e] * rs * lg[e] + lb[e]);
	v_add_f32_e32 v30, v31, v53
	ds_swizzle_b32 v31, v30 offset:swizzle(SWAP,2)
	v_readlane_b32 s2, v0, 0
	v_readlane_b32 s3, v0, 32
	s_waitcnt lgkmcnt(1)
	v_add_f32_e32 v0, v28, v29
	ds_swizzle_b32 v28, v0 offset:swizzle(SWAP,8)
	s_waitcnt lgkmcnt(1)
	v_add_f32_e32 v30, v30, v31
	ds_swizzle_b32 v31, v30 offset:swizzle(SWAP,4)
	v_mov_b32_e32 v29, s3
	v_add_f32_e32 v29, s2, v29
	s_waitcnt lgkmcnt(1)
	v_add_f32_e32 v0, v0, v28
	ds_swizzle_b32 v28, v0 offset:swizzle(SWAP,16)
	s_waitcnt lgkmcnt(1)
	v_add_f32_e32 v30, v30, v31
	ds_swizzle_b32 v31, v30 offset:swizzle(SWAP,8)
	v_fmamk_f32 v29, v29, 0x3b800000, v183
	v_rsq_f32_e32 v53, v29
	s_waitcnt lgkmcnt(1)
	v_add_f32_e32 v0, v0, v28
	s_nop 0
	v_readlane_b32 s2, v0, 0
	v_readlane_b32 s3, v0, 32
	s_waitcnt lgkmcnt(0)
	v_add_f32_e32 v0, v30, v31
	ds_swizzle_b32 v28, v0 offset:swizzle(SWAP,16)
	v_mov_b32_e32 v29, s3
	v_add_f32_e32 v29, s2, v29
	v_fmamk_f32 v29, v29, 0x3b800000, v183
	v_rsq_f32_e32 v62, v29
	s_waitcnt lgkmcnt(0)
	v_add_f32_e32 v0, v0, v28
	s_nop 0
	v_readlane_b32 s3, v0, 32
	v_readlane_b32 s2, v0, 0
	s_nop 0
	v_mov_b32_e32 v0, s3
	v_add_f32_e32 v0, s2, v0
	v_fmamk_f32 v0, v0, 0x3b800000, v183
	v_rsq_f32_e32 v63, v0
	v_cvt_pk_bf16_f32 v0, v40, v41
	v_lshlrev_b32_e32 v40, 16, v37
	v_mul_f32_e32 v37, 0x3d372713, v40
	v_mul_f32_e32 v37, v37, v40
	v_fma_f32 v37, v37, v40, v40
	v_mul_f32_e32 v37, 0x3f4c422a, v37
	v_mul_f32_e32 v37, -2.0, v37
	v_mul_f32_e32 v37, 0x3fb8aa3b, v37
	v_exp_f32_e32 v37, v37
	ds_write_b128 v15, v[0:3] offset:52224
	v_pk_mul_f32 v[0:1], v[26:27], v[52:53]
	v_pk_mul_f32 v[2:3], v[24:25], v[62:63]
	v_pk_fma_f32 v[30:31], v[20:21], v[0:1], v[22:23] op_sel_hi:[0,1,0]
	v_pk_mul_f32 v[0:1], v[50:51], v[52:53]
	v_lshlrev_b32_e32 v41, 16, v34
	v_add_f32_e32 v34, 1.0, v37
	v_pk_fma_f32 v[28:29], v[20:21], v[2:3], v[22:23] op_sel_hi:[0,1,0]
	v_pk_mul_f32 v[2:3], v[48:49], v[62:63]
	v_pk_fma_f32 v[26:27], v[16:17], v[0:1], v[18:19] op_sel_hi:[0,1,0]
	v_pk_mul_f32 v[0:1], v[42:43], v[62:63]
	v_rcp_f32_e32 v42, v34
	v_mul_f32_e32 v34, 0x3d372713, v41
	v_pk_fma_f32 v[24:25], v[16:17], v[2:3], v[18:19] op_sel_hi:[0,1,0]
	v_pk_mul_f32 v[2:3], v[38:39], v[52:53]
	v_lshlrev_b32_e32 v38, 16, v35
	v_mul_f32_e32 v34, v34, v41
	v_lshlrev_b32_e32 v39, 16, v36
	v_fma_f32 v34, v34, v41, v41
	v_mul_f32_e32 v35, 0x3d372713, v38
	v_mul_f32_e32 v34, 0x3f4c422a, v34
	v_mul_f32_e32 v35, v35, v38
	v_mul_f32_e32 v36, 0x3d372713, v39
	v_mul_f32_e32 v34, -2.0, v34
	v_fma_f32 v35, v35, v38, v38
	v_mul_f32_e32 v36, v36, v39
	v_mul_f32_e32 v34, 0x3fb8aa3b, v34
	v_mul_f32_e32 v35, 0x3f4c422a, v35
	v_fma_f32 v36, v36, v39, v39
	v_exp_f32_e32 v34, v34
	v_mul_f32_e32 v35, -2.0, v35
	v_mul_f32_e32 v36, 0x3f4c422a, v36
	v_mul_f32_e32 v35, 0x3fb8aa3b, v35
	v_mul_f32_e32 v36, -2.0, v36
	v_exp_f32_e32 v35, v35
	v_mul_f32_e32 v36, 0x3fb8aa3b, v36
	v_exp_f32_e32 v36, v36
	v_add_f32_e32 v34, 1.0, v34
	v_rcp_f32_e32 v43, v34
	v_add_f32_e32 v35, 1.0, v35
	v_rcp_f32_e32 v48, v35
	v_add_f32_e32 v35, 1.0, v36
	v_rcp_f32_e32 v49, v35
	v_pk_mul_f32 v[34:35], v[44:45], v[52:53]
	v_lshlrev_b32_e32 v44, 16, v59
	v_lshlrev_b32_e32 v45, 16, v58
	v_pk_mul_f32 v[36:37], v[46:47], v[62:63]
	v_pk_mul_f32 v[40:41], v[42:43], v[40:41]
	v_mul_f32_e32 v42, 0x3d372713, v44
	v_mul_f32_e32 v47, 0x3d372713, v45
	v_mul_f32_e32 v42, v42, v44
	v_mul_f32_e32 v47, v47, v45
	v_fma_f32 v42, v42, v44, v44
	v_fma_f32 v47, v47, v45, v45
	v_mul_f32_e32 v42, 0x3f4c422a, v42
	v_mul_f32_e32 v47, 0x3f4c422a, v47
	v_mul_f32_e32 v42, -2.0, v42
	v_mul_f32_e32 v47, -2.0, v47
	v_mul_f32_e32 v42, 0x3fb8aa3b, v42
	v_mul_f32_e32 v47, 0x3fb8aa3b, v47
	v_exp_f32_e32 v46, v42
	v_exp_f32_e32 v47, v47
	v_lshlrev_b32_e32 v43, 16, v61
	v_lshlrev_b32_e32 v42, 16, v60
	v_add_f32_e32 v46, 1.0, v46
	v_add_f32_e32 v47, 1.0, v47
	v_rcp_f32_e32 v46, v46
	v_rcp_f32_e32 v47, v47
	v_pk_mul_f32 v[38:39], v[48:49], v[38:39]
	v_mul_f32_e32 v48, 0x3d372713, v42
	v_mul_f32_e32 v49, 0x3d372713, v43
	v_pk_mul_f32 v[44:45], v[46:47], v[44:45]
	v_lshlrev_b32_e32 v46, 16, v54
	v_mul_f32_e32 v47, 0x3d372713, v46
	v_mul_f32_e32 v47, v47, v46
	v_fma_f32 v47, v47, v46, v46
	v_mul_f32_e32 v48, v48, v42
	v_mul_f32_e32 v49, v49, v43
	v_mul_f32_e32 v47, 0x3f4c422a, v47
	v_fma_f32 v48, v48, v42, v42
	v_fma_f32 v49, v49, v43, v43
	v_mul_f32_e32 v47, -2.0, v47
	v_add_f32_e32 v50, 0, v40
	v_mul_f32_e32 v48, 0x3f4c422a, v48
	v_mul_f32_e32 v49, 0x3f4c422a, v49
	v_mul_f32_e32 v47, 0x3fb8aa3b, v47
	v_add_f32_e32 v51, 0, v41
	v_mul_f32_e32 v48, -2.0, v48
	v_mul_f32_e32 v49, -2.0, v49
	v_add_f32_e32 v60, v50, v44
	v_exp_f32_e32 v50, v47
	v_lshlrev_b32_e32 v47, 16, v55
	v_mul_f32_e32 v48, 0x3fb8aa3b, v48
	v_mul_f32_e32 v49, 0x3fb8aa3b, v49
	v_add_f32_e32 v61, v51, v45
	v_mul_f32_e32 v51, 0x3d372713, v47
	v_exp_f32_e32 v48, v48
	v_exp_f32_e32 v49, v49
	v_mul_f32_e32 v51, v51, v47
	v_fma_f32 v51, v51, v47, v47
	v_mul_f32_e32 v51, 0x3f4c422a, v51
	v_mul_f32_e32 v51, -2.0, v51
	v_add_f32_e32 v48, 1.0, v48
	v_add_f32_e32 v49, 1.0, v49
	v_mul_f32_e32 v51, 0x3fb8aa3b, v51
	v_rcp_f32_e32 v48, v48
	v_rcp_f32_e32 v49, v49
	v_exp_f32_e32 v51, v51
	v_add_f32_e32 v50, 1.0, v50
	v_rcp_f32_e32 v50, v50
	v_pk_mul_f32 v[42:43], v[48:49], v[42:43]
	v_lshlrev_b32_e32 v49, 16, v57
	v_lshlrev_b32_e32 v48, 16, v56
	v_add_f32_e32 v51, 1.0, v51
	v_mul_f32_e32 v52, 0x3d372713, v48
	v_mul_f32_e32 v53, 0x3d372713, v49
	v_rcp_f32_e32 v51, v51
	v_mul_f32_e32 v52, v52, v48
	v_mul_f32_e32 v53, v53, v49
	v_fma_f32 v52, v52, v48, v48
	v_fma_f32 v53, v53, v49, v49
	v_mul_f32_e32 v52, 0x3f4c422a, v52
	v_mul_f32_e32 v53, 0x3f4c422a, v53
	v_mul_f32_e32 v52, -2.0, v52
	v_mul_f32_e32 v53, -2.0, v53
	v_pk_mul_f32 v[46:47], v[50:51], v[46:47]
; __device__ __forceinline__ float bf2f(u16 h) { return __uint_as_float(((unsigned)h) << 16); }
; __device__ __forceinline__ float gelu_(float x) { float u = 0.7978845608028654f * (x + 0.044715f * x * x * x); return x * rcp_(1.f + __expf(-2.f * u)); }
; __device__ __forceinline__ float rsq_(float x) { return __builtin_amdgcn_rsqf(x); }
; __device__ __forceinline__ void sgu_chunk(const Params& p, int l, int b, int c) {
;     ...
;       for (int e = 0; e < 4; ++e) { v[e] = gelu_(bf2f(rv[i][e])); s += v[e]; }
;       const float mean = wave_sum(s) * (1.f / 256.f);
;       float q = 0.f;
; #pragma unroll
;       for (int e = 0; e < 4; ++e) { v[e] -= mean; q += v[e] * v[e]; }
;       const float rs = rsq_(wave_sum(q) * (1.f / 256.f) + EPS);
	v_lshlrev_b32_e32 v50, 16, v19
	v_mul_f32_e32 v52, 0x3fb8aa3b, v52
	v_mul_f32_e32 v53, 0x3fb8aa3b, v53
	v_lshlrev_b32_e32 v51, 16, v23
	v_mul_f32_e32 v19, 0x3d372713, v50
	v_exp_f32_e32 v52, v52
	v_exp_f32_e32 v53, v53
	v_mul_f32_e32 v19, v19, v50
	v_mul_f32_e32 v23, 0x3d372713, v51
	v_fma_f32 v19, v19, v50, v50
	v_mul_f32_e32 v23, v23, v51
	v_mul_f32_e32 v19, 0x3f4c422a, v19
	v_fma_f32 v23, v23, v51, v51
	v_mul_f32_e32 v19, -2.0, v19
	v_mul_f32_e32 v23, 0x3f4c422a, v23
	v_add_f32_e32 v52, 1.0, v52
	v_add_f32_e32 v53, 1.0, v53
	v_mul_f32_e32 v19, 0x3fb8aa3b, v19
	v_mul_f32_e32 v23, -2.0, v23
	v_rcp_f32_e32 v52, v52
	v_rcp_f32_e32 v53, v53
	v_exp_f32_e32 v19, v19
	v_mul_f32_e32 v23, 0x3fb8aa3b, v23
	v_exp_f32_e32 v23, v23
	v_add_f32_e32 v58, 0, v38
	v_add_f32_e32 v54, v58, v42
	v_pk_mul_f32 v[48:49], v[52:53], v[48:49]
	v_add_f32_e32 v19, 1.0, v19
	v_add_f32_e32 v58, v54, v48
	v_rcp_f32_e32 v54, v19
	v_add_f32_e32 v19, 1.0, v23
	v_lshlrev_b32_e32 v52, 16, v21
	v_rcp_f32_e32 v55, v19
	v_mul_f32_e32 v19, 0x3d372713, v52
	v_mul_f32_e32 v19, v19, v52
	v_fma_f32 v19, v19, v52, v52
	v_add_f32_e32 v53, v60, v46
	v_mul_f32_e32 v19, 0x3f4c422a, v19
	v_pk_mul_f32 v[50:51], v[54:55], v[50:51]
	v_mul_f32_e32 v19, -2.0, v19
	v_add_f32_e32 v21, v53, v50
	v_mul_f32_e32 v19, 0x3fb8aa3b, v19
	ds_swizzle_b32 v23, v21 offset:swizzle(SWAP,1)
	v_exp_f32_e32 v19, v19
	v_lshlrev_b32_e32 v53, 16, v17
	v_add_f32_e32 v57, v61, v47
	v_add_f32_e32 v59, 0, v39
	v_add_f32_e32 v17, 1.0, v19
	s_waitcnt lgkmcnt(0)
	v_add_f32_e32 v19, v21, v23
	ds_swizzle_b32 v21, v19 offset:swizzle(SWAP,2)
	v_add_f32_e32 v23, v57, v51
	v_rcp_f32_e32 v54, v17
	v_mul_f32_e32 v17, 0x3d372713, v53
	ds_swizzle_b32 v55, v23 offset:swizzle(SWAP,1)
	s_waitcnt lgkmcnt(1)
	v_add_f32_e32 v19, v19, v21
	ds_swizzle_b32 v21, v19 offset:swizzle(SWAP,4)
	v_mul_f32_e32 v17, v17, v53
	v_fma_f32 v17, v17, v53, v53
	v_mul_f32_e32 v17, 0x3f4c422a, v17
	v_mul_f32_e32 v17, -2.0, v17
	v_mul_f32_e32 v17, 0x3fb8aa3b, v17
	s_waitcnt lgkmcnt(0)
	v_add_f32_e32 v19, v19, v21
	v_add_f32_e32 v23, v23, v55
	v_exp_f32_e32 v17, v17
	ds_swizzle_b32 v21, v19 offset:swizzle(SWAP,8)
	ds_swizzle_b32 v57, v23 offset:swizzle(SWAP,2)
	v_add_f32_e32 v56, v59, v43
	v_add_f32_e32 v17, 1.0, v17
	v_rcp_f32_e32 v55, v17
	s_waitcnt lgkmcnt(1)
	v_add_f32_e32 v17, v19, v21
	s_waitcnt lgkmcnt(0)
	v_add_f32_e32 v21, v23, v57
	ds_swizzle_b32 v19, v17 offset:swizzle(SWAP,16)
	ds_swizzle_b32 v23, v21 offset:swizzle(SWAP,4)
	v_add_f32_e32 v56, v56, v49
	v_pk_mul_f32 v[52:53], v[54:55], v[52:53]
	v_pk_fma_f32 v[0:1], v[12:13], v[0:1], v[14:15] op_sel_hi:[0,1,0]
	s_waitcnt lgkmcnt(1)
	v_add_f32_e32 v17, v17, v19
	s_waitcnt lgkmcnt(0)
	v_add_f32_e32 v19, v21, v23
	v_add_f32_e32 v23, v58, v52
	v_add_f32_e32 v55, v56, v53
	ds_swizzle_b32 v21, v19 offset:swizzle(SWAP,8)
	ds_swizzle_b32 v54, v23 offset:swizzle(SWAP,1)
	ds_swizzle_b32 v56, v55 offset:swizzle(SWAP,1)
	v_readlane_b32 s2, v17, 0
	v_readlane_b32 s8, v17, 32
	s_waitcnt lgkmcnt(2)
	v_add_f32_e32 v19, v19, v21
	s_waitcnt lgkmcnt(1)
	v_add_f32_e32 v23, v23, v54
	s_waitcnt lgkmcnt(0)
	v_add_f32_e32 v55, v55, v56
	ds_swizzle_b32 v21, v19 offset:swizzle(SWAP,16)
	ds_swizzle_b32 v54, v23 offset:swizzle(SWAP,2)
	ds_swizzle_b32 v56, v55 offset:swizzle(SWAP,2)
	v_pk_fma_f32 v[2:3], v[12:13], v[2:3], v[14:15] op_sel_hi:[0,1,0]
	v_pk_fma_f32 v[36:37], v[8:9], v[36:37], v[10:11] op_sel_hi:[0,1,0]
	s_waitcnt lgkmcnt(2)
	v_add_f32_e32 v17, v19, v21
	s_waitcnt lgkmcnt(1)
	v_add_f32_e32 v19, v23, v54
	s_waitcnt lgkmcnt(0)
	v_add_f32_e32 v23, v55, v56
	ds_swizzle_b32 v21, v19 offset:swizzle(SWAP,4)
	ds_swizzle_b32 v54, v23 offset:swizzle(SWAP,4)
	v_readlane_b32 s10, v17, 32
	v_readlane_b32 s3, v17, 0
	v_pk_fma_f32 v[34:35], v[8:9], v[34:35], v[10:11] op_sel_hi:[0,1,0]
	s_waitcnt lgkmcnt(1)
	v_add_f32_e32 v17, v19, v21
	s_waitcnt lgkmcnt(0)
	v_add_f32_e32 v21, v23, v54
	v_mov_b32_e32 v54, s8
	v_mov_b32_e32 v55, s10
	v_pk_add_f32 v[54:55], s[2:3], v[54:55]
	ds_swizzle_b32 v19, v17 offset:swizzle(SWAP,8)
	v_pk_fma_f32 v[44:45], v[54:55], s[26:27], v[44:45] op_sel_hi:[1,0,1] neg_lo:[1,0,0] neg_hi:[1,0,0]
	v_pk_fma_f32 v[40:41], v[54:55], s[26:27], v[40:41] op_sel_hi:[1,0,1] neg_lo:[1,0,0] neg_hi:[1,0,0]
	v_mul_f32_e32 v56, v44, v44
	v_fmac_f32_e32 v56, v40, v40
	v_pk_fma_f32 v[46:47], v[54:55], s[26:27], v[46:47] op_sel_hi:[1,0,1] neg_lo:[1,0,0] neg_hi:[1,0,0]
	v_pk_fma_f32 v[50:51], v[54:55], s[26:27], v[50:51] op_sel_hi:[1,0,1] neg_lo:[1,0,0] neg_hi:[1,0,0]
	v_fmac_f32_e32 v56, v46, v46
	v_fmac_f32_e32 v56, v50, v50
	ds_swizzle_b32 v54, v56 offset:swizzle(SWAP,1)
	ds_swizzle_b32 v23, v21 offset:swizzle(SWAP,8)
	s_waitcnt lgkmcnt(2)
	v_add_f32_e32 v17, v17, v19
	ds_swizzle_b32 v19, v17 offset:swizzle(SWAP,16)
	s_waitcnt lgkmcnt(2)
	v_add_f32_e32 v54, v56, v54
	s_waitcnt lgkmcnt(1)
	v_add_f32_e32 v21, v21, v23
	ds_swizzle_b32 v55, v54 offset:swizzle(SWAP,2)
	ds_swizzle_b32 v23, v21 offset:swizzle(SWAP,16)
	s_waitcnt lgkmcnt(2)
	v_add_f32_e32 v17, v17, v19
	s_waitcnt lgkmcnt(1)
	v_add_f32_e32 v19, v54, v55
	v_readlane_b32 s2, v17, 0
	v_readlane_b32 s8, v17, 32
	s_waitcnt lgkmcnt(0)
	v_add_f32_e32 v17, v21, v23
	ds_swizzle_b32 v21, v19 offset:swizzle(SWAP,4)
	v_readlane_b32 s3, v17, 0
	v_readlane_b32 s10, v17, 32
	v_mov_b32_e32 v54, s8
	s_waitcnt lgkmcnt(0)
	v_add_f32_e32 v17, v19, v21
	v_mul_f32_e32 v21, v45, v45
	v_fmac_f32_e32 v21, v41, v41
	v_fmac_f32_e32 v21, v47, v47
	v_fmac_f32_e32 v21, v51, v51
	ds_swizzle_b32 v19, v17 offset:swizzle(SWAP,8)
	ds_swizzle_b32 v23, v21 offset:swizzle(SWAP,1)
	v_mov_b32_e32 v55, s10
	v_pk_add_f32 v[54:55], s[2:3], v[54:55]
	s_waitcnt lgkmcnt(1)
	v_add_f32_e32 v17, v17, v19
	s_waitcnt lgkmcnt(0)
; __device__ __forceinline__ float rsq_(float x) { return __builtin_amdgcn_rsqf(x); }
; __device__ __forceinline__ void sgu_chunk(const Params& p, int l, int b, int c) {
;     ...
;       const float rs = rsq_(wave_sum(q) * (1.f / 256.f) + EPS);
; #pragma unroll
;       for (int e = 0; e < 4; ++e) vT[(lane + 64 * e) * LROW + t] = f2bf(v[e] * rs * lg[e] + lb[e]);
;     }
;   }
;   __syncthreads();
;   const int g = wid >> 1, th = wid & 1;
;   u16 uq[4][4][4];
; #pragma unroll
;   for (int m = 0; m < 4; ++m)
; #pragma unroll
;     for (int jj = 0; jj < 4; ++jj)
; #pragma unroll
;       for (int n = 0; n < 4; ++n)
;         uq[m][jj][n] = proj[(rowbase + th * 64 + m * 16 + fq * 4 + jj) * PS + PC_U + g * 64 + n * 16 + fr];
	v_add_f32_e32 v21, v21, v23
	ds_swizzle_b32 v19, v17 offset:swizzle(SWAP,16)
	ds_swizzle_b32 v23, v21 offset:swizzle(SWAP,2)
	v_pk_fma_f32 v[42:43], v[54:55], s[26:27], v[42:43] op_sel_hi:[1,0,1] neg_lo:[1,0,0] neg_hi:[1,0,0]
	v_pk_fma_f32 v[38:39], v[54:55], s[26:27], v[38:39] op_sel_hi:[1,0,1] neg_lo:[1,0,0] neg_hi:[1,0,0]
	v_pk_fma_f32 v[48:49], v[54:55], s[26:27], v[48:49] op_sel_hi:[1,0,1] neg_lo:[1,0,0] neg_hi:[1,0,0]
	s_waitcnt lgkmcnt(1)
	v_add_f32_e32 v17, v17, v19
	s_waitcnt lgkmcnt(0)
	v_add_f32_e32 v19, v21, v23
	ds_swizzle_b32 v21, v19 offset:swizzle(SWAP,4)
	v_mul_f32_e32 v23, v42, v42
	v_fmac_f32_e32 v23, v38, v38
	v_pk_fma_f32 v[52:53], v[54:55], s[26:27], v[52:53] op_sel_hi:[1,0,1] neg_lo:[1,0,0] neg_hi:[1,0,0]
	v_fmac_f32_e32 v23, v48, v48
	s_waitcnt lgkmcnt(0)
	v_add_f32_e32 v19, v19, v21
	v_fmac_f32_e32 v23, v52, v52
	ds_swizzle_b32 v21, v19 offset:swizzle(SWAP,8)
	ds_swizzle_b32 v55, v23 offset:swizzle(SWAP,1)
	v_readlane_b32 s3, v17, 32
	v_readlane_b32 s2, v17, 0
	s_mov_b64 s[26:27], 0x1000
	v_mov_b32_e32 v17, s3
	v_add_f32_e32 v17, s2, v17
	v_fmamk_f32 v17, v17, 0x3b800000, v183
	v_rsq_f32_e32 v54, v17
	s_waitcnt lgkmcnt(1)
	v_add_f32_e32 v17, v19, v21
	s_waitcnt lgkmcnt(0)
	v_add_f32_e32 v21, v23, v55
	v_mul_f32_e32 v55, v43, v43
	v_fmac_f32_e32 v55, v39, v39
	v_fmac_f32_e32 v55, v49, v49
	ds_swizzle_b32 v19, v17 offset:swizzle(SWAP,16)
	ds_swizzle_b32 v23, v21 offset:swizzle(SWAP,2)
	v_fmac_f32_e32 v55, v53, v53
	ds_swizzle_b32 v56, v55 offset:swizzle(SWAP,1)
	s_waitcnt lgkmcnt(2)
	v_add_f32_e32 v17, v17, v19
	s_waitcnt lgkmcnt(1)
	v_add_f32_e32 v19, v21, v23
	ds_swizzle_b32 v21, v19 offset:swizzle(SWAP,4)
	s_waitcnt lgkmcnt(1)
	v_add_f32_e32 v23, v55, v56
	ds_swizzle_b32 v55, v23 offset:swizzle(SWAP,2)
	v_readlane_b32 s2, v17, 0
	v_readlane_b32 s3, v17, 32
	s_waitcnt lgkmcnt(1)
	v_add_f32_e32 v17, v19, v21
	ds_swizzle_b32 v19, v17 offset:swizzle(SWAP,8)
	s_waitcnt lgkmcnt(1)
	v_add_f32_e32 v23, v23, v55
	ds_swizzle_b32 v55, v23 offset:swizzle(SWAP,4)
	v_mov_b32_e32 v21, s3
	v_add_f32_e32 v21, s2, v21
	s_waitcnt lgkmcnt(1)
	v_add_f32_e32 v17, v17, v19
	ds_swizzle_b32 v19, v17 offset:swizzle(SWAP,16)
	s_waitcnt lgkmcnt(1)
	v_add_f32_e32 v23, v23, v55
	ds_swizzle_b32 v56, v23 offset:swizzle(SWAP,8)
	v_fmamk_f32 v21, v21, 0x3b800000, v183
	v_rsq_f32_e32 v55, v21
	s_waitcnt lgkmcnt(1)
	v_add_f32_e32 v17, v17, v19
	v_pk_mul_f32 v[40:41], v[40:41], v[54:55]
	v_readlane_b32 s2, v17, 0
	v_readlane_b32 s3, v17, 32
	s_waitcnt lgkmcnt(0)
	v_add_f32_e32 v17, v23, v56
	ds_swizzle_b32 v19, v17 offset:swizzle(SWAP,16)
	v_mov_b32_e32 v21, s3
	v_add_f32_e32 v21, s2, v21
	v_fmamk_f32 v21, v21, 0x3b800000, v183
	v_rsq_f32_e32 v56, v21
	s_waitcnt lgkmcnt(0)
	v_add_f32_e32 v17, v17, v19
	s_nop 0
	v_readlane_b32 s3, v17, 32
	v_readlane_b32 s2, v17, 0
	s_nop 0
	v_mov_b32_e32 v17, s3
	v_add_f32_e32 v17, s2, v17
	v_fmamk_f32 v17, v17, 0x3b800000, v183
	v_rsq_f32_e32 v57, v17
	s_nop 0
	v_pk_mul_f32 v[38:39], v[38:39], v[56:57]
	s_nop 0
	v_pk_fma_f32 v[38:39], v[20:21], v[38:39], v[22:23] op_sel_hi:[0,1,0]
	v_pk_fma_f32 v[20:21], v[20:21], v[40:41], v[22:23] op_sel_hi:[0,1,0]
	v_cvt_pk_bf16_f32 v23, v38, v39
	v_cvt_pk_bf16_f32 v22, v20, v21
	v_cvt_pk_bf16_f32 v21, v28, v29
	v_cvt_pk_bf16_f32 v20, v30, v31
	ds_write_b128 v15, v[20:23] offset:16
	v_pk_mul_f32 v[20:21], v[44:45], v[54:55]
	v_pk_mul_f32 v[22:23], v[42:43], v[56:57]
	s_nop 0
	v_pk_fma_f32 v[22:23], v[16:17], v[22:23], v[18:19] op_sel_hi:[0,1,0]
	v_pk_fma_f32 v[16:17], v[16:17], v[20:21], v[18:19] op_sel_hi:[0,1,0]
	v_cvt_pk_bf16_f32 v19, v22, v23
	v_cvt_pk_bf16_f32 v18, v16, v17
	v_cvt_pk_bf16_f32 v17, v24, v25
	v_cvt_pk_bf16_f32 v16, v26, v27
	ds_write_b128 v15, v[16:19] offset:17424
	v_pk_mul_f32 v[16:17], v[46:47], v[54:55]
	v_pk_mul_f32 v[18:19], v[48:49], v[56:57]
	v_pk_fma_f32 v[16:17], v[12:13], v[16:17], v[14:15] op_sel_hi:[0,1,0]
	v_pk_fma_f32 v[18:19], v[12:13], v[18:19], v[14:15] op_sel_hi:[0,1,0]
	v_cvt_pk_bf16_f32 v19, v18, v19
	v_cvt_pk_bf16_f32 v18, v16, v17
	v_cvt_pk_bf16_f32 v17, v0, v1
	v_cvt_pk_bf16_f32 v16, v2, v3
	v_pk_mul_f32 v[0:1], v[50:51], v[54:55]
	v_pk_mul_f32 v[2:3], v[52:53], v[56:57]
	v_pk_fma_f32 v[0:1], v[8:9], v[0:1], v[10:11] op_sel_hi:[0,1,0]
	v_pk_fma_f32 v[2:3], v[8:9], v[2:3], v[10:11] op_sel_hi:[0,1,0]
	v_cvt_pk_bf16_f32 v3, v2, v3
	v_cvt_pk_bf16_f32 v2, v0, v1
	v_cvt_pk_bf16_f32 v1, v36, v37
	v_cvt_pk_bf16_f32 v0, v34, v35
	ds_write_b128 v15, v[0:3] offset:52240
	v_lshrrev_b32_e32 v0, 2, v11
	v_and_b32_e32 v0, 12, v0
	v_lshl_or_b32 v77, v67, 6, v0
	v_ashrrev_i32_e32 v10, 7, v11
	v_or_b32_e32 v70, s20, v77
	v_lshlrev_b32_e32 v8, 6, v10
	v_mad_u64_u32 v[2:3], s[2:3], v70, s25, v[6:7]
	v_ashrrev_i32_e32 v9, 31, v8
	s_mul_i32 s2, s21, 0x1600
	v_add_u32_e32 v3, s2, v3
	v_lshlrev_b64 v[0:1], 1, v[8:9]
	v_or_b32_e32 v102, 1, v70
	ds_write_b128 v15, v[16:19] offset:34832
	v_lshl_add_u64 v[14:15], v[2:3], 0, v[0:1]
	v_lshlrev_b32_e32 v2, 1, v13
	v_mov_b32_e32 v3, v172
	v_mad_u64_u32 v[18:19], s[10:11], v102, s25, v[6:7]
	v_lshl_add_u64 v[14:15], v[14:15], 0, v[2:3]
	v_add_u32_e32 v19, s2, v19
	v_lshl_add_u64 v[16:17], v[14:15], 0, s[26:27]
	v_add_co_u32_e32 v14, vcc, s50, v14
	v_lshl_add_u64 v[18:19], v[18:19], 0, v[0:1]
	s_nop 0
	v_addc_co_u32_e32 v15, vcc, 0, v15, vcc
	v_lshl_add_u64 v[18:19], v[18:19], 0, v[2:3]
	v_lshl_add_u64 v[20:21], v[18:19], 0, s[26:27]
	v_add_co_u32_e32 v18, vcc, s50, v18
	v_or_b32_e32 v100, 2, v70
	s_waitcnt lgkmcnt(0)
	s_barrier
; __device__ __forceinline__ void sgu_chunk(const Params& p, int l, int b, int c) {
;     ...
;   u16 uq[4][4][4];
; #pragma unroll
;   for (int m = 0; m < 4; ++m)
; #pragma unroll
;     for (int jj = 0; jj < 4; ++jj)
; #pragma unroll
;       for (int n = 0; n < 4; ++n)
;         uq[m][jj][n] = proj[(rowbase + th * 64 + m * 16 + fq * 4 + jj) * PS + PC_U + g * 64 + n * 16 + fr];
;   f32x4 acc[4][4];
; #pragma unroll
;   for (int m = 0; m < 4; ++m)
; #pragma unroll
;     for (int n = 0; n < 4; ++n) acc[m][n] = f32x4{0.f, 0.f, 0.f, 0.f};
;   const u16* wm = L_wmask + ((long)(l * 4 + g) * 128) * 128;
; #pragma unroll
;   for (int k = 0; k < 4; ++k) {
;     if (k < 2 * (th + 1)) {
;       bf16x8 a[4];
; #pragma unroll
;       for (int m = 0; m < 4; ++m) a[m] = *(const bf16x8*)(wm + (th * 64 + m * 16 + fr) * 128 + k * 32 + fq * 8);
	v_addc_co_u32_e32 v19, vcc, 0, v19, vcc
	flat_load_ushort v175, v[14:15]
	flat_load_ushort v107, v[16:17] offset:32
	flat_load_ushort v111, v[16:17] offset:64
	flat_load_ushort v174, v[18:19]
	flat_load_ushort v173, v[20:21] offset:32
	flat_load_ushort v171, v[20:21] offset:64
	flat_load_ushort v170, v[20:21] offset:96
	flat_load_ushort v81, v[16:17] offset:96
	v_mad_u64_u32 v[14:15], s[10:11], v100, s25, v[6:7]
	v_add_u32_e32 v15, s2, v15
	v_or_b32_e32 v98, 3, v70
	v_lshl_add_u64 v[14:15], v[14:15], 0, v[0:1]
	v_mad_u64_u32 v[18:19], s[10:11], v98, s25, v[6:7]
	v_lshl_add_u64 v[14:15], v[14:15], 0, v[2:3]
	v_add_u32_e32 v19, s2, v19
	v_lshl_add_u64 v[16:17], v[14:15], 0, s[26:27]
	v_add_co_u32_e32 v14, vcc, s50, v14
	v_lshl_add_u64 v[18:19], v[18:19], 0, v[0:1]
	s_nop 0
	v_addc_co_u32_e32 v15, vcc, 0, v15, vcc
	v_lshl_add_u64 v[18:19], v[18:19], 0, v[2:3]
	v_lshl_add_u64 v[20:21], v[18:19], 0, s[26:27]
	v_add_co_u32_e32 v18, vcc, s50, v18
	v_or_b32_e32 v96, 16, v70
	s_nop 0
	v_addc_co_u32_e32 v19, vcc, 0, v19, vcc
	flat_load_ushort v169, v[14:15]
	flat_load_ushort v168, v[16:17] offset:32
	flat_load_ushort v167, v[16:17] offset:64
	flat_load_ushort v165, v[18:19]
	flat_load_ushort v164, v[20:21] offset:32
	flat_load_ushort v163, v[20:21] offset:64
	flat_load_ushort v162, v[20:21] offset:96
	flat_load_ushort v166, v[16:17] offset:96
	v_mad_u64_u32 v[14:15], s[10:11], v96, s25, v[6:7]
	v_add_u32_e32 v15, s2, v15
	v_or_b32_e32 v94, 17, v70
	v_lshl_add_u64 v[14:15], v[14:15], 0, v[0:1]
	v_mad_u64_u32 v[18:19], s[10:11], v94, s25, v[6:7]
	v_lshl_add_u64 v[14:15], v[14:15], 0, v[2:3]
	v_add_u32_e32 v19, s2, v19
	v_lshl_add_u64 v[16:17], v[14:15], 0, s[26:27]
	v_add_co_u32_e32 v14, vcc, s50, v14
	v_lshl_add_u64 v[18:19], v[18:19], 0, v[0:1]
	s_nop 0
	v_addc_co_u32_e32 v15, vcc, 0, v15, vcc
	v_lshl_add_u64 v[18:19], v[18:19], 0, v[2:3]
	v_lshl_add_u64 v[20:21], v[18:19], 0, s[26:27]
	v_add_co_u32_e32 v18, vcc, s50, v18
	v_or_b32_e32 v92, 18, v70
	s_nop 0
	v_addc_co_u32_e32 v19, vcc, 0, v19, vcc
	flat_load_ushort v161, v[14:15]
	flat_load_ushort v160, v[16:17] offset:32
	flat_load_ushort v159, v[16:17] offset:64
	flat_load_ushort v157, v[18:19]
	flat_load_ushort v156, v[20:21] offset:32
	flat_load_ushort v155, v[20:21] offset:64
	flat_load_ushort v154, v[20:21] offset:96
	flat_load_ushort v158, v[16:17] offset:96
	v_mad_u64_u32 v[14:15], s[10:11], v92, s25, v[6:7]
	v_add_u32_e32 v15, s2, v15
	v_lshl_add_u64 v[14:15], v[14:15], 0, v[0:1]
	v_lshl_add_u64 v[14:15], v[14:15], 0, v[2:3]
	v_add_co_u32_e32 v34, vcc, s50, v14
	v_or_b32_e32 v90, 19, v70
	v_lshl_add_u64 v[30:31], v[14:15], 0, s[26:27]
	v_addc_co_u32_e32 v35, vcc, 0, v15, vcc
	v_mad_u64_u32 v[14:15], s[10:11], v90, s25, v[6:7]
	v_add_u32_e32 v15, s2, v15
	v_lshl_add_u64 v[14:15], v[14:15], 0, v[0:1]
	v_lshl_add_u64 v[14:15], v[14:15], 0, v[2:3]
	v_add_u32_e32 v74, s40, v10
	v_add_co_u32_e32 v38, vcc, s50, v14
	v_ashrrev_i32_e32 v75, 31, v74
	v_lshl_add_u64 v[36:37], v[14:15], 0, s[26:27]
	v_addc_co_u32_e32 v39, vcc, 0, v15, vcc
	v_lshlrev_b64 v[14:15], 15, v[74:75]
	v_lshl_add_u64 v[14:15], s[0:1], 0, v[14:15]
	v_lshlrev_b32_e32 v9, 8, v13
	v_lshl_add_u64 v[108:109], v[14:15], 0, v[104:105]
	v_lshl_or_b32 v10, v67, 14, v9
	v_mov_b32_e32 v11, v172
	v_lshl_add_u64 v[62:63], v[108:109], 0, v[10:11]
	v_add_co_u32_e32 v64, vcc, s50, v62
	v_or_b32_e32 v88, 32, v70
	s_nop 0
	v_addc_co_u32_e32 v65, vcc, 0, v63, vcc
	flat_load_dwordx4 v[14:17], v[62:63]
	flat_load_dwordx4 v[18:21], v[64:65]
	v_add_co_u32_e32 v112, vcc, s23, v62
	v_mad_u64_u32 v[10:11], s[0:1], v88, s25, v[6:7]
	s_nop 0
	v_addc_co_u32_e32 v113, vcc, 0, v63, vcc
	v_add_co_u32_e32 v180, vcc, s24, v62
	v_add_u32_e32 v11, s2, v11
	s_nop 0
	v_addc_co_u32_e32 v181, vcc, 0, v63, vcc
	flat_load_dwordx4 v[22:25], v[112:113]
	flat_load_dwordx4 v[26:29], v[180:181]
	flat_load_ushort v153, v[34:35]
	flat_load_ushort v152, v[30:31] offset:32
	flat_load_ushort v151, v[30:31] offset:64
	flat_load_ushort v149, v[38:39]
	flat_load_ushort v148, v[36:37] offset:32
	flat_load_ushort v147, v[36:37] offset:64
	flat_load_ushort v146, v[36:37] offset:96
	flat_load_ushort v150, v[30:31] offset:96
	v_or_b32_e32 v86, 33, v70
	v_lshl_add_u64 v[10:11], v[10:11], 0, v[0:1]
	v_mad_u64_u32 v[34:35], s[0:1], v86, s25, v[6:7]
	v_lshl_add_u64 v[10:11], v[10:11], 0, v[2:3]
	v_add_u32_e32 v35, s2, v35
	v_lshl_add_u64 v[30:31], v[10:11], 0, s[26:27]
	v_add_co_u32_e32 v10, vcc, s50, v10
	v_lshl_add_u64 v[34:35], v[34:35], 0, v[0:1]
	s_nop 0
	v_addc_co_u32_e32 v11, vcc, 0, v11, vcc
	v_lshl_add_u64 v[34:35], v[34:35], 0, v[2:3]
	v_lshl_add_u64 v[36:37], v[34:35], 0, s[26:27]
	v_add_co_u32_e32 v34, vcc, s50, v34
	v_or_b32_e32 v84, 34, v70
	s_nop 0
	v_addc_co_u32_e32 v35, vcc, 0, v35, vcc
	flat_load_ushort v145, v[10:11]
	flat_load_ushort v144, v[30:31] offset:32
	flat_load_ushort v143, v[30:31] offset:64
	flat_load_ushort v141, v[34:35]
	flat_load_ushort v140, v[36:37] offset:32
	flat_load_ushort v139, v[36:37] offset:64
	flat_load_ushort v138, v[36:37] offset:96
	flat_load_ushort v142, v[30:31] offset:96
	v_mad_u64_u32 v[10:11], s[0:1], v84, s25, v[6:7]
	v_add_u32_e32 v11, s2, v11
	v_lshl_add_u64 v[10:11], v[10:11], 0, v[0:1]
	v_lshl_add_u64 v[10:11], v[10:11], 0, v[2:3]
	v_add_co_u32_e32 v34, vcc, s50, v10
	v_or_b32_e32 v82, 35, v70
	v_lshl_add_u64 v[30:31], v[10:11], 0, s[26:27]
	v_addc_co_u32_e32 v35, vcc, 0, v11, vcc
	v_mad_u64_u32 v[10:11], s[0:1], v82, s25, v[6:7]
	v_add_u32_e32 v11, s2, v11
	v_lshl_add_u64 v[10:11], v[10:11], 0, v[0:1]
	v_or_b32_e32 v76, v8, v13
	s_movk_i32 s0, 0x110
	v_lshl_add_u64 v[10:11], v[10:11], 0, v[2:3]
	v_mul_lo_u32 v8, v76, s0
; __device__ __forceinline__ f32x4 mfma16(bf16x8 a, bf16x8 b, f32x4 c) { return __builtin_amdgcn_mfma_f32_16x16x32_bf16(a, b, c, 0, 0, 0); }
; __device__ __forceinline__ void sgu_chunk(const Params& p, int l, int b, int c) {
;     ...
;   const u16* wm = L_wmask + ((long)(l * 4 + g) * 128) * 128;
; #pragma unroll
;   for (int k = 0; k < 4; ++k) {
;     if (k < 2 * (th + 1)) {
;       bf16x8 a[4];
; #pragma unroll
;       for (int m = 0; m < 4; ++m) a[m] = *(const bf16x8*)(wm + (th * 64 + m * 16 + fr) * 128 + k * 32 + fq * 8);
; #pragma unroll
;       for (int n = 0; n < 4; ++n) {
;         const bf16x8 bb = *(const bf16x8*)(vT + (g * 64 + n * 16 + fr) * LROW + k * 32 + fq * 8);
; #pragma unroll
;         for (int m = 0; m < 4; ++m) acc[m][n] = mfma16(a[m], bb, acc[m][n]);
;       }
;     }
	v_add_co_u32_e32 v38, vcc, s50, v10
	v_add_u32_e32 v69, v104, v8
	v_or_b32_e32 v78, 48, v70
	v_lshl_add_u64 v[36:37], v[10:11], 0, s[26:27]
	v_addc_co_u32_e32 v39, vcc, 0, v11, vcc
	ds_read_b128 v[8:11], v69
	flat_load_ushort v137, v[34:35]
	flat_load_ushort v136, v[30:31] offset:32
	flat_load_ushort v135, v[30:31] offset:64
	flat_load_ushort v133, v[38:39]
	flat_load_ushort v132, v[36:37] offset:32
	flat_load_ushort v131, v[36:37] offset:64
	flat_load_ushort v130, v[36:37] offset:96
	flat_load_ushort v134, v[30:31] offset:96
	v_mad_u64_u32 v[30:31], s[0:1], v78, s25, v[6:7]
	v_add_u32_e32 v31, s2, v31
	v_or_b32_e32 v72, 49, v70
	v_lshl_add_u64 v[30:31], v[30:31], 0, v[0:1]
	v_mad_u64_u32 v[48:49], s[0:1], v72, s25, v[6:7]
	v_lshl_add_u64 v[30:31], v[30:31], 0, v[2:3]
	v_add_u32_e32 v49, s2, v49
	v_lshl_add_u64 v[46:47], v[30:31], 0, s[26:27]
	v_add_co_u32_e32 v30, vcc, s50, v30
	v_lshl_add_u64 v[48:49], v[48:49], 0, v[0:1]
	s_nop 0
	v_addc_co_u32_e32 v31, vcc, 0, v31, vcc
	v_lshl_add_u64 v[48:49], v[48:49], 0, v[2:3]
	v_lshl_add_u64 v[58:59], v[48:49], 0, s[26:27]
	v_add_co_u32_e32 v48, vcc, s50, v48
	v_or_b32_e32 v68, 50, v70
	ds_read_b128 v[34:37], v69 offset:4352
	v_addc_co_u32_e32 v49, vcc, 0, v49, vcc
	flat_load_ushort v129, v[30:31]
	flat_load_ushort v128, v[46:47] offset:32
	flat_load_ushort v127, v[46:47] offset:64
	flat_load_ushort v125, v[48:49]
	flat_load_ushort v124, v[58:59] offset:32
	flat_load_ushort v123, v[58:59] offset:64
	flat_load_ushort v122, v[58:59] offset:96
	flat_load_ushort v126, v[46:47] offset:96
	v_mad_u64_u32 v[30:31], s[0:1], v68, s25, v[6:7]
	ds_read_b128 v[46:49], v69 offset:8704
	ds_read_b128 v[58:61], v69 offset:13056
	v_add_u32_e32 v31, s2, v31
	v_or_b32_e32 v66, 51, v70
	v_lshl_add_u64 v[30:31], v[30:31], 0, v[0:1]
	v_mad_u64_u32 v[6:7], s[0:1], v66, s25, v[6:7]
	v_lshl_add_u64 v[30:31], v[30:31], 0, v[2:3]
	v_add_u32_e32 v7, s2, v7
	v_lshl_add_u64 v[212:213], v[30:31], 0, s[26:27]
	v_add_co_u32_e32 v30, vcc, s50, v30
	v_lshl_add_u64 v[0:1], v[6:7], 0, v[0:1]
	s_nop 0
	v_addc_co_u32_e32 v31, vcc, 0, v31, vcc
	v_lshl_add_u64 v[6:7], v[0:1], 0, v[2:3]
	s_waitcnt vmcnt(0) lgkmcnt(0)
	v_mfma_f32_16x16x32_bf16 v[196:199], v[14:17], v[46:49], 0
	v_readfirstlane_b32 s3, v5
	v_readfirstlane_b32 s2, v4
	v_mfma_f32_16x16x32_bf16 v[200:203], v[18:21], v[46:49], 0
	v_mfma_f32_16x16x32_bf16 v[204:207], v[22:25], v[46:49], 0
	v_mfma_f32_16x16x32_bf16 v[208:211], v[26:29], v[46:49], 0
	v_lshl_add_u64 v[46:47], v[6:7], 0, s[26:27]
	v_add_co_u32_e32 v6, vcc, s50, v6
	v_mfma_f32_16x16x32_bf16 v[38:41], v[14:17], v[8:11], 0
	s_nop 0
	v_addc_co_u32_e32 v7, vcc, 0, v7, vcc
	flat_load_ushort v121, v[30:31]
	flat_load_ushort v120, v[212:213] offset:32
	flat_load_ushort v119, v[212:213] offset:64
	flat_load_ushort v117, v[6:7]
	flat_load_ushort v116, v[46:47] offset:32
	flat_load_ushort v115, v[46:47] offset:64
	flat_load_ushort v114, v[46:47] offset:96
	flat_load_ushort v118, v[212:213] offset:96
	v_mfma_f32_16x16x32_bf16 v[42:45], v[18:21], v[8:11], 0
	v_mfma_f32_16x16x32_bf16 v[50:53], v[22:25], v[8:11], 0
	v_mfma_f32_16x16x32_bf16 v[8:11], v[26:29], v[8:11], 0
	v_mfma_f32_16x16x32_bf16 v[54:57], v[14:17], v[34:37], 0
	v_mfma_f32_16x16x32_bf16 v[176:179], v[18:21], v[34:37], 0
	v_mfma_f32_16x16x32_bf16 v[192:195], v[22:25], v[34:37], 0
	v_mfma_f32_16x16x32_bf16 v[34:37], v[26:29], v[34:37], 0
	v_mfma_f32_16x16x32_bf16 v[0:3], v[14:17], v[58:61], 0
	v_mfma_f32_16x16x32_bf16 v[16:19], v[18:21], v[58:61], 0
	v_mfma_f32_16x16x32_bf16 v[212:215], v[22:25], v[58:61], 0
	v_mfma_f32_16x16x32_bf16 v[216:219], v[26:29], v[58:61], 0
	flat_load_dwordx4 v[220:223], v[62:63] offset:64
	flat_load_dwordx4 v[224:227], v[64:65] offset:64
	flat_load_dwordx4 v[228:231], v[112:113] offset:64
	flat_load_dwordx4 v[232:235], v[180:181] offset:64
	ds_read_b128 v[4:7], v69 offset:64
	s_waitcnt vmcnt(0) lgkmcnt(0)
	v_mfma_f32_16x16x32_bf16 v[62:65], v[220:223], v[4:7], v[38:41]
	v_mfma_f32_16x16x32_bf16 v[46:49], v[224:227], v[4:7], v[42:45]
	v_mfma_f32_16x16x32_bf16 v[28:31], v[228:231], v[4:7], v[50:53]
	v_mfma_f32_16x16x32_bf16 v[12:15], v[232:235], v[4:7], v[8:11]
	ds_read_b128 v[4:7], v69 offset:4416
	s_waitcnt lgkmcnt(0)
	v_mfma_f32_16x16x32_bf16 v[58:61], v[220:223], v[4:7], v[54:57]
	v_mfma_f32_16x16x32_bf16 v[42:45], v[224:227], v[4:7], v[176:179]
	v_mfma_f32_16x16x32_bf16 v[24:27], v[228:231], v[4:7], v[192:195]
	s_nop 1
	ds_read_b128 v[176:179], v69 offset:13120
	v_mfma_f32_16x16x32_bf16 v[8:11], v[232:235], v[4:7], v[34:37]
	ds_read_b128 v[4:7], v69 offset:8768
	s_waitcnt lgkmcnt(0)
	v_mfma_f32_16x16x32_bf16 v[54:57], v[220:223], v[4:7], v[196:199]
	v_mfma_f32_16x16x32_bf16 v[38:41], v[224:227], v[4:7], v[200:203]
	v_mfma_f32_16x16x32_bf16 v[20:23], v[228:231], v[4:7], v[204:207]
	v_mfma_f32_16x16x32_bf16 v[4:7], v[232:235], v[4:7], v[208:211]
	v_mfma_f32_16x16x32_bf16 v[50:53], v[220:223], v[176:179], v[0:3]
	v_mfma_f32_16x16x32_bf16 v[34:37], v[224:227], v[176:179], v[16:19]
	v_mfma_f32_16x16x32_bf16 v[16:19], v[228:231], v[176:179], v[212:215]
	v_mfma_f32_16x16x32_bf16 v[0:3], v[232:235], v[176:179], v[216:219]
	v_cmp_eq_u32_e64 s[0:1], 1, v67
	v_lshlrev_b32_e32 v112, 1, v73
	s_and_saveexec_b64 s[10:11], s[0:1]
	s_cbranch_execz .LBB0_848
; __device__ __forceinline__ f32x4 mfma16(bf16x8 a, bf16x8 b, f32x4 c) { return __builtin_amdgcn_mfma_f32_16x16x32_bf16(a, b, c, 0, 0, 0); }
; __device__ __forceinline__ void sgu_chunk(const Params& p, int l, int b, int c) {
;     ...
; #pragma unroll
;   for (int k = 0; k < 4; ++k) {
;     if (k < 2 * (th + 1)) {
;       bf16x8 a[4];
; #pragma unroll
;       for (int m = 0; m < 4; ++m) a[m] = *(const bf16x8*)(wm + (th * 64 + m * 16 + fr) * 128 + k * 32 + fq * 8);
; #pragma unroll
;       for (int n = 0; n < 4; ++n) {
;         const bf16x8 bb = *(const bf16x8*)(vT + (g * 64 + n * 16 + fr) * LROW + k * 32 + fq * 8);
; #pragma unroll
;         for (int m = 0; m < 4; ++m) acc[m][n] = mfma16(a[m], bb, acc[m][n]);
;       }
;     }
	v_mov_b32_e32 v113, v172
	v_lshl_add_u64 v[180:181], v[108:109], 0, v[112:113]
	v_add_co_u32_e32 v176, vcc, 0x4000, v180
	ds_read_b128 v[204:207], v69 offset:128
	s_nop 0
	v_addc_co_u32_e32 v177, vcc, 0, v181, vcc
	v_add_co_u32_e32 v192, vcc, 0x5000, v180
	flat_load_dwordx4 v[176:179], v[176:177] offset:128
	s_nop 0
	v_addc_co_u32_e32 v193, vcc, 0, v181, vcc
	v_add_co_u32_e32 v196, vcc, 0x6000, v180
	flat_load_dwordx4 v[192:195], v[192:193] offset:128
	s_nop 0
	v_addc_co_u32_e32 v197, vcc, 0, v181, vcc
	v_add_co_u32_e32 v180, vcc, 0x7000, v180
	flat_load_dwordx4 v[196:199], v[196:197] offset:128
	s_nop 0
	v_addc_co_u32_e32 v181, vcc, 0, v181, vcc
	flat_load_dwordx4 v[200:203], v[180:181] offset:128
	s_waitcnt vmcnt(0) lgkmcnt(0)
	v_mfma_f32_16x16x32_bf16 v[62:65], v[176:179], v[204:207], v[62:65]
	v_mfma_f32_16x16x32_bf16 v[46:49], v[192:195], v[204:207], v[46:49]
	v_mfma_f32_16x16x32_bf16 v[28:31], v[196:199], v[204:207], v[28:31]
	v_mfma_f32_16x16x32_bf16 v[12:15], v[200:203], v[204:207], v[12:15]
	ds_read_b128 v[204:207], v69 offset:4480
	s_waitcnt lgkmcnt(0)
	v_mfma_f32_16x16x32_bf16 v[58:61], v[176:179], v[204:207], v[58:61]
	v_mfma_f32_16x16x32_bf16 v[42:45], v[192:195], v[204:207], v[42:45]
	v_mfma_f32_16x16x32_bf16 v[24:27], v[196:199], v[204:207], v[24:27]
	v_mfma_f32_16x16x32_bf16 v[8:11], v[200:203], v[204:207], v[8:11]
	ds_read_b128 v[204:207], v69 offset:8832
	s_waitcnt lgkmcnt(0)
	v_mfma_f32_16x16x32_bf16 v[54:57], v[176:179], v[204:207], v[54:57]
	v_mfma_f32_16x16x32_bf16 v[38:41], v[192:195], v[204:207], v[38:41]
	v_mfma_f32_16x16x32_bf16 v[20:23], v[196:199], v[204:207], v[20:23]
	v_mfma_f32_16x16x32_bf16 v[4:7], v[200:203], v[204:207], v[4:7]
	ds_read_b128 v[204:207], v69 offset:13184
	s_waitcnt lgkmcnt(0)
	v_mfma_f32_16x16x32_bf16 v[50:53], v[176:179], v[204:207], v[50:53]
	v_mfma_f32_16x16x32_bf16 v[34:37], v[192:195], v[204:207], v[34:37]
	v_mfma_f32_16x16x32_bf16 v[16:19], v[196:199], v[204:207], v[16:19]
	v_mfma_f32_16x16x32_bf16 v[0:3], v[200:203], v[204:207], v[0:3]

; __device__ __forceinline__ int tid_() { int t = threadIdx.x; asm volatile("" : "+v"(t)); return t; }
; template <int EPI>
; __device__ __forceinline__ void gemm_phase(const Params& p, const u16* __restrict__ A, const u16* __restrict__ Bt, int K, int nN,
;                            u16* __restrict__ Cout, int ldc) {
;   float* const L_ssx = TAB_ssx;
;   float* const L_dtbuf = TAB_dtbuf;
;   const int tid = tid_(), wid = tid >> 6, lane = tid & 63, wr = wid >> 2, wc = wid & 3, fr = lane & 15, fq = lane >> 4;
;   constexpr int nM = NTOK / 256, NXCD = 8, WGM = 8;
;   const int nwg = nM * nN;
;   unsigned soff[GL];
; #pragma unroll
;   for (int i = 0; i < GL; ++i) { int r_, c_; stage_rc(wid * 1024 + i * 8192 + lane * 16, r_, c_); soff[i] = (unsigned)(r_ * K + c_); }
;   const int nt = K / BK;
;   const int laneoff = (fr * 64 + fq * 16) ^ ((fr >> 3) << 5);
;   const int aoff = wr * 16384 + laneoff, boff = TILE_B + wc * 8192 + laneoff;
;     ...
;     gemm_phase<EPI_WIN>(p, TAB_xb, wl + W_WIN, DM, 10, TAB_big, PS);
.LBB0_851:
	s_andn2_b64 vcc, exec, s[0:1]
	s_cbranch_vccnz .LBB0_882
	v_mov_b32_e32 v173, v182
	s_mov_b32 s39, s92
	s_waitcnt vmcnt(0)
	v_readlane_b32 s8, v251, 32
	v_readlane_b32 s33, v250, 32
	v_readlane_b32 s11, v251, 33
	v_readlane_b32 s10, v250, 33
	s_cmpk_gt_i32 s39, 0x4ff
	s_waitcnt vmcnt(0)
	v_readlane_b32 s13, v251, 39
	v_readlane_b32 s12, v250, 39
	s_cbranch_scc1 .LBB0_882
	v_lshlrev_b32_e32 v1, 4, v173
	v_and_b32_e32 v2, 32, v173
	v_bitop3_b32 v1, v1, v2, 48 bitop3:0x6c
	v_lshrrev_b32_e32 v1, 1, v1
	v_lshlrev_b32_e32 v2, 8, v173
	s_movk_i32 s0, 0x3c00
	v_ashrrev_i32_e32 v0, 6, v173
	v_and_or_b32 v1, v2, s0, v1
	v_lshrrev_b32_e32 v2, 31, v173
	v_add_u32_e32 v2, v0, v2
	v_lshlrev_b32_e32 v175, 10, v0
	v_lshrrev_b32_e32 v2, 1, v2
	s_movk_i32 s0, 0x3fc0
	v_lshlrev_b32_e32 v3, 5, v0
	v_mul_lo_u32 v2, v2, s0
	v_add_u32_e32 v177, 0x2000, v175
	v_add3_u32 v176, v2, v3, v1
	v_ashrrev_i32_e32 v2, 10, v177
	v_lshrrev_b32_e32 v3, 31, v177
	v_add_u32_e32 v3, v2, v3
	v_ashrrev_i32_e32 v3, 1, v3
	v_mul_i32_i24_e32 v4, 2, v3
	v_sub_u32_e32 v2, v2, v4
	v_lshl_or_b32 v3, v3, 14, v1
	v_add_u32_e32 v179, 0x4000, v175
	v_lshl_add_u32 v178, v2, 5, v3
	v_ashrrev_i32_e32 v2, 10, v179
	v_lshrrev_b32_e32 v3, 31, v179
	v_add_u32_e32 v3, v2, v3
	v_ashrrev_i32_e32 v3, 1, v3
	v_mul_i32_i24_e32 v4, 2, v3
	v_sub_u32_e32 v2, v2, v4
	v_lshl_or_b32 v3, v3, 14, v1
	v_add_u32_e32 v181, 0x6000, v175
	v_lshl_add_u32 v180, v2, 5, v3
	v_ashrrev_i32_e32 v2, 10, v181
	v_lshrrev_b32_e32 v3, 31, v181
	v_add_u32_e32 v3, v2, v3
	v_ashrrev_i32_e32 v3, 1, v3
	v_and_b32_e32 v174, 15, v173
	v_mul_i32_i24_e32 v4, 2, v3
	v_lshlrev_b32_e32 v7, 2, v173
	s_add_u32 s40, s66, 0x1080000
	v_sub_u32_e32 v2, v2, v4
	v_lshl_or_b32 v1, v3, 14, v1
	v_and_b32_e32 v0, 3, v0
	v_lshlrev_b32_e32 v4, 6, v174
	v_and_b32_e32 v5, 48, v173
	v_and_b32_e32 v8, 32, v7
	s_addc_u32 s41, s67, 0
	v_lshl_add_u32 v191, v2, 5, v1
	v_lshlrev_b32_e32 v2, 13, v0
	v_or_b32_e32 v6, v4, v5
	v_bitop3_b32 v4, v4, v8, v5 bitop3:0x36
	s_mov_b32 s2, 0x8000
	v_or3_b32 v194, v2, v4, s2
	s_add_u32 s2, s35, s20
	s_addc_u32 s3, s36, s37
	s_add_u32 s42, s2, 0x1080100
	v_ashrrev_i32_e32 v1, 8, v173
	s_addc_u32 s43, s3, 0
	v_lshlrev_b32_e32 v3, 14, v1
	s_movk_i32 s0, 0x100
	s_add_u32 s44, s33, 0x100
	s_mov_b32 s68, s66
	s_mov_b32 s69, s67
	v_bfe_u32 v192, v173, 4, 2
	v_cmp_gt_i32_e64 s[0:1], s0, v173
	v_bitop3_b32 v193, v3, v6, v8 bitop3:0xf6
	v_add_u32_e32 v195, 0x20000, v7
	v_lshl_add_u32 v196, v1, 9, v187
	v_lshlrev_b32_e32 v197, 6, v0
	v_add_u32_e32 v198, 0x10000, v175
	v_add_u32_e32 v199, 0x12000, v175
	v_add_u32_e32 v200, 0x14000, v175
	v_add_u32_e32 v201, 0x16000, v175
	v_add_u32_e32 v202, 0x1a000, v175
	v_add_u32_e32 v203, 0x1c000, v175
	v_add_u32_e32 v204, 0x1e000, v175
	v_lshl_add_u32 v205, v1, 15, v188
	s_mov_b32 s65, s35
	s_mov_b32 s67, s20
	s_mov_b32 s64, s36
	s_mov_b32 s66, s37
	s_addc_u32 s45, s8, 0
	s_mov_b64 s[34:35], 0
	v_add_u32_e32 v206, 0x18000, v175
	s_branch .LBB0_855

; #define TAB_IN(i) uni((const float*)p.tab[(i)])
; __device__ __forceinline__ float softplus_(float x) { return fmaxf(x, 0.f) + log1p_(__expf(-fabsf(x))); }
; __device__ __forceinline__ int tid_() { int t = threadIdx.x; asm volatile("" : "+v"(t)); return t; }
; __device__ __forceinline__ void ssd_dt(const Params& p, int l, long rowbase) {
;   float* const L_dtbuf = TAB_dtbuf;
;   const float* const L_in18 = TAB_IN(18);
;   const float* const L_in19 = TAB_IN(19);
;   const int tid = tid_(); const int wid = tid >> 6, lane = tid & 63;
;   float* dts = (float*)shm;
;   float* acs = dts + 768;
;   if (wid < 6) {
;     const int h = wid;
;     const float a = -__expf(L_in19[l * 6 + h]), bias = L_in18[l * 6 + h];
;     const long row = rowbase + 2 * lane;
;     const float d0 = softplus_(L_dtbuf[row * 8 + h] + bias), d1 = softplus_(L_dtbuf[(row + 1) * 8 + h] + bias);
; __device__ __forceinline__ void ssd_out(const Params& p, int l, int b, int c) {
;   u16* const L_big = TAB_big;
;   u16* const L_ymix = TAB_ymix;
;   u16* const L_prevb = TAB_prevb;
;   const float* const L_in16 = TAB_IN(16);
;   const float* const L_in17 = TAB_IN(17);
;   const float* const L_in20 = TAB_IN(20);
;   const float* const L_in21 = TAB_IN(21);
;   const int tid = tid_(), wid = tid >> 6, lane = tid & 63, fr = lane & 15, fq = lane >> 4;
;   const long rowbase = (long)b * SEQ + c * 128;
.LBB0_888:
	s_ashr_i32 s68, s0, 5
	v_writelane_b32 v249, s0, 42
	s_and_b32 s19, s0, 31
	v_mov_b32_e32 v152, v182
	s_ashr_i32 s69, s68, 31
	s_lshl_b64 s[6:7], s[68:69], 12
	s_waitcnt vmcnt(0)
	v_readlane_b32 s4, v250, 35
	v_readlane_b32 s1, v251, 33
	v_readlane_b32 s0, v250, 33
	v_readlane_b32 s63, v251, 34
	v_readlane_b32 s62, v250, 34
	v_writelane_b32 v249, s0, 43
	v_mov_b32_e32 v4, v182
	v_readlane_b32 s5, v251, 35
	v_writelane_b32 v249, s1, 44
	s_mov_b32 s1, s7
	s_waitcnt vmcnt(0)
	v_readlane_b32 s8, v251, 16
	v_readlane_b32 s15, v250, 16
	v_readlane_b32 s14, v251, 17
	v_readlane_b32 s16, v250, 17
	s_waitcnt vmcnt(0)
	v_readlane_b32 s33, v251, 20
	v_readlane_b32 s18, v250, 20
	v_readlane_b32 s0, v251, 21
	s_nop 1
	v_writelane_b32 v249, s0, 45
	v_readlane_b32 s0, v250, 21
	s_nop 1
	v_writelane_b32 v249, s0, 46
	s_lshl_b32 s0, s19, 7
	s_or_b32 s0, s6, s0
	v_writelane_b32 v249, s0, 47
	s_nop 1
	v_writelane_b32 v249, s1, 48
	s_waitcnt vmcnt(0)
	v_readlane_b32 s1, v251, 41
	v_readlane_b32 s0, v250, 41
	s_waitcnt vmcnt(0)
	v_readlane_b32 s10, v250, 18
	v_ashrrev_i32_e32 v0, 6, v4
	v_readlane_b32 s11, v251, 18
	v_readlane_b32 s13, v251, 19
	v_readlane_b32 s12, v250, 19
	v_cmp_gt_i32_e32 vcc, 6, v0
	s_and_saveexec_b64 s[2:3], vcc
	s_cbranch_execz .LBB0_898
	v_readlane_b32 s17, v249, 32
	v_and_b32_e32 v5, 63, v4
	v_ashrrev_i32_e32 v1, 31, v0
	v_add_u32_e32 v2, s17, v0
	v_ashrrev_i32_e32 v3, 31, v2
	v_lshlrev_b64 v[2:3], 2, v[2:3]
	v_lshl_add_u64 v[6:7], s[12:13], 0, v[2:3]
	v_lshl_add_u64 v[2:3], s[10:11], 0, v[2:3]
	v_readlane_b32 s10, v249, 47
	flat_load_dword v7, v[6:7]
	v_lshlrev_b32_e32 v6, 1, v5
	v_readlane_b32 s11, v249, 48
	flat_load_dword v9, v[2:3]
	v_or_b32_e32 v2, s10, v6
	v_mov_b32_e32 v3, s11
	v_lshlrev_b64 v[2:3], 5, v[2:3]
	v_lshl_add_u64 v[2:3], s[0:1], 0, v[2:3]
	v_lshl_add_u64 v[2:3], v[0:1], 2, v[2:3]
	flat_load_dword v1, v[2:3]
	s_mov_b32 s0, 0xbfb8aa3b
	s_waitcnt vmcnt(0) lgkmcnt(0)
	v_add_f32_e32 v1, v9, v1
	v_mul_f32_e64 v8, |v1|, s0
	v_exp_f32_e32 v10, v8
	s_nop 0
	v_cmp_ngt_f32_e32 vcc, s54, v10
	s_and_saveexec_b64 s[0:1], vcc
	s_xor_b64 s[10:11], exec, s[0:1]
	s_cbranch_execz .LBB0_891
	v_add_f32_e32 v8, 1.0, v10
	v_cmp_gt_f32_e32 vcc, s55, v8
	s_nop 1
	v_cndmask_b32_e64 v10, 0, 32, vcc
	v_ldexp_f32 v8, v8, v10
	v_log_f32_e32 v8, v8
	s_nop 0
	v_mul_f32_e32 v10, 0x3f317217, v8
	v_fma_f32 v10, v8, s56, -v10
	v_fmac_f32_e32 v10, 0x3377d1cf, v8
	v_fmac_f32_e32 v10, 0x3f317217, v8
	v_cmp_lt_f32_e64 s[0:1], |v8|, s57
	s_nop 1
	v_cndmask_b32_e64 v8, v8, v10, s[0:1]
	v_cndmask_b32_e32 v10, 0, v185, vcc
	v_sub_f32_e32 v8, v8, v10

; __device__ __forceinline__ float bf2f(u16 h) { return __uint_as_float(((unsigned)h) << 16); }
; __device__ __forceinline__ float rsq_(float x) { return __builtin_amdgcn_rsqf(x); }
; __device__ __forceinline__ void ssd_out(const Params& p, int l, int b, int c) {
;     ...
;   float* rsd = (float*)shm;
; #pragma unroll
;   for (int jj = 0; jj < 4; ++jj) {
;     float s = ssq[jj];
;     s += swz_xor<1>(s); s += swz_xor<2>(s); s += swz_xor<4>(s); s += swz_xor<8>(s);
;     if (fr == 0) rsd[wid * 16 + fq * 4 + jj] = rsq_(s * (1.f / 384.f) + EPS);
;   }
;   __syncthreads();
;   {
;     const float* ng = L_in21 + l * 384;
;     u16* ym = L_ymix;
;     uint4 v[12];
; #pragma unroll
;     for (int it = 0; it < 12; ++it) {
;       const int id = it * 512 + tid, r = id / 48, ck = id % 48;
;       v[it] = *(const uint4*)(ym + (rowbase + r) * DM + 384 + ck * 8);
;     }
; #pragma unroll
;     for (int it = 0; it < 12; ++it) {
;       const int id = it * 512 + tid, r = id / 48, ck = id % 48;
;       const float rs = rsd[r];
;       const float4 g0 = *(const float4*)(ng + ck * 8), g1 = *(const float4*)(ng + ck * 8 + 4);
;       uint4 o;
;       o.x = pack2(bf2f((u16)(v[it].x & 0xffff)) * rs * g0.x, bf2f((u16)(v[it].x >> 16)) * rs * g0.y);
;       o.y = pack2(bf2f((u16)(v[it].y & 0xffff)) * rs * g0.z, bf2f((u16)(v[it].y >> 16)) * rs * g0.w);
;       o.z = pack2(bf2f((u16)(v[it].z & 0xffff)) * rs * g1.x, bf2f((u16)(v[it].z >> 16)) * rs * g1.y);
;       o.w = pack2(bf2f((u16)(v[it].w & 0xffff)) * rs * g1.z, bf2f((u16)(v[it].w >> 16)) * rs * g1.w);
;       *(uint4*)(ym + (rowbase + r) * DM + 384 + ck * 8) = o;
;     }
.LBB0_994:
	s_or_b64 exec, exec, s[0:1]
	v_mul_hi_i32 v0, v152, s49
	v_lshrrev_b32_e32 v1, 31, v0
	v_ashrrev_i32_e32 v0, 3, v0
	v_add_u32_e32 v0, v0, v1
	v_mul_lo_u32 v1, v0, 48
	v_readlane_b32 s4, v249, 47
	v_sub_u32_e32 v4, v152, v1
	v_ashrrev_i32_e32 v1, 31, v0
	v_readlane_b32 s5, v249, 48
	v_readlane_b32 s6, v248, 13
	v_readlane_b32 s7, v248, 14
	s_waitcnt lgkmcnt(0)
	v_lshl_add_u64 v[2:3], s[4:5], 0, v[0:1]
	v_lshlrev_b64 v[2:3], 11, v[2:3]
	v_lshlrev_b32_e32 v4, 3, v4
	v_lshl_add_u64 v[2:3], s[6:7], 0, v[2:3]
	v_ashrrev_i32_e32 v5, 31, v4
	v_add_u32_e32 v1, 0x200, v152
	v_lshl_add_u64 v[112:113], v[4:5], 1, v[2:3]
	v_mul_hi_i32 v2, v1, s49
	v_lshrrev_b32_e32 v3, 31, v2
	v_ashrrev_i32_e32 v2, 3, v2
	v_add_u32_e32 v110, v2, v3
	v_mul_lo_u32 v2, v110, 48
	v_ashrrev_i32_e32 v111, 31, v110
	v_sub_u32_e32 v1, v1, v2
	v_lshl_add_u64 v[2:3], s[4:5], 0, v[110:111]
	v_lshlrev_b64 v[2:3], 11, v[2:3]
	v_lshlrev_b32_e32 v114, 3, v1
	v_lshl_add_u64 v[2:3], s[6:7], 0, v[2:3]
	v_ashrrev_i32_e32 v115, 31, v114
	v_add_u32_e32 v1, 0x400, v152
	v_lshl_add_u64 v[106:107], v[114:115], 1, v[2:3]
	v_mul_hi_i32 v2, v1, s49
	v_lshrrev_b32_e32 v3, 31, v2
	v_ashrrev_i32_e32 v2, 3, v2
	v_add_u32_e32 v104, v2, v3
	v_mul_lo_u32 v2, v104, 48
	v_ashrrev_i32_e32 v105, 31, v104
	v_sub_u32_e32 v1, v1, v2
	v_lshl_add_u64 v[2:3], s[4:5], 0, v[104:105]
	v_lshlrev_b64 v[2:3], 11, v[2:3]
	v_lshlrev_b32_e32 v108, 3, v1
	v_lshl_add_u64 v[2:3], s[6:7], 0, v[2:3]
	v_ashrrev_i32_e32 v109, 31, v108
	v_add_u32_e32 v1, 0x600, v152
	v_lshl_add_u64 v[100:101], v[108:109], 1, v[2:3]
	v_mul_hi_i32 v2, v1, s49
	v_lshrrev_b32_e32 v3, 31, v2
	v_ashrrev_i32_e32 v2, 3, v2
	v_add_u32_e32 v96, v2, v3
	v_mul_lo_u32 v2, v96, 48
	v_ashrrev_i32_e32 v97, 31, v96
	v_sub_u32_e32 v1, v1, v2
	v_lshl_add_u64 v[2:3], s[4:5], 0, v[96:97]
	v_lshlrev_b64 v[2:3], 11, v[2:3]
	v_lshlrev_b32_e32 v102, 3, v1
	v_lshl_add_u64 v[2:3], s[6:7], 0, v[2:3]
	v_ashrrev_i32_e32 v103, 31, v102
	v_add_u32_e32 v1, 0x800, v152
	v_lshl_add_u64 v[92:93], v[102:103], 1, v[2:3]
	v_mul_hi_i32 v2, v1, s49
	v_lshrrev_b32_e32 v3, 31, v2
	v_ashrrev_i32_e32 v2, 3, v2
	v_add_u32_e32 v88, v2, v3
	v_mul_lo_u32 v2, v88, 48
	v_ashrrev_i32_e32 v89, 31, v88
	v_sub_u32_e32 v1, v1, v2
	v_lshl_add_u64 v[2:3], s[4:5], 0, v[88:89]
	v_lshlrev_b64 v[2:3], 11, v[2:3]
	v_lshlrev_b32_e32 v98, 3, v1
	v_lshl_add_u64 v[2:3], s[6:7], 0, v[2:3]
	v_ashrrev_i32_e32 v99, 31, v98
	v_add_u32_e32 v1, 0xa00, v152
	v_lshl_add_u64 v[84:85], v[98:99], 1, v[2:3]
	v_mul_hi_i32 v2, v1, s49
	v_lshrrev_b32_e32 v3, 31, v2
	v_ashrrev_i32_e32 v2, 3, v2
	v_add_u32_e32 v78, v2, v3
	v_mul_lo_u32 v2, v78, 48
	v_ashrrev_i32_e32 v79, 31, v78
	v_sub_u32_e32 v1, v1, v2
	v_lshl_add_u64 v[2:3], s[4:5], 0, v[78:79]
	v_lshlrev_b64 v[2:3], 11, v[2:3]
	v_lshlrev_b32_e32 v90, 3, v1
	v_lshl_add_u64 v[2:3], s[6:7], 0, v[2:3]
	v_ashrrev_i32_e32 v91, 31, v90
	v_add_u32_e32 v1, 0xc00, v152
	v_lshl_add_u64 v[70:71], v[90:91], 1, v[2:3]
	v_mul_hi_i32 v2, v1, s49
	v_lshrrev_b32_e32 v3, 31, v2
	v_ashrrev_i32_e32 v2, 3, v2
	v_add_u32_e32 v68, v2, v3
	v_mul_lo_u32 v2, v68, 48
	v_ashrrev_i32_e32 v69, 31, v68
	v_sub_u32_e32 v1, v1, v2
	v_lshl_add_u64 v[2:3], s[4:5], 0, v[68:69]
	s_lshl_b64 s[0:1], s[30:31], 2
	v_readlane_b32 s2, v249, 46
	v_lshlrev_b64 v[2:3], 11, v[2:3]
	v_lshlrev_b32_e32 v80, 3, v1
	s_add_u32 s2, s2, s0
	v_readlane_b32 s3, v249, 45
	v_lshl_add_u64 v[2:3], s[6:7], 0, v[2:3]
	v_ashrrev_i32_e32 v81, 31, v80
	s_addc_u32 s3, s3, s1
	s_barrier
	flat_load_dwordx4 v[44:47], v[112:113] offset:768
	flat_load_dwordx4 v[40:43], v[106:107] offset:768
	v_lshl_add_u64 v[60:61], v[80:81], 1, v[2:3]
	v_lshl_add_u64 v[2:3], v[4:5], 2, s[2:3]
	flat_load_dwordx4 v[36:39], v[100:101] offset:768
	flat_load_dwordx4 v[32:35], v[92:93] offset:768
	flat_load_dwordx4 v[24:27], v[84:85] offset:768
	flat_load_dwordx4 v[16:19], v[70:71] offset:768
	flat_load_dwordx4 v[116:119], v[2:3]
	flat_load_dwordx4 v[120:123], v[2:3] offset:16
	v_add_u32_e32 v1, 0xe00, v152
	v_mul_hi_i32 v6, v1, s49
	v_lshrrev_b32_e32 v7, 31, v6
	v_ashrrev_i32_e32 v4, 3, v6
	v_add_u32_e32 v82, v4, v7
	v_mul_lo_u32 v4, v82, 48
	v_sub_u32_e32 v1, v1, v4
	v_lshlrev_b32_e32 v94, 3, v1
	v_add_u32_e32 v1, 0x1000, v152
	v_mul_hi_i32 v2, v1, s49
	v_lshrrev_b32_e32 v3, 31, v2
	v_ashrrev_i32_e32 v2, 3, v2
	v_add_u32_e32 v74, v2, v3
	v_mul_lo_u32 v2, v74, 48
	v_ashrrev_i32_e32 v75, 31, v74
	v_sub_u32_e32 v1, v1, v2
	v_lshl_add_u64 v[2:3], s[4:5], 0, v[74:75]
	v_lshlrev_b64 v[2:3], 11, v[2:3]
	v_lshlrev_b32_e32 v86, 3, v1
	v_lshl_add_u64 v[2:3], s[6:7], 0, v[2:3]
	v_ashrrev_i32_e32 v87, 31, v86
	v_add_u32_e32 v1, 0x1200, v152
	v_lshl_add_u64 v[66:67], v[86:87], 1, v[2:3]
	v_mul_hi_i32 v2, v1, s49
	v_lshrrev_b32_e32 v3, 31, v2
	v_ashrrev_i32_e32 v2, 3, v2
	v_add_u32_e32 v62, v2, v3
	v_ashrrev_i32_e32 v83, 31, v82
	v_mul_lo_u32 v2, v62, 48
	v_ashrrev_i32_e32 v63, 31, v62
	v_lshl_add_u64 v[4:5], s[4:5], 0, v[82:83]
	v_sub_u32_e32 v1, v1, v2
	v_lshl_add_u64 v[2:3], s[4:5], 0, v[62:63]
	v_lshlrev_b64 v[4:5], 11, v[4:5]
	v_lshlrev_b64 v[2:3], 11, v[2:3]
	v_lshlrev_b32_e32 v72, 3, v1
	v_lshl_add_u64 v[4:5], s[6:7], 0, v[4:5]
	v_ashrrev_i32_e32 v95, 31, v94
	v_lshl_add_u64 v[2:3], s[6:7], 0, v[2:3]
	v_ashrrev_i32_e32 v73, 31, v72
	v_lshlrev_b32_e32 v0, 2, v0
	v_lshl_add_u64 v[76:77], v[94:95], 1, v[4:5]
	flat_load_dwordx4 v[28:31], v[60:61] offset:768
	flat_load_dwordx4 v[20:23], v[76:77] offset:768
	v_lshl_add_u64 v[58:59], v[72:73], 1, v[2:3]
	flat_load_dwordx4 v[12:15], v[66:67] offset:768
	flat_load_dwordx4 v[8:11], v[58:59] offset:768
	ds_read_b32 v124, v0
	v_add_u32_e32 v1, 0x1400, v152
	v_mul_hi_i32 v2, v1, s49
	v_lshrrev_b32_e32 v3, 31, v2
	v_ashrrev_i32_e32 v2, 3, v2
	v_add_u32_e32 v56, v2, v3
	v_mul_lo_u32 v2, v56, 48
	v_ashrrev_i32_e32 v57, 31, v56
	v_sub_u32_e32 v1, v1, v2
	v_lshl_add_u64 v[2:3], s[4:5], 0, v[56:57]
	v_lshlrev_b64 v[2:3], 11, v[2:3]
	v_lshlrev_b32_e32 v64, 3, v1
	v_lshl_add_u64 v[2:3], s[6:7], 0, v[2:3]
	v_ashrrev_i32_e32 v65, 31, v64
	v_add_u32_e32 v1, 0x1600, v152
	v_lshl_add_u64 v[52:53], v[64:65], 1, v[2:3]
	v_mul_hi_i32 v2, v1, s49
	v_lshrrev_b32_e32 v3, 31, v2
	v_ashrrev_i32_e32 v2, 3, v2
	v_add_u32_e32 v50, v2, v3
	v_mul_lo_u32 v2, v50, 48
	v_ashrrev_i32_e32 v51, 31, v50
	v_sub_u32_e32 v1, v1, v2
	v_lshl_add_u64 v[2:3], s[4:5], 0, v[50:51]
	v_lshlrev_b64 v[2:3], 11, v[2:3]
	v_lshlrev_b32_e32 v54, 3, v1
	v_lshl_add_u64 v[2:3], s[6:7], 0, v[2:3]
	s_waitcnt vmcnt(0) lgkmcnt(0)
; __device__ __forceinline__ float bf2f(u16 h) { return __uint_as_float(((unsigned)h) << 16); }
; __device__ __forceinline__ void ssd_out(const Params& p, int l, int b, int c) {
;     ...
; #pragma unroll
;     for (int it = 0; it < 12; ++it) {
;       const int id = it * 512 + tid, r = id / 48, ck = id % 48;
;       const float rs = rsd[r];
;       const float4 g0 = *(const float4*)(ng + ck * 8), g1 = *(const float4*)(ng + ck * 8 + 4);
;       uint4 o;
;       o.x = pack2(bf2f((u16)(v[it].x & 0xffff)) * rs * g0.x, bf2f((u16)(v[it].x >> 16)) * rs * g0.y);
;       o.y = pack2(bf2f((u16)(v[it].y & 0xffff)) * rs * g0.z, bf2f((u16)(v[it].y >> 16)) * rs * g0.w);
;       o.z = pack2(bf2f((u16)(v[it].z & 0xffff)) * rs * g1.x, bf2f((u16)(v[it].z >> 16)) * rs * g1.y);
;       o.w = pack2(bf2f((u16)(v[it].w & 0xffff)) * rs * g1.z, bf2f((u16)(v[it].w >> 16)) * rs * g1.w);
;       *(uint4*)(ym + (rowbase + r) * DM + 384 + ck * 8) = o;
;     }
	v_lshlrev_b32_e32 v126, 16, v44
	v_and_b32_e32 v127, 0xffff0000, v44
	v_pk_mul_f32 v[126:127], v[124:125], v[126:127] op_sel_hi:[0,1]
	v_ashrrev_i32_e32 v55, 31, v54
	v_lshl_add_u64 v[48:49], v[54:55], 1, v[2:3]
	flat_load_dwordx4 v[4:7], v[52:53] offset:768
	flat_load_dwordx4 v[0:3], v[48:49] offset:768
	v_pk_mul_f32 v[116:117], v[116:117], v[126:127]
	v_lshlrev_b32_e32 v51, 2, v110
	v_cvt_pk_bf16_f32 v44, v116, v117
	v_lshlrev_b32_e32 v116, 16, v45
	v_and_b32_e32 v117, 0xffff0000, v45
	v_pk_mul_f32 v[116:117], v[124:125], v[116:117] op_sel_hi:[0,1]
	v_pk_mul_f32 v[116:117], v[116:117], v[118:119]
	v_and_b32_e32 v105, 0xffff0000, v36
	v_cvt_pk_bf16_f32 v45, v116, v117
	v_lshlrev_b32_e32 v116, 16, v46
	v_and_b32_e32 v117, 0xffff0000, v46
	v_pk_mul_f32 v[116:117], v[124:125], v[116:117] op_sel_hi:[0,1]
	v_pk_mul_f32 v[116:117], v[116:117], v[120:121]
	s_movk_i32 s25, 0x1600
	v_cvt_pk_bf16_f32 v46, v116, v117
	v_lshlrev_b32_e32 v116, 16, v47
	v_and_b32_e32 v117, 0xffff0000, v47
	v_pk_mul_f32 v[116:117], v[124:125], v[116:117] op_sel_hi:[0,1]
	v_pk_mul_f32 v[116:117], v[116:117], v[122:123]
	s_nop 0
	v_cvt_pk_bf16_f32 v47, v116, v117
	flat_store_dwordx4 v[112:113], v[44:47] offset:768
	v_lshl_add_u64 v[112:113], v[114:115], 2, s[2:3]
	flat_load_dwordx4 v[44:47], v[112:113]
	s_nop 0
	flat_load_dwordx4 v[112:115], v[112:113] offset:16
	ds_read_b32 v110, v51
	v_lshlrev_b32_e32 v116, 16, v40
	v_and_b32_e32 v117, 0xffff0000, v40
	v_lshlrev_b32_e32 v51, 2, v104
	v_lshlrev_b32_e32 v104, 16, v36
	s_waitcnt lgkmcnt(0)
	v_pk_mul_f32 v[116:117], v[110:111], v[116:117] op_sel_hi:[0,1]
	v_lshlrev_b32_e32 v36, 16, v37
	v_and_b32_e32 v37, 0xffff0000, v37
	s_waitcnt vmcnt(0)
	v_pk_mul_f32 v[44:45], v[44:45], v[116:117]
	s_nop 0
	v_cvt_pk_bf16_f32 v40, v44, v45
	v_lshlrev_b32_e32 v44, 16, v41
	v_and_b32_e32 v45, 0xffff0000, v41
	v_pk_mul_f32 v[44:45], v[110:111], v[44:45] op_sel_hi:[0,1]
	v_pk_mul_f32 v[44:45], v[44:45], v[46:47]
	s_nop 0
	v_cvt_pk_bf16_f32 v41, v44, v45
	v_lshlrev_b32_e32 v44, 16, v42
	v_and_b32_e32 v45, 0xffff0000, v42
	v_pk_mul_f32 v[44:45], v[110:111], v[44:45] op_sel_hi:[0,1]
	v_pk_mul_f32 v[44:45], v[44:45], v[112:113]
	s_nop 0
	v_cvt_pk_bf16_f32 v42, v44, v45
	v_lshlrev_b32_e32 v44, 16, v43
	v_and_b32_e32 v45, 0xffff0000, v43
	v_pk_mul_f32 v[44:45], v[110:111], v[44:45] op_sel_hi:[0,1]
	v_pk_mul_f32 v[44:45], v[44:45], v[114:115]
	v_lshlrev_b32_e32 v110, 16, v39
	v_cvt_pk_bf16_f32 v43, v44, v45
	flat_store_dwordx4 v[106:107], v[40:43] offset:768
	v_lshl_add_u64 v[44:45], v[108:109], 2, s[2:3]
	flat_load_dwordx4 v[40:43], v[44:45]
	s_nop 0
	flat_load_dwordx4 v[44:47], v[44:45] offset:16
	ds_read_b32 v106, v51
	v_lshlrev_b32_e32 v108, 16, v38
	v_and_b32_e32 v109, 0xffff0000, v38
	v_and_b32_e32 v111, 0xffff0000, v39
	v_lshlrev_b32_e32 v51, 2, v96
	s_waitcnt lgkmcnt(0)
	v_pk_mul_f32 v[104:105], v[106:107], v[104:105] op_sel_hi:[0,1]
	v_pk_mul_f32 v[36:37], v[106:107], v[36:37] op_sel_hi:[0,1]
	v_pk_mul_f32 v[108:109], v[106:107], v[108:109] op_sel_hi:[0,1]
	s_waitcnt vmcnt(0)
	v_pk_mul_f32 v[40:41], v[40:41], v[104:105]
	v_pk_mul_f32 v[42:43], v[36:37], v[42:43]
	v_cvt_pk_bf16_f32 v36, v40, v41
	v_pk_mul_f32 v[40:41], v[106:107], v[110:111] op_sel_hi:[0,1]
	v_pk_mul_f32 v[44:45], v[108:109], v[44:45]
	v_pk_mul_f32 v[40:41], v[40:41], v[46:47]
	v_cvt_pk_bf16_f32 v37, v42, v43
	v_cvt_pk_bf16_f32 v38, v44, v45
	v_cvt_pk_bf16_f32 v39, v40, v41
	flat_store_dwordx4 v[100:101], v[36:39] offset:768
	v_lshl_add_u64 v[40:41], v[102:103], 2, s[2:3]
	flat_load_dwordx4 v[36:39], v[40:41]
	s_nop 0
	flat_load_dwordx4 v[40:43], v[40:41] offset:16
	ds_read_b32 v96, v51
	v_lshl_add_u64 v[44:45], v[98:99], 2, s[2:3]
	v_lshlrev_b32_e32 v46, 16, v32
	v_and_b32_e32 v47, 0xffff0000, v32
	v_lshlrev_b32_e32 v32, 16, v33
	v_and_b32_e32 v33, 0xffff0000, v33
	v_lshlrev_b32_e32 v98, 16, v34
	v_and_b32_e32 v99, 0xffff0000, v34
	v_lshlrev_b32_e32 v34, 16, v35
	v_and_b32_e32 v35, 0xffff0000, v35
	s_waitcnt lgkmcnt(0)
	v_pk_mul_f32 v[46:47], v[96:97], v[46:47] op_sel_hi:[0,1]
	v_pk_mul_f32 v[32:33], v[96:97], v[32:33] op_sel_hi:[0,1]
	v_pk_mul_f32 v[98:99], v[96:97], v[98:99] op_sel_hi:[0,1]
	v_pk_mul_f32 v[34:35], v[96:97], v[34:35] op_sel_hi:[0,1]
	v_mov_b32_e32 v96, v182
	v_mov_b32_e32 v111, 0
	s_waitcnt vmcnt(0)
	v_pk_mul_f32 v[36:37], v[36:37], v[46:47]
	v_pk_mul_f32 v[38:39], v[32:33], v[38:39]
	v_pk_mul_f32 v[40:41], v[98:99], v[40:41]
	v_pk_mul_f32 v[42:43], v[34:35], v[42:43]
	v_cvt_pk_bf16_f32 v32, v36, v37
	v_cvt_pk_bf16_f32 v33, v38, v39
	v_cvt_pk_bf16_f32 v34, v40, v41
	v_cvt_pk_bf16_f32 v35, v42, v43
	flat_store_dwordx4 v[92:93], v[32:35] offset:768
	flat_load_dwordx4 v[32:35], v[44:45]
	s_nop 0
	flat_load_dwordx4 v[36:39], v[44:45] offset:16
	v_lshlrev_b32_e32 v44, 2, v88
	ds_read_b32 v44, v44
	v_lshlrev_b32_e32 v42, 16, v24
	v_and_b32_e32 v43, 0xffff0000, v24
	v_lshlrev_b32_e32 v24, 16, v25
	v_and_b32_e32 v25, 0xffff0000, v25
	v_lshlrev_b32_e32 v46, 16, v26
	v_and_b32_e32 v47, 0xffff0000, v26
	v_lshlrev_b32_e32 v26, 16, v27
	v_and_b32_e32 v27, 0xffff0000, v27
	s_waitcnt lgkmcnt(0)
	v_pk_mul_f32 v[42:43], v[44:45], v[42:43] op_sel_hi:[0,1]
	v_pk_mul_f32 v[24:25], v[44:45], v[24:25] op_sel_hi:[0,1]
	v_pk_mul_f32 v[46:47], v[44:45], v[46:47] op_sel_hi:[0,1]
	v_pk_mul_f32 v[26:27], v[44:45], v[26:27] op_sel_hi:[0,1]
	v_lshl_add_u64 v[40:41], v[90:91], 2, s[2:3]
	s_waitcnt vmcnt(0)
; __device__ __forceinline__ float bf2f(u16 h) { return __uint_as_float(((unsigned)h) << 16); }
; __device__ __forceinline__ void ssd_out(const Params& p, int l, int b, int c) {
;     ...
; #pragma unroll
;     for (int it = 0; it < 12; ++it) {
;       const int id = it * 512 + tid, r = id / 48, ck = id % 48;
;       const float rs = rsd[r];
;       const float4 g0 = *(const float4*)(ng + ck * 8), g1 = *(const float4*)(ng + ck * 8 + 4);
;       uint4 o;
;       o.x = pack2(bf2f((u16)(v[it].x & 0xffff)) * rs * g0.x, bf2f((u16)(v[it].x >> 16)) * rs * g0.y);
;       o.y = pack2(bf2f((u16)(v[it].y & 0xffff)) * rs * g0.z, bf2f((u16)(v[it].y >> 16)) * rs * g0.w);
;       o.z = pack2(bf2f((u16)(v[it].z & 0xffff)) * rs * g1.x, bf2f((u16)(v[it].z >> 16)) * rs * g1.y);
;       o.w = pack2(bf2f((u16)(v[it].w & 0xffff)) * rs * g1.z, bf2f((u16)(v[it].w >> 16)) * rs * g1.w);
;       *(uint4*)(ym + (rowbase + r) * DM + 384 + ck * 8) = o;
;     }
	v_pk_mul_f32 v[32:33], v[32:33], v[42:43]
	v_pk_mul_f32 v[34:35], v[24:25], v[34:35]
	v_pk_mul_f32 v[36:37], v[46:47], v[36:37]
	v_pk_mul_f32 v[38:39], v[26:27], v[38:39]
	v_cvt_pk_bf16_f32 v24, v32, v33
	v_cvt_pk_bf16_f32 v25, v34, v35
	v_cvt_pk_bf16_f32 v26, v36, v37
	v_cvt_pk_bf16_f32 v27, v38, v39
	flat_store_dwordx4 v[84:85], v[24:27] offset:768
	flat_load_dwordx4 v[24:27], v[40:41]
	s_nop 0
	flat_load_dwordx4 v[32:35], v[40:41] offset:16
	v_lshlrev_b32_e32 v40, 2, v78
	ds_read_b32 v40, v40
	v_lshlrev_b32_e32 v38, 16, v16
	v_and_b32_e32 v39, 0xffff0000, v16
	v_lshlrev_b32_e32 v16, 16, v17
	v_and_b32_e32 v17, 0xffff0000, v17
	v_lshlrev_b32_e32 v42, 16, v18
	v_and_b32_e32 v43, 0xffff0000, v18
	v_lshlrev_b32_e32 v18, 16, v19
	v_and_b32_e32 v19, 0xffff0000, v19
	s_waitcnt lgkmcnt(0)
	v_pk_mul_f32 v[38:39], v[40:41], v[38:39] op_sel_hi:[0,1]
	v_pk_mul_f32 v[16:17], v[40:41], v[16:17] op_sel_hi:[0,1]
	v_pk_mul_f32 v[42:43], v[40:41], v[42:43] op_sel_hi:[0,1]
	v_pk_mul_f32 v[18:19], v[40:41], v[18:19] op_sel_hi:[0,1]
	v_lshl_add_u64 v[36:37], v[80:81], 2, s[2:3]
	s_waitcnt vmcnt(0)
	v_pk_mul_f32 v[24:25], v[24:25], v[38:39]
	v_pk_mul_f32 v[26:27], v[16:17], v[26:27]
	v_pk_mul_f32 v[32:33], v[42:43], v[32:33]
	v_pk_mul_f32 v[34:35], v[18:19], v[34:35]
	v_cvt_pk_bf16_f32 v16, v24, v25
	v_cvt_pk_bf16_f32 v17, v26, v27
	v_cvt_pk_bf16_f32 v18, v32, v33
	v_cvt_pk_bf16_f32 v19, v34, v35
	flat_store_dwordx4 v[70:71], v[16:19] offset:768
	flat_load_dwordx4 v[16:19], v[36:37]
	s_nop 0
	flat_load_dwordx4 v[24:27], v[36:37] offset:16
	v_lshlrev_b32_e32 v36, 2, v68
	ds_read_b32 v36, v36
	v_lshlrev_b32_e32 v34, 16, v28
	v_and_b32_e32 v35, 0xffff0000, v28
	v_lshlrev_b32_e32 v28, 16, v29
	v_and_b32_e32 v29, 0xffff0000, v29
	v_lshlrev_b32_e32 v38, 16, v30
	v_and_b32_e32 v39, 0xffff0000, v30
	v_lshlrev_b32_e32 v30, 16, v31
	v_and_b32_e32 v31, 0xffff0000, v31
	s_waitcnt lgkmcnt(0)
	v_pk_mul_f32 v[34:35], v[36:37], v[34:35] op_sel_hi:[0,1]
	v_pk_mul_f32 v[28:29], v[36:37], v[28:29] op_sel_hi:[0,1]
	v_pk_mul_f32 v[38:39], v[36:37], v[38:39] op_sel_hi:[0,1]
	v_pk_mul_f32 v[30:31], v[36:37], v[30:31] op_sel_hi:[0,1]
	v_lshl_add_u64 v[32:33], v[94:95], 2, s[2:3]
	s_waitcnt vmcnt(0)
	v_pk_mul_f32 v[16:17], v[16:17], v[34:35]
	v_pk_mul_f32 v[18:19], v[28:29], v[18:19]
	v_pk_mul_f32 v[24:25], v[38:39], v[24:25]
	v_pk_mul_f32 v[26:27], v[30:31], v[26:27]
	v_cvt_pk_bf16_f32 v16, v16, v17
	v_cvt_pk_bf16_f32 v17, v18, v19
	v_cvt_pk_bf16_f32 v18, v24, v25
	v_cvt_pk_bf16_f32 v19, v26, v27
	flat_store_dwordx4 v[60:61], v[16:19] offset:768
	flat_load_dwordx4 v[16:19], v[32:33]
	s_nop 0
	flat_load_dwordx4 v[24:27], v[32:33] offset:16
	v_lshlrev_b32_e32 v32, 2, v82
	ds_read_b32 v32, v32
	v_lshlrev_b32_e32 v30, 16, v20
	v_and_b32_e32 v31, 0xffff0000, v20
	v_lshlrev_b32_e32 v20, 16, v21
	v_and_b32_e32 v21, 0xffff0000, v21
	v_lshlrev_b32_e32 v34, 16, v22
	v_and_b32_e32 v35, 0xffff0000, v22
	v_lshlrev_b32_e32 v22, 16, v23
	v_and_b32_e32 v23, 0xffff0000, v23
	s_waitcnt lgkmcnt(0)
	v_pk_mul_f32 v[30:31], v[32:33], v[30:31] op_sel_hi:[0,1]
	v_pk_mul_f32 v[20:21], v[32:33], v[20:21] op_sel_hi:[0,1]
	v_pk_mul_f32 v[34:35], v[32:33], v[34:35] op_sel_hi:[0,1]
	v_pk_mul_f32 v[22:23], v[32:33], v[22:23] op_sel_hi:[0,1]
	v_lshl_add_u64 v[28:29], v[86:87], 2, s[2:3]
	s_waitcnt vmcnt(0)
	v_pk_mul_f32 v[16:17], v[16:17], v[30:31]
	v_pk_mul_f32 v[18:19], v[20:21], v[18:19]
	v_pk_mul_f32 v[20:21], v[34:35], v[24:25]
	v_pk_mul_f32 v[22:23], v[22:23], v[26:27]
	v_cvt_pk_bf16_f32 v16, v16, v17
	v_cvt_pk_bf16_f32 v17, v18, v19
	v_cvt_pk_bf16_f32 v18, v20, v21
	v_cvt_pk_bf16_f32 v19, v22, v23
	flat_store_dwordx4 v[76:77], v[16:19] offset:768
	flat_load_dwordx4 v[16:19], v[28:29]
	s_nop 0
	flat_load_dwordx4 v[20:23], v[28:29] offset:16
	v_lshlrev_b32_e32 v28, 2, v74
	ds_read_b32 v28, v28
	v_lshlrev_b32_e32 v26, 16, v12
	v_and_b32_e32 v27, 0xffff0000, v12
	v_lshlrev_b32_e32 v12, 16, v13
	v_and_b32_e32 v13, 0xffff0000, v13
	v_lshlrev_b32_e32 v30, 16, v14
	v_and_b32_e32 v31, 0xffff0000, v14
	v_lshlrev_b32_e32 v14, 16, v15
	v_and_b32_e32 v15, 0xffff0000, v15
	s_waitcnt lgkmcnt(0)
	v_pk_mul_f32 v[26:27], v[28:29], v[26:27] op_sel_hi:[0,1]
	v_pk_mul_f32 v[12:13], v[28:29], v[12:13] op_sel_hi:[0,1]
	v_pk_mul_f32 v[30:31], v[28:29], v[30:31] op_sel_hi:[0,1]
	v_pk_mul_f32 v[14:15], v[28:29], v[14:15] op_sel_hi:[0,1]
	v_lshl_add_u64 v[24:25], v[72:73], 2, s[2:3]
	s_waitcnt vmcnt(0)
	v_pk_mul_f32 v[16:17], v[16:17], v[26:27]
	v_pk_mul_f32 v[18:19], v[12:13], v[18:19]
	v_pk_mul_f32 v[20:21], v[30:31], v[20:21]
	v_pk_mul_f32 v[22:23], v[14:15], v[22:23]
	v_cvt_pk_bf16_f32 v12, v16, v17
	v_cvt_pk_bf16_f32 v13, v18, v19
	v_cvt_pk_bf16_f32 v14, v20, v21
	v_cvt_pk_bf16_f32 v15, v22, v23
	flat_store_dwordx4 v[66:67], v[12:15] offset:768
	flat_load_dwordx4 v[12:15], v[24:25]
	s_nop 0
	flat_load_dwordx4 v[16:19], v[24:25] offset:16
	v_lshlrev_b32_e32 v24, 2, v62
	ds_read_b32 v24, v24
	v_lshlrev_b32_e32 v22, 16, v8
	v_and_b32_e32 v23, 0xffff0000, v8
	v_lshlrev_b32_e32 v8, 16, v9
	v_and_b32_e32 v9, 0xffff0000, v9
	v_lshlrev_b32_e32 v26, 16, v10
	v_and_b32_e32 v27, 0xffff0000, v10
	v_lshlrev_b32_e32 v10, 16, v11
	v_and_b32_e32 v11, 0xffff0000, v11
	s_waitcnt lgkmcnt(0)
; template <int NCG, class F>
; __device__ __forceinline__ void conv_chunk(const u16* __restrict__ proj, int c, long rowbase, int col,
;                                            const float* __restrict__ cw, int cstride, const float* __restrict__ cb, F store) {
;   const int tid = tid_(); const int wid = tid >> 6, lane = tid & 63;
;   const int t0 = wid * 16;
;   const bool has_prev = !(c == 0 && wid == 0);
;   const u16* src = proj + (rowbase + t0) * PS + col + lane;
;   u16 raw[NCG][19];
; #pragma unroll
;   for (int i = 0; i < NCG; ++i) {
; #pragma unroll
;     for (int r = 0; r < 3; ++r) raw[i][r] = has_prev ? src[(long)(r - 3) * PS + i * 64] : (u16)0;
; __device__ __forceinline__ void ssd_out(const Params& p, int l, int b, int c) {
;     ...
; #pragma unroll
;     for (int it = 0; it < 12; ++it) {
;       const int id = it * 512 + tid, r = id / 48, ck = id % 48;
;       const float rs = rsd[r];
;       const float4 g0 = *(const float4*)(ng + ck * 8), g1 = *(const float4*)(ng + ck * 8 + 4);
;       uint4 o;
;       o.x = pack2(bf2f((u16)(v[it].x & 0xffff)) * rs * g0.x, bf2f((u16)(v[it].x >> 16)) * rs * g0.y);
;       o.y = pack2(bf2f((u16)(v[it].y & 0xffff)) * rs * g0.z, bf2f((u16)(v[it].y >> 16)) * rs * g0.w);
;       o.z = pack2(bf2f((u16)(v[it].z & 0xffff)) * rs * g1.x, bf2f((u16)(v[it].z >> 16)) * rs * g1.y);
;       o.w = pack2(bf2f((u16)(v[it].w & 0xffff)) * rs * g1.z, bf2f((u16)(v[it].w >> 16)) * rs * g1.w);
;       *(uint4*)(ym + (rowbase + r) * DM + 384 + ck * 8) = o;
;     }
; __device__ __forceinline__ void lru_chunk(const Params& p, int l, int b, int c, bool final) {
;   u16* const L_big = TAB_big;
;   u16* const L_ymix = TAB_ymix;
;   u16* const L_wgt = TAB_wgt;
;   float* const L_lcarry = TAB_lcarry;
;   float* const L_lagg = TAB_lagg;
;   const float* const L_in9 = TAB_IN(9);
;   const float* const L_in10 = TAB_IN(10);
;   const float* const L_in12 = TAB_IN(12);
;   const float* const L_in14 = TAB_IN(14);
;   const float* const L_in15 = TAB_IN(15);
;   const int tid = tid_(), wid = tid >> 6, lane = tid & 63, fr = lane & 15, fq = lane >> 4;
;   const long rowbase = (long)b * SEQ + c * 128;
;   const u16* proj = L_big;
;   constexpr int RROW = 392;
;   u16* rec = (u16*)shm;
;   conv_chunk<6>(proj, c, rowbase, PC_REC, L_in9 + l * 4 * 384, 384, L_in10 + l * 384,
;              [&](int t, int chl, float y) { rec[t * RROW + chl] = f2bf(y); });
	v_pk_mul_f32 v[22:23], v[24:25], v[22:23] op_sel_hi:[0,1]
	v_pk_mul_f32 v[8:9], v[24:25], v[8:9] op_sel_hi:[0,1]
	v_pk_mul_f32 v[26:27], v[24:25], v[26:27] op_sel_hi:[0,1]
	v_pk_mul_f32 v[10:11], v[24:25], v[10:11] op_sel_hi:[0,1]
	v_lshl_add_u64 v[20:21], v[64:65], 2, s[2:3]
	s_waitcnt vmcnt(0)
	v_pk_mul_f32 v[12:13], v[12:13], v[22:23]
	v_pk_mul_f32 v[14:15], v[8:9], v[14:15]
	v_pk_mul_f32 v[16:17], v[26:27], v[16:17]
	v_pk_mul_f32 v[18:19], v[10:11], v[18:19]
	v_cvt_pk_bf16_f32 v8, v12, v13
	v_cvt_pk_bf16_f32 v9, v14, v15
	v_cvt_pk_bf16_f32 v10, v16, v17
	v_cvt_pk_bf16_f32 v11, v18, v19
	flat_store_dwordx4 v[58:59], v[8:11] offset:768
	flat_load_dwordx4 v[8:11], v[20:21]
	s_nop 0
	flat_load_dwordx4 v[12:15], v[20:21] offset:16
	v_lshlrev_b32_e32 v20, 2, v56
	ds_read_b32 v20, v20
	v_lshlrev_b32_e32 v18, 16, v4
	v_and_b32_e32 v19, 0xffff0000, v4
	v_lshlrev_b32_e32 v4, 16, v5
	v_and_b32_e32 v5, 0xffff0000, v5
	v_lshlrev_b32_e32 v22, 16, v6
	v_and_b32_e32 v23, 0xffff0000, v6
	v_lshlrev_b32_e32 v6, 16, v7
	v_and_b32_e32 v7, 0xffff0000, v7
	s_waitcnt lgkmcnt(0)
	v_pk_mul_f32 v[18:19], v[20:21], v[18:19] op_sel_hi:[0,1]
	v_pk_mul_f32 v[4:5], v[20:21], v[4:5] op_sel_hi:[0,1]
	v_pk_mul_f32 v[22:23], v[20:21], v[22:23] op_sel_hi:[0,1]
	v_pk_mul_f32 v[6:7], v[20:21], v[6:7] op_sel_hi:[0,1]
	v_lshl_add_u64 v[16:17], v[54:55], 2, s[2:3]
	v_readlane_b32 s2, v249, 55
	v_readlane_b32 s3, v249, 56
	s_waitcnt vmcnt(0)
	v_pk_mul_f32 v[8:9], v[8:9], v[18:19]
	v_pk_mul_f32 v[10:11], v[4:5], v[10:11]
	v_pk_mul_f32 v[12:13], v[22:23], v[12:13]
	v_pk_mul_f32 v[14:15], v[6:7], v[14:15]
	v_cvt_pk_bf16_f32 v4, v8, v9
	v_cvt_pk_bf16_f32 v5, v10, v11
	v_cvt_pk_bf16_f32 v6, v12, v13
	v_cvt_pk_bf16_f32 v7, v14, v15
	flat_store_dwordx4 v[52:53], v[4:7] offset:768
	flat_load_dwordx4 v[4:7], v[16:17]
	s_nop 0
	flat_load_dwordx4 v[8:11], v[16:17] offset:16
	v_lshlrev_b32_e32 v14, 2, v50
	ds_read_b32 v14, v14
	v_lshlrev_b32_e32 v12, 16, v0
	v_and_b32_e32 v13, 0xffff0000, v0
	v_lshlrev_b32_e32 v0, 16, v1
	v_and_b32_e32 v1, 0xffff0000, v1
	v_lshlrev_b32_e32 v16, 16, v2
	v_and_b32_e32 v17, 0xffff0000, v2
	v_lshlrev_b32_e32 v2, 16, v3
	v_and_b32_e32 v3, 0xffff0000, v3
	s_waitcnt lgkmcnt(0)
	v_pk_mul_f32 v[12:13], v[14:15], v[12:13] op_sel_hi:[0,1]
	v_pk_mul_f32 v[0:1], v[14:15], v[0:1] op_sel_hi:[0,1]
	v_pk_mul_f32 v[16:17], v[14:15], v[16:17] op_sel_hi:[0,1]
	v_pk_mul_f32 v[2:3], v[14:15], v[2:3] op_sel_hi:[0,1]
	s_waitcnt vmcnt(0)
	v_pk_mul_f32 v[4:5], v[4:5], v[12:13]
	v_pk_mul_f32 v[6:7], v[0:1], v[6:7]
	v_pk_mul_f32 v[8:9], v[16:17], v[8:9]
	v_pk_mul_f32 v[10:11], v[2:3], v[10:11]
	v_cvt_pk_bf16_f32 v0, v4, v5
	v_cvt_pk_bf16_f32 v1, v6, v7
	v_cvt_pk_bf16_f32 v2, v8, v9
	v_cvt_pk_bf16_f32 v3, v10, v11
	flat_store_dwordx4 v[48:49], v[0:3] offset:768
	s_waitcnt lgkmcnt(0)
	s_barrier
	global_load_dwordx4 v[6:9], v172, s[94:95] offset:264
	global_load_dwordx2 v[18:19], v172, s[94:95] offset:296
	global_load_dwordx2 v[20:21], v172, s[94:95] offset:320
	global_load_dwordx2 v[22:23], v172, s[94:95] offset:96
	global_load_dwordx4 v[14:17], v172, s[94:95] offset:112
	v_mov_b32_e32 v0, v182
	v_mov_b32_e32 v3, v172
	v_ashrrev_i32_e32 v110, 2, v0
	v_and_b32_e32 v4, 63, v0
	v_cmp_lt_u32_e32 vcc, 63, v0
	v_and_b32_e32 v0, -16, v110
	v_ashrrev_i32_e32 v1, 31, v0
	v_lshl_add_u64 v[24:25], s[4:5], 0, v[0:1]
	v_lshlrev_b32_e32 v2, 1, v4
	s_or_b64 s[2:3], s[2:3], vcc
	v_mov_b32_e32 v1, 0
	s_waitcnt vmcnt(0)
	v_readfirstlane_b32 s15, v7
	v_readfirstlane_b32 s14, v6
	v_readfirstlane_b32 s12, v8
	v_readfirstlane_b32 s13, v9
	v_mov_b64_e32 v[6:7], s[14:15]
	v_mad_u64_u32 v[6:7], s[4:5], v24, s25, v[6:7]
	v_mov_b32_e32 v8, v7
	v_mad_u64_u32 v[8:9], s[4:5], v25, s25, v[8:9]
	v_mov_b32_e32 v7, v8
	v_readlane_b32 s8, v251, 10
	v_readlane_b32 s11, v250, 10
	v_lshl_add_u64 v[12:13], v[6:7], 0, v[2:3]
	s_mov_b64 s[4:5], 0x300
	v_readfirstlane_b32 s17, v19
	v_readfirstlane_b32 s16, v18
	v_readfirstlane_b32 s6, v21
	v_readfirstlane_b32 s7, v20
	v_readlane_b32 s10, v251, 9
	v_readlane_b32 s24, v250, 9
	v_readfirstlane_b32 s19, v23
	v_readfirstlane_b32 s18, v22
	v_readfirstlane_b32 s21, v15
	v_readfirstlane_b32 s20, v14
	v_readfirstlane_b32 s23, v17
	v_readfirstlane_b32 s22, v16
	v_lshl_add_u64 v[10:11], v[12:13], 0, s[4:5]
	s_and_saveexec_b64 s[4:5], s[2:3]
	s_cbranch_execz .LBB0_996
	v_add_co_u32_e32 v6, vcc, 0xffffbe00, v10
	s_nop 1
	v_addc_co_u32_e32 v7, vcc, -1, v11, vcc
	flat_load_ushort v1, v[6:7]
	s_waitcnt vmcnt(0) lgkmcnt(0)
	v_lshlrev_b32_e32 v1, 16, v1

; #define TAB_IN(i) uni((const float*)p.tab[(i)])
;     ...
;   } else if (k == 2 || k == 8 || k == 11) {
;     const float* g = (k == 2 ? TAB_IN(2) : (k == 8 ? TAB_IN(6) : TAB_IN(27))) + l * DM;
.LBB0_1040:
	s_andn2_b64 vcc, exec, s[4:5]
	s_cbranch_vccnz .LBB0_1085
	s_cmp_eq_u32 s70, 2
	s_cselect_b64 s[4:5], -1, 0
	s_cmp_eq_u32 s70, 8
	s_cselect_b64 s[0:1], -1, 0
	s_cmp_lg_u32 s70, 8
	s_cselect_b64 s[10:11], -1, 0
	s_cmp_lg_u32 s70, 2
	s_mov_b64 s[6:7], -1
	s_cbranch_scc0 .LBB0_1047
	s_and_b64 vcc, exec, s[10:11]
	s_cbranch_vccz .LBB0_1044
	s_mov_b64 s[6:7], 0
	s_waitcnt vmcnt(0)
	v_readlane_b32 s3, v251, 27
	v_readlane_b32 s2, v250, 27
.LBB0_1044:
	s_andn2_b64 vcc, exec, s[6:7]
	s_cbranch_vccnz .LBB0_1046
	s_waitcnt vmcnt(0)
	v_readlane_b32 s3, v251, 6
	v_readlane_b32 s2, v250, 6

; #define TAB_IN(i) uni((const float*)p.tab[(i)])
; __device__ __forceinline__ int tid_() { int t = threadIdx.x; asm volatile("" : "+v"(t)); return t; }
; __device__ __forceinline__ int bid_() { int b = blockIdx.x; asm volatile("" : "+s"(b)); return b; }
; __device__ __forceinline__ void phase_resid(const Params& p, const float* __restrict__ gpost, float scale, const float* __restrict__ wdt) {
;   float* const L_dtbuf = TAB_dtbuf;
;   float* const L_out = TAB_out;
;   u16* const L_xb = TAB_xb;
;   float* const L_ssx = TAB_ssx;
;   const int tid = tid_(), wid = tid >> 6, lane = tid & 63;
;   for (int row0 = bid_() * 8 + wid; row0 < NTOK / 2; row0 += gridDim.x * 8) {
;     ...
;     const float* g = (k == 2 ? TAB_IN(2) : (k == 8 ? TAB_IN(6) : TAB_IN(27))) + l * DM;
;     phase_resid(p, g, (sub == 99) ? 0.f : ((k == 8) ? 1.0f : 0.5f), (k == 2) ? TAB_wdt + l * 6 * DM : nullptr);
.LBB0_1047:
	s_andn2_b64 vcc, exec, s[6:7]
	s_cbranch_vccnz .LBB0_1049
	s_waitcnt vmcnt(0)
	v_readlane_b32 s3, v251, 2
	v_readlane_b32 s2, v250, 2
.LBB0_1049:
	s_mov_b32 s40, s67
	s_mov_b32 s39, s66
	s_mov_b32 s38, s20
	s_mov_b32 s34, s36
	s_andn2_b64 vcc, exec, s[4:5]
	s_mov_b64 s[4:5], 0
	s_cbranch_vccnz .LBB0_1051
	s_mul_i32 s8, s14, 0x1800
	s_lshl_b64 s[4:5], s[8:9], 2
	s_waitcnt vmcnt(0)
	v_readlane_b32 s7, v250, 44
	v_readlane_b32 s6, v251, 44
	s_add_u32 s4, s7, s4
	s_addc_u32 s5, s6, s5
.LBB0_1051:
	s_mov_b32 s8, s92
	s_waitcnt vmcnt(0)
	v_readlane_b32 s11, v251, 41
	v_readlane_b32 s10, v250, 41
	s_waitcnt vmcnt(0)
	v_readlane_b32 s7, v251, 30
	v_readlane_b32 s6, v250, 30
	s_waitcnt vmcnt(0)
	v_readlane_b32 s13, v251, 32
	v_readlane_b32 s12, v250, 32
	s_waitcnt vmcnt(0)
	v_readlane_b32 s16, v250, 39
	v_mov_b32_e32 v0, v182
	v_readlane_b32 s17, v251, 39
	s_nop 0
	v_ashrrev_i32_e32 v1, 6, v0
	v_lshl_add_u32 v128, s8, 3, v1
	s_movk_i32 s8, 0x4000
	v_cmp_gt_i32_e32 vcc, s8, v128
	s_and_saveexec_b64 s[18:19], vcc
	s_cbranch_execz .LBB0_1084
	v_readlane_b32 s8, v249, 27
	s_lshl_b32 s8, s8, 10
	s_lshl_b64 s[14:15], s[8:9], 2
	s_add_u32 s2, s2, s14
	v_and_b32_e32 v20, 63, v0
	s_addc_u32 s3, s3, s15
	v_lshlrev_b32_e32 v16, 4, v20
	v_mov_b32_e32 v17, v172
	v_lshl_add_u64 v[12:13], s[2:3], 0, v[16:17]
	flat_load_dwordx4 v[0:3], v[12:13]
	flat_load_dwordx4 v[4:7], v[12:13] offset:1024
	flat_load_dwordx4 v[8:11], v[12:13] offset:2048
	s_nop 0
	flat_load_dwordx4 v[12:15], v[12:13] offset:3072
	v_lshl_add_u64 v[134:135], s[4:5], 0, v[16:17]
	s_mov_b64 s[2:3], 0x1000
	v_lshl_add_u64 v[136:137], v[134:135], 0, s[2:3]
	s_mov_b64 s[2:3], 0x3000
	v_lshl_add_u64 v[140:141], v[134:135], 0, s[2:3]
	s_mov_b64 s[2:3], 0x4000
	v_lshl_add_u64 v[142:143], v[134:135], 0, s[2:3]
	s_mov_b64 s[2:3], 0x5000
	v_lshl_add_u64 v[144:145], v[134:135], 0, s[2:3]
	s_mov_b64 s[2:3], 0x1400
	v_lshl_add_u64 v[146:147], v[134:135], 0, s[2:3]
	s_mov_b64 s[2:3], 0x2400
	v_lshl_add_u64 v[148:149], v[134:135], 0, s[2:3]
	s_mov_b64 s[2:3], 0x3400
	v_lshl_add_u64 v[150:151], v[134:135], 0, s[2:3]
	s_mov_b64 s[2:3], 0x4400
	v_lshl_add_u64 v[152:153], v[134:135], 0, s[2:3]
	s_mov_b64 s[2:3], 0x5400
	v_lshl_add_u64 v[154:155], v[134:135], 0, s[2:3]
	s_mov_b64 s[2:3], 0x1800
	v_lshl_add_u64 v[156:157], v[134:135], 0, s[2:3]
	s_mov_b64 s[2:3], 0x2800
	v_lshl_add_u64 v[158:159], v[134:135], 0, s[2:3]
	s_mov_b64 s[2:3], 0x3800
	v_lshl_add_u64 v[160:161], v[134:135], 0, s[2:3]
	s_mov_b64 s[2:3], 0x4800
	v_lshl_add_u64 v[162:163], v[134:135], 0, s[2:3]
	s_mov_b64 s[2:3], 0x5800
	v_lshl_add_u64 v[164:165], v[134:135], 0, s[2:3]
	s_mov_b64 s[2:3], 0x1c00
	v_lshl_add_u64 v[166:167], v[134:135], 0, s[2:3]
	s_mov_b64 s[2:3], 0x2c00
	v_lshl_add_u64 v[168:169], v[134:135], 0, s[2:3]
	s_mov_b64 s[2:3], 0x3c00
	v_lshl_add_u64 v[170:171], v[134:135], 0, s[2:3]
	s_mov_b64 s[2:3], 0x4c00
	v_lshlrev_b32_e32 v18, 3, v20
	v_mov_b32_e32 v19, v172
	s_cmp_lg_u64 s[4:5], 0
	v_lshl_add_u64 v[174:175], v[134:135], 0, s[2:3]
	s_mov_b64 s[2:3], 0x5c00
	v_cndmask_b32_e64 v173, 0.5, 1.0, s[0:1]
	v_lshl_add_u64 v[130:131], s[12:13], 0, v[18:19]
	v_lshl_add_u64 v[132:133], s[6:7], 0, v[16:17]
	v_cmp_eq_u32_e64 s[0:1], 0, v20
	s_mov_b64 s[20:21], 0
	s_cselect_b64 s[22:23], -1, 0
	v_lshl_add_u64 v[138:139], v[134:135], 0, s[60:61]
	v_lshl_add_u64 v[176:177], v[134:135], 0, s[2:3]
	v_cmp_eq_u32_e64 s[2:3], 1, v20
	v_cmp_eq_u32_e64 s[4:5], 2, v20
	v_cmp_eq_u32_e64 s[6:7], 3, v20
	v_cmp_eq_u32_e64 s[12:13], 4, v20
	v_cmp_eq_u32_e64 s[14:15], 5, v20
	s_branch .LBB0_1055

; __device__ __forceinline__ int tid_() { int t = threadIdx.x; asm volatile("" : "+v"(t)); return t; }
; template <int EPI>
; __device__ __forceinline__ void gemm_phase(const Params& p, const u16* __restrict__ A, const u16* __restrict__ Bt, int K, int nN,
;                            u16* __restrict__ Cout, int ldc) {
;   float* const L_ssx = TAB_ssx;
;   float* const L_dtbuf = TAB_dtbuf;
;   const int tid = tid_(), wid = tid >> 6, lane = tid & 63, wr = wid >> 2, wc = wid & 3, fr = lane & 15, fq = lane >> 4;
;   constexpr int nM = NTOK / 256, NXCD = 8, WGM = 8;
;   const int nwg = nM * nN;
;   unsigned soff[GL];
; #pragma unroll
;   for (int i = 0; i < GL; ++i) { int r_, c_; stage_rc(wid * 1024 + i * 8192 + lane * 16, r_, c_); soff[i] = (unsigned)(r_ * K + c_); }
;   const int nt = K / BK;
;   const int laneoff = (fr * 64 + fq * 16) ^ ((fr >> 3) << 5);
;   const int aoff = wr * 16384 + laneoff, boff = TILE_B + wc * 8192 + laneoff;
;     ...
;   } else if (k == 1 || k == 10 || k == 7) {
;     const u16* A = (k == 7) ? TAB_ymix : TAB_big;
;     const u16* W = wl + (k == 1 ? W_DN1 : (k == 10 ? W_DN2 : W_WOUT));
;     gemm_phase<EPI_SS>(p, A, W, (k == 7) ? DM : DFF, 4, TAB_xb, DM);
.LBB0_1086:
	s_movk_i32 s8, 0x400
	s_and_b64 vcc, exec, s[0:1]
	s_cbranch_vccz .LBB0_1088
	s_mov_b64 s[0:1], -1
	v_writelane_b32 v249, s0, 22
	s_movk_i32 s8, 0xb00
	s_nop 0
	v_writelane_b32 v249, s1, 23
	s_waitcnt vmcnt(0)
	v_readlane_b32 s1, v251, 33
	v_readlane_b32 s0, v250, 33
	s_nop 1
	v_writelane_b32 v249, s0, 24
	s_nop 1
	v_writelane_b32 v249, s1, 25
.LBB0_1088:
	s_nop 0
	v_readlane_b32 s0, v249, 22
	v_readlane_b32 s1, v249, 23
	s_andn2_b64 vcc, exec, s[0:1]
	s_cbranch_vccnz .LBB0_1123
	v_mov_b32_e32 v173, v182
	s_mov_b32 s18, s92
	s_cmpk_gt_i32 s18, 0x1ff
	s_waitcnt vmcnt(0)
	v_readlane_b32 s3, v251, 32
	v_readlane_b32 s2, v250, 32
	s_cbranch_scc1 .LBB0_1123
	v_lshlrev_b32_e32 v0, 4, v173
	v_and_b32_e32 v2, 32, v173
	v_bitop3_b32 v0, v0, v2, 48 bitop3:0x6c
	v_ashrrev_i32_e32 v1, 6, v173
	v_lshrrev_b32_e32 v2, 1, v0
	v_lshrrev_b32_e32 v0, 31, v173
	v_add_u32_e32 v0, v1, v0
	s_cmp_eq_u32 s70, 10
	s_mov_b32 s0, 0x1180000
	v_lshlrev_b32_e32 v5, 3, v0
	v_and_b32_e32 v0, 0x7fffffe, v0
	s_cselect_b32 s0, s0, 0xb00000
	s_cmp_lg_u32 s70, 1
	v_lshrrev_b32_e32 v3, 2, v173
	v_sub_u32_e32 v0, v1, v0
	s_cselect_b32 s0, s0, 0x580000
	v_bfi_b32 v3, -16, v5, v3
	v_lshl_or_b32 v0, v0, 5, v2
	s_lshl_b32 s4, s0, 1
	v_lshlrev_b32_e32 v192, 10, v1
	v_mad_u64_u32 v[174:175], s[0:1], v3, s8, v[0:1]
	v_add_u32_e32 v175, 0x2000, v192
	v_ashrrev_i32_e32 v0, 10, v175
	v_lshrrev_b32_e32 v3, 31, v175
	v_add_u32_e32 v3, v0, v3
	v_bfe_u32 v4, v173, 2, 4
	v_ashrrev_i32_e32 v3, 1, v3
	v_lshl_or_b32 v5, v3, 4, v4
	v_mul_i32_i24_e32 v3, 2, v3
	v_sub_u32_e32 v0, v0, v3
	v_lshl_or_b32 v0, v0, 5, v2
	v_mad_u64_u32 v[176:177], s[0:1], v5, s8, v[0:1]
	v_add_u32_e32 v177, 0x4000, v192
	v_ashrrev_i32_e32 v0, 10, v177
	v_lshrrev_b32_e32 v3, 31, v177
	v_add_u32_e32 v3, v0, v3
	v_ashrrev_i32_e32 v3, 1, v3
	v_lshl_or_b32 v5, v3, 4, v4
	v_mul_i32_i24_e32 v3, 2, v3
	v_sub_u32_e32 v0, v0, v3
	v_lshl_or_b32 v0, v0, 5, v2
	v_mad_u64_u32 v[178:179], s[0:1], v5, s8, v[0:1]
	v_add_u32_e32 v179, 0x6000, v192
	v_ashrrev_i32_e32 v0, 10, v179
	v_lshrrev_b32_e32 v3, 31, v179
	v_add_u32_e32 v3, v0, v3
	v_ashrrev_i32_e32 v3, 1, v3
	v_lshl_or_b32 v4, v3, 4, v4
	v_mul_i32_i24_e32 v3, 2, v3
	v_sub_u32_e32 v0, v0, v3
	s_add_u32 s19, s66, s4
	v_and_b32_e32 v191, 15, v173
	v_lshl_or_b32 v0, v0, 5, v2
	v_lshlrev_b32_e32 v7, 2, v173
	s_mov_b32 s6, s20
	s_addc_u32 s20, s67, 0
	v_mad_u64_u32 v[180:181], s[0:1], v4, s8, v[0:1]
	s_lshr_b32 s21, s8, 6
	v_and_b32_e32 v0, 3, v1
	v_lshlrev_b32_e32 v4, 6, v191
	v_and_b32_e32 v5, 48, v173
	v_and_b32_e32 v7, 32, v7
	v_lshlrev_b32_e32 v2, 13, v0
	v_or_b32_e32 v6, v4, v5
	v_bitop3_b32 v4, v4, v7, v5 bitop3:0x36
	s_mov_b32 s0, 0x8000
	s_add_i32 s21, s21, -1
	v_or3_b32 v194, v2, v4, s0
	s_add_u32 s0, s6, s4
	s_addc_u32 s1, s37, 0
	s_add_u32 s0, s35, s0
	s_addc_u32 s1, s36, s1
	s_add_u32 s22, s0, 0x80
	v_ashrrev_i32_e32 v1, 8, v173
	s_addc_u32 s23, s1, 0
	s_lshl_b32 s24, s8, 1
	v_readlane_b32 s42, v249, 24
	v_lshlrev_b32_e32 v3, 14, v1
	v_readlane_b32 s43, v249, 25
	s_add_u32 s25, s42, 0x80
	s_mov_b32 s40, s66
	s_mov_b32 s41, s67
	v_bfe_u32 v181, v173, 4, 2
	v_bitop3_b32 v193, v3, v6, v7 bitop3:0xf6
	v_lshlrev_b32_e32 v195, 15, v1
	v_lshlrev_b32_e32 v196, 6, v0
	s_mov_b32 s39, s6
	s_mov_b32 s38, s37
	s_mov_b32 s37, s35
	s_addc_u32 s26, s43, 0
	s_mov_b64 s[0:1], 0
	s_branch .LBB0_1092

; __device__ __forceinline__ int tid_() { int t = threadIdx.x; asm volatile("" : "+v"(t)); return t; }
; template <int EPI>
; __device__ __forceinline__ void gemm_phase(const Params& p, const u16* __restrict__ A, const u16* __restrict__ Bt, int K, int nN,
;                            u16* __restrict__ Cout, int ldc) {
;   float* const L_ssx = TAB_ssx;
;   float* const L_dtbuf = TAB_dtbuf;
;   const int tid = tid_(), wid = tid >> 6, lane = tid & 63, wr = wid >> 2, wc = wid & 3, fr = lane & 15, fq = lane >> 4;
;   constexpr int nM = NTOK / 256, NXCD = 8, WGM = 8;
;   const int nwg = nM * nN;
;   unsigned soff[GL];
; #pragma unroll
;   for (int i = 0; i < GL; ++i) { int r_, c_; stage_rc(wid * 1024 + i * 8192 + lane * 16, r_, c_); soff[i] = (unsigned)(r_ * K + c_); }
;   const int nt = K / BK;
;   const int laneoff = (fr * 64 + fq * 16) ^ ((fr >> 3) << 5);
;   const int aoff = wr * 16384 + laneoff, boff = TILE_B + wc * 8192 + laneoff;
;     ...
;   if (k == 0 || k == 9) {
;     gemm_phase<EPI_GU>(p, TAB_xb, wl + (k == 0 ? W_GU1 : W_GU2), DM, 22, TAB_big, DFF);
.LBB0_1124:
	v_mov_b32_e32 v173, v182
	s_mov_b32 s31, s92
	s_waitcnt vmcnt(0)
	v_readlane_b32 s8, v251, 32
	v_readlane_b32 s30, v250, 32
	v_readlane_b32 s5, v251, 33
	v_readlane_b32 s4, v250, 33
	s_cmpk_gt_i32 s31, 0xaff
	s_waitcnt vmcnt(0)
	v_readlane_b32 s7, v251, 39
	v_readlane_b32 s6, v250, 39
	s_cbranch_scc1 .LBB0_1154
	v_lshlrev_b32_e32 v1, 4, v173
	v_and_b32_e32 v2, 32, v173
	v_bitop3_b32 v1, v1, v2, 48 bitop3:0x6c
	v_lshrrev_b32_e32 v1, 1, v1
	v_lshlrev_b32_e32 v2, 8, v173
	s_movk_i32 s0, 0x3c00
	v_ashrrev_i32_e32 v0, 6, v173
	v_and_or_b32 v1, v2, s0, v1
	v_lshrrev_b32_e32 v2, 31, v173
	v_add_u32_e32 v2, v0, v2
	v_lshlrev_b32_e32 v175, 10, v0
	v_lshrrev_b32_e32 v2, 1, v2
	s_movk_i32 s0, 0x3fc0
	v_lshlrev_b32_e32 v3, 5, v0
	v_mul_lo_u32 v2, v2, s0
	v_add_u32_e32 v177, 0x2000, v175
	v_add3_u32 v176, v2, v3, v1
	v_ashrrev_i32_e32 v2, 10, v177
	v_lshrrev_b32_e32 v3, 31, v177
	v_add_u32_e32 v3, v2, v3
	v_ashrrev_i32_e32 v3, 1, v3
	v_mul_i32_i24_e32 v4, 2, v3
	v_sub_u32_e32 v2, v2, v4
	v_lshl_or_b32 v3, v3, 14, v1
	v_add_u32_e32 v179, 0x4000, v175
	v_lshl_add_u32 v178, v2, 5, v3
	v_ashrrev_i32_e32 v2, 10, v179
	v_lshrrev_b32_e32 v3, 31, v179
	v_add_u32_e32 v3, v2, v3
	v_ashrrev_i32_e32 v3, 1, v3
	v_mul_i32_i24_e32 v4, 2, v3
	v_sub_u32_e32 v2, v2, v4
	v_lshl_or_b32 v3, v3, 14, v1
	v_add_u32_e32 v181, 0x6000, v175
	v_lshl_add_u32 v180, v2, 5, v3
	v_ashrrev_i32_e32 v2, 10, v181
	v_lshrrev_b32_e32 v3, 31, v181
	s_cmp_eq_u32 s70, 0
	v_add_u32_e32 v3, v2, v3
	s_cselect_b32 s2, 0, 0x1800000
	v_ashrrev_i32_e32 v3, 1, v3
	s_add_u32 s33, s66, s2
	v_and_b32_e32 v174, 15, v173
	v_mul_i32_i24_e32 v4, 2, v3
	v_lshlrev_b32_e32 v7, 2, v173
	s_addc_u32 s34, s67, 0
	v_sub_u32_e32 v2, v2, v4
	v_lshl_or_b32 v1, v3, 14, v1
	v_and_b32_e32 v0, 3, v0
	v_lshlrev_b32_e32 v4, 6, v174
	v_and_b32_e32 v5, 48, v173
	v_and_b32_e32 v8, 32, v7
	v_lshl_add_u32 v191, v2, 5, v1
	v_lshlrev_b32_e32 v2, 13, v0
	v_or_b32_e32 v6, v4, v5
	v_bitop3_b32 v4, v4, v8, v5 bitop3:0x36
	s_mov_b32 s3, 0x8000
	s_add_u32 s2, s20, s2
	v_or3_b32 v194, v2, v4, s3
	s_addc_u32 s3, s37, 0
	s_add_u32 s2, s35, s2
	s_addc_u32 s3, s36, s3
	s_add_u32 s35, s2, 0x100
	v_ashrrev_i32_e32 v1, 8, v173
	s_addc_u32 s36, s3, 0
	v_lshlrev_b32_e32 v3, 14, v1
	s_movk_i32 s0, 0x100
	s_add_u32 s37, s30, 0x100
	v_bfe_u32 v192, v173, 4, 2
	v_cmp_gt_i32_e64 s[0:1], s0, v173
	v_bitop3_b32 v193, v3, v6, v8 bitop3:0xf6
	v_add_u32_e32 v195, 0x20000, v7
	v_lshlrev_b32_e32 v196, 7, v1
	v_lshlrev_b32_e32 v197, 2, v0
	v_add_u32_e32 v198, 0x10000, v175
	v_add_u32_e32 v199, 0x12000, v175
	v_add_u32_e32 v200, 0x14000, v175
	v_add_u32_e32 v201, 0x16000, v175
	v_add_u32_e32 v202, 0x1a000, v175
	v_add_u32_e32 v203, 0x1c000, v175
	v_add_u32_e32 v204, 0x1e000, v175
	s_addc_u32 s38, s8, 0
	s_mov_b64 s[26:27], 0
	v_add_u32_e32 v205, 0x18000, v175
	s_branch .LBB0_1127

; __global__ void __launch_bounds__(512, 2) fwd_kernel(Params p, int lo, int hi, int sub) {
	.amdhsa_kernel _Z10fwd_kernel6Paramsiii
		.amdhsa_group_segment_fixed_size 132096
		.amdhsa_private_segment_fixed_size 0
		.amdhsa_kernarg_size 648
		.amdhsa_user_sgpr_count 2
		.amdhsa_user_sgpr_dispatch_ptr 0
		.amdhsa_user_sgpr_queue_ptr 0
		.amdhsa_user_sgpr_kernarg_segment_ptr 1
		.amdhsa_user_sgpr_dispatch_id 0
		.amdhsa_user_sgpr_kernarg_preload_length 0
		.amdhsa_user_sgpr_kernarg_preload_offset 0
		.amdhsa_user_sgpr_private_segment_size 0
		.amdhsa_uses_dynamic_stack 0
		.amdhsa_enable_private_segment 0
		.amdhsa_system_sgpr_workgroup_id_x 1
		.amdhsa_system_sgpr_workgroup_id_y 0
		.amdhsa_system_sgpr_workgroup_id_z 0
		.amdhsa_system_sgpr_workgroup_info 0
		.amdhsa_system_vgpr_workitem_id 2
		.amdhsa_next_free_vgpr 252
		.amdhsa_next_free_sgpr 98
		.amdhsa_accum_offset 252
		.amdhsa_reserve_vcc 1
		.amdhsa_float_round_mode_32 0
		.amdhsa_float_round_mode_16_64 0
		.amdhsa_float_denorm_mode_32 3
		.amdhsa_float_denorm_mode_16_64 3
		.amdhsa_dx10_clamp 1
		.amdhsa_ieee_mode 1
		.amdhsa_fp16_overflow 0
		.amdhsa_tg_split 0
		.amdhsa_exception_fp_ieee_invalid_op 0
		.amdhsa_exception_fp_denorm_src 0
		.amdhsa_exception_fp_ieee_div_zero 0
		.amdhsa_exception_fp_ieee_overflow 0
		.amdhsa_exception_fp_ieee_underflow 0
		.amdhsa_exception_fp_ieee_inexact 0
		.amdhsa_exception_int_div_zero 0
	.end_amdhsa_kernel

; __global__ void __launch_bounds__(512, 2) fwd_kernel(Params p, int lo, int hi, int sub) {
.Lfunc_end0:
	.size	_Z10fwd_kernel6Paramsiii, .Lfunc_end0-_Z10fwd_kernel6Paramsiii
	.set _Z10fwd_kernel6Paramsiii.num_vgpr, 252
	.set _Z10fwd_kernel6Paramsiii.num_agpr, 0
	.set _Z10fwd_kernel6Paramsiii.numbered_sgpr, 98
	.set _Z10fwd_kernel6Paramsiii.num_named_barrier, 0
	.set _Z10fwd_kernel6Paramsiii.private_seg_size, 0
	.set _Z10fwd_kernel6Paramsiii.uses_vcc, 1
	.set _Z10fwd_kernel6Paramsiii.uses_flat_scratch, 0
	.set _Z10fwd_kernel6Paramsiii.has_dyn_sized_stack, 0
	.set _Z10fwd_kernel6Paramsiii.has_recursion, 0
	.set _Z10fwd_kernel6Paramsiii.has_indirect_call, 0

; __global__ void __launch_bounds__(512, 2) fwd_kernel(Params p, int lo, int hi, int sub) {
amdhsa.kernels:
  - .agpr_count:     0
    .args:
      - .offset:         0
        .size:           376
        .value_kind:     by_value
      - .offset:         376
        .size:           4
        .value_kind:     by_value
      - .offset:         380
        .size:           4
        .value_kind:     by_value
      - .offset:         384
        .size:           4
        .value_kind:     by_value
      - .offset:         392
        .size:           4
        .value_kind:     hidden_block_count_x
      - .offset:         396
        .size:           4
        .value_kind:     hidden_block_count_y
      - .offset:         400
        .size:           4
        .value_kind:     hidden_block_count_z
      - .offset:         404
        .size:           2
        .value_kind:     hidden_group_size_x
      - .offset:         406
        .size:           2
        .value_kind:     hidden_group_size_y
      - .offset:         408
        .size:           2
        .value_kind:     hidden_group_size_z
      - .offset:         410
        .size:           2
        .value_kind:     hidden_remainder_x
      - .offset:         412
        .size:           2
        .value_kind:     hidden_remainder_y
      - .offset:         414
        .size:           2
        .value_kind:     hidden_remainder_z
      - .offset:         432
        .size:           8
        .value_kind:     hidden_global_offset_x
      - .offset:         440
        .size:           8
        .value_kind:     hidden_global_offset_y
      - .offset:         448
        .size:           8
        .value_kind:     hidden_global_offset_z
      - .offset:         456
        .size:           2
        .value_kind:     hidden_grid_dims
      - .offset:         480
        .size:           8
        .value_kind:     hidden_multigrid_sync_arg
    .group_segment_fixed_size: 132096
    .kernarg_segment_align: 8
    .kernarg_segment_size: 648
    .language:       OpenCL C
    .language_version:
      - 2
      - 0
    .max_flat_workgroup_size: 512
    .name:           _Z10fwd_kernel6Paramsiii
    .private_segment_fixed_size: 0
    .sgpr_count:     104
    .sgpr_spill_count: 98
    .symbol:         _Z10fwd_kernel6Paramsiii.kd
    .uniform_work_group_size: 1
    .uses_dynamic_stack: false
    .vgpr_count:     252
    .vgpr_spill_count: 0
    .wavefront_size: 64
